# v16 + the barrier closing an MFMA segment is issued right behind the last MFMA (s_setprio 0 moved behind it)
# speedup vs baseline: 1.0084x; 1.0000x over previous
; #define GAS __attribute__((address_space(1)))
; #define PG8_STAGE(bufoff, gbase, voff) do { _Pragma("unroll") for (int _i = 0; _i < 2; ++_i) \
;         __builtin_amdgcn_global_load_lds((const GAS unsigned*)((const GAS char*)(gbase) + (voff)[_i]), (LAS unsigned*)(lds + (bufoff) + ldsw + _i * 8192), 16, 0, 0); } while (0)
; #define PG8_LDA(dst, b, h) do { _Pragma("unroll") for (int m = 0; m < 4; ++m) _Pragma("unroll") for (int k = 0; k < 2; ++k) dst[m][k] = *(const LAS bf16x8*)(lds + PG8_SA(b, h) + aoff + m * 2048 + k * 1024); } while (0)
; #define PG8_LDB(dst, b, h) do { _Pragma("unroll") for (int n = 0; n < 2; ++n) _Pragma("unroll") for (int k = 0; k < 2; ++k) dst[n][k] = *(const LAS bf16x8*)(lds + PG8_SB(b, h) + boff + n * 2048 + k * 1024); } while (0)
; #define PG8_MMA(ai, bj, At, Bt) do { __builtin_amdgcn_s_setprio(1); _Pragma("unroll") for (int m = 0; m < 4; ++m) _Pragma("unroll") for (int n = 0; n < 2; ++n) _Pragma("unroll") for (int k = 0; k < 2; ++k) \
;         acc[ai][bj][m][n] = __builtin_amdgcn_mfma_f32_16x16x32_bf16(Bt[n][k], At[m][k], acc[ai][bj][m][n], 0, 0, 0); __builtin_amdgcn_s_setprio(0); } while (0)
; #define PG8_WAIT_V(n) asm volatile("s_waitcnt vmcnt(" #n ")" ::: "memory")
; #define PG8_WAIT_L(n) asm volatile("s_waitcnt lgkmcnt(" #n ")" ::: "memory")
; #define PG8_BAR __builtin_amdgcn_s_barrier()
; template <class Epi, class Sched, bool ALIGN_EPI>
; __device__ __forceinline__ void gemm_phase(LAS unsigned char* lds, const Gemm g, const Sched& S, const Epi& E, int wave_id) {
;     ...
;             const bool last = (t == nt - 2);
;             const GAS char* a1 = cA + (size_t)(t + 1) * kstep;
;             const GAS char* a2 = last ? nA : cA + (size_t)(t + 2) * kstep; const GAS char* b2 = last ? nB : cB + (size_t)(t + 2) * kstep;
;             const GAS char* a3 = a2 + kstep; const GAS char* b3 = b2 + kstep;
;             PG8_LDB(B0, 0, 0); PG8_LDB(B1, 0, 1); PG8_SCHED; PG8_LDA(At, 0, 0); PG8_STAGE(PG8_SA(1, 1), a1 + hsA, voffA);
;             PG8_WAIT_V(8); PG8_WAIT_L(0); PG8_BAR; PG8_MMA(0, 0, At, B0); PG8_MMA(0, 1, At, B1); PG8_BAR; PG8_SCHED;
;             PG8_LDA(At, 0, 1); PG8_STAGE(PG8_SB(0, 0), b2, voffB); PG8_STAGE(PG8_SB(0, 1), b2 + hsB, voffB); PG8_STAGE(PG8_SA(0, 0), a2, voffA);
;             PG8_WAIT_V(8); PG8_WAIT_L(0); PG8_BAR; PG8_MMA(1, 0, At, B0); PG8_MMA(1, 1, At, B1); PG8_BAR; PG8_SCHED;
.LBB0_1117:
	s_add_u32 s58, s0, 0xfff80080
	s_addc_u32 s59, s1, -1
	s_cmp_eq_u32 s76, 28
	s_cselect_b32 s61, s33, s59
	s_cselect_b32 s60, s47, s58
	s_cselect_b32 s59, s49, s74
	s_cselect_b32 s58, s57, s71
	s_mov_b32 m0, s87
	v_lshl_add_u64 v[206:207], s[0:1], 0, v[204:205]
	global_load_lds_dwordx4 v[206:207], off
	v_lshl_add_u64 v[206:207], s[0:1], 0, v[202:203]
	s_mov_b32 m0, s88
	s_nop 0
	global_load_lds_dwordx4 v[206:207], off
	v_add_u32_e32 v0, 0x10400, v250
	ds_read_b128 v[130:133], v0
	ds_read_b128 v[134:137], v0 offset:1024
	ds_read_b128 v[138:141], v0 offset:2048
	ds_read_b128 v[142:145], v0 offset:3072
	v_add_u32_e32 v0, 0x14400, v250
	ds_read_b128 v[146:149], v0
	ds_read_b128 v[150:153], v0 offset:1024
	ds_read_b128 v[154:157], v0 offset:2048
	ds_read_b128 v[158:161], v0 offset:3072
	ds_read_b128 v[162:165], v253 offset:1024
	ds_read_b128 v[166:169], v253 offset:2048
	ds_read_b128 v[170:173], v253 offset:3072
	ds_read_b128 v[174:177], v253 offset:4096
	ds_read_b128 v[178:181], v253 offset:5120
	ds_read_b128 v[182:185], v253 offset:6144
	ds_read_b128 v[186:189], v253 offset:7168
	ds_read_b128 v[190:193], v253 offset:8192
	s_waitcnt vmcnt(8)
	s_waitcnt lgkmcnt(0)
	s_setprio 1
	s_barrier
	v_mfma_f32_16x16x32_bf16 v[126:129], v[130:133], v[162:165], v[126:129]
	v_mfma_f32_16x16x32_bf16 v[122:125], v[138:141], v[162:165], v[122:125]
	v_mfma_f32_16x16x32_bf16 v[110:113], v[130:133], v[170:173], v[110:113]
	v_mfma_f32_16x16x32_bf16 v[106:109], v[138:141], v[170:173], v[106:109]
	v_mfma_f32_16x16x32_bf16 v[94:97], v[130:133], v[178:181], v[94:97]
	v_mfma_f32_16x16x32_bf16 v[90:93], v[138:141], v[178:181], v[90:93]
	v_mfma_f32_16x16x32_bf16 v[78:81], v[130:133], v[186:189], v[78:81]
	v_mfma_f32_16x16x32_bf16 v[74:77], v[138:141], v[186:189], v[74:77]
	v_mfma_f32_16x16x32_bf16 v[126:129], v[134:137], v[166:169], v[126:129]
	v_mfma_f32_16x16x32_bf16 v[122:125], v[142:145], v[166:169], v[122:125]
	v_mfma_f32_16x16x32_bf16 v[110:113], v[134:137], v[174:177], v[110:113]
	v_mfma_f32_16x16x32_bf16 v[106:109], v[142:145], v[174:177], v[106:109]
	v_mfma_f32_16x16x32_bf16 v[94:97], v[134:137], v[182:185], v[94:97]
	v_mfma_f32_16x16x32_bf16 v[90:93], v[142:145], v[182:185], v[90:93]
	v_mfma_f32_16x16x32_bf16 v[78:81], v[134:137], v[190:193], v[78:81]
	v_mfma_f32_16x16x32_bf16 v[74:77], v[142:145], v[190:193], v[74:77]
	s_setprio 0
	s_setprio 1
	v_mfma_f32_16x16x32_bf16 v[118:121], v[146:149], v[162:165], v[118:121]
	v_mfma_f32_16x16x32_bf16 v[114:117], v[154:157], v[162:165], v[114:117]
	v_mfma_f32_16x16x32_bf16 v[102:105], v[146:149], v[170:173], v[102:105]
	v_mfma_f32_16x16x32_bf16 v[98:101], v[154:157], v[170:173], v[98:101]
	v_mfma_f32_16x16x32_bf16 v[86:89], v[146:149], v[178:181], v[86:89]
	v_mfma_f32_16x16x32_bf16 v[82:85], v[154:157], v[178:181], v[82:85]
	v_mfma_f32_16x16x32_bf16 v[70:73], v[146:149], v[186:189], v[70:73]
	v_mfma_f32_16x16x32_bf16 v[66:69], v[154:157], v[186:189], v[66:69]
	v_mfma_f32_16x16x32_bf16 v[118:121], v[150:153], v[166:169], v[118:121]
	v_mfma_f32_16x16x32_bf16 v[114:117], v[158:161], v[166:169], v[114:117]
	v_mfma_f32_16x16x32_bf16 v[102:105], v[150:153], v[174:177], v[102:105]
	v_mfma_f32_16x16x32_bf16 v[98:101], v[158:161], v[174:177], v[98:101]
	v_mfma_f32_16x16x32_bf16 v[86:89], v[150:153], v[182:185], v[86:89]
	v_mfma_f32_16x16x32_bf16 v[82:85], v[158:161], v[182:185], v[82:85]
	v_mfma_f32_16x16x32_bf16 v[70:73], v[150:153], v[190:193], v[70:73]
	v_mfma_f32_16x16x32_bf16 v[66:69], v[158:161], v[190:193], v[66:69]
	s_barrier
	s_setprio 0
	s_mov_b32 m0, s15
	v_lshl_add_u64 v[206:207], s[58:59], 0, v[196:197]
	s_add_u32 vcc_lo, s58, 0x80000
	global_load_lds_dwordx4 v[206:207], off
	v_lshl_add_u64 v[208:209], s[58:59], 0, v[200:201]
	s_mov_b32 m0, s73
	s_addc_u32 vcc_hi, s59, 0
	global_load_lds_dwordx4 v[208:209], off
	v_lshl_add_u64 v[210:211], vcc, 0, v[196:197]
	s_mov_b32 m0, s75
	v_lshl_add_u64 v[212:213], s[60:61], 0, v[198:199]
	global_load_lds_dwordx4 v[210:211], off
	v_lshl_add_u64 v[210:211], vcc, 0, v[200:201]
	s_mov_b32 m0, s80
	s_nop 0
	global_load_lds_dwordx4 v[210:211], off
	v_lshl_add_u64 v[210:211], s[60:61], 0, v[194:195]
	s_mov_b32 m0, s81
	s_nop 0
	global_load_lds_dwordx4 v[210:211], off
	s_mov_b32 m0, s82
	s_nop 0
	global_load_lds_dwordx4 v[212:213], off
	ds_read_b128 v[162:165], v253 offset:17408
	ds_read_b128 v[166:169], v253 offset:18432
	ds_read_b128 v[170:173], v253 offset:19456
	ds_read_b128 v[174:177], v253 offset:20480
	ds_read_b128 v[178:181], v253 offset:21504
	ds_read_b128 v[182:185], v253 offset:22528
	ds_read_b128 v[186:189], v253 offset:23552
	ds_read_b128 v[190:193], v253 offset:24576
	s_waitcnt vmcnt(8)
	s_waitcnt lgkmcnt(0)
	s_setprio 1
	s_barrier
; #define PG8_STAGE(bufoff, gbase, voff) do { _Pragma("unroll") for (int _i = 0; _i < 2; ++_i) \
;         __builtin_amdgcn_global_load_lds((const GAS unsigned*)((const GAS char*)(gbase) + (voff)[_i]), (LAS unsigned*)(lds + (bufoff) + ldsw + _i * 8192), 16, 0, 0); } while (0)
; #define PG8_LDA(dst, b, h) do { _Pragma("unroll") for (int m = 0; m < 4; ++m) _Pragma("unroll") for (int k = 0; k < 2; ++k) dst[m][k] = *(const LAS bf16x8*)(lds + PG8_SA(b, h) + aoff + m * 2048 + k * 1024); } while (0)
; #define PG8_LDB(dst, b, h) do { _Pragma("unroll") for (int n = 0; n < 2; ++n) _Pragma("unroll") for (int k = 0; k < 2; ++k) dst[n][k] = *(const LAS bf16x8*)(lds + PG8_SB(b, h) + boff + n * 2048 + k * 1024); } while (0)
; #define PG8_MMA(ai, bj, At, Bt) do { __builtin_amdgcn_s_setprio(1); _Pragma("unroll") for (int m = 0; m < 4; ++m) _Pragma("unroll") for (int n = 0; n < 2; ++n) _Pragma("unroll") for (int k = 0; k < 2; ++k) \
;         acc[ai][bj][m][n] = __builtin_amdgcn_mfma_f32_16x16x32_bf16(Bt[n][k], At[m][k], acc[ai][bj][m][n], 0, 0, 0); __builtin_amdgcn_s_setprio(0); } while (0)
; #define PG8_WAIT_V(n) asm volatile("s_waitcnt vmcnt(" #n ")" ::: "memory")
; #define PG8_WAIT_L(n) asm volatile("s_waitcnt lgkmcnt(" #n ")" ::: "memory")
; #define PG8_BAR __builtin_amdgcn_s_barrier()
; #define PG8_SCHED __builtin_amdgcn_sched_barrier(0)
; template <class Epi, class Sched, bool ALIGN_EPI>
; __device__ __forceinline__ void gemm_phase(LAS unsigned char* lds, const Gemm g, const Sched& S, const Epi& E, int wave_id) {
;     ...
;             PG8_WAIT_V(8); PG8_WAIT_L(0); PG8_BAR; PG8_MMA(1, 0, At, B0); PG8_MMA(1, 1, At, B1); PG8_BAR; PG8_SCHED;
;             PG8_LDB(B0, 1, 0); PG8_LDB(B1, 1, 1); PG8_SCHED; PG8_LDA(At, 1, 0); PG8_STAGE(PG8_SA(0, 1), a2 + hsA, voffA);
;             PG8_WAIT_V(8); PG8_WAIT_L(0); PG8_BAR; PG8_MMA(0, 0, At, B0); PG8_MMA(0, 1, At, B1); PG8_BAR; PG8_SCHED;
;             PG8_LDA(At, 1, 1); PG8_STAGE(PG8_SB(1, 0), b3, voffB); PG8_STAGE(PG8_SB(1, 1), b3 + hsB, voffB); PG8_STAGE(PG8_SA(1, 0), a3, voffA);
;             PG8_WAIT_V(8); PG8_WAIT_L(0); PG8_BAR; PG8_MMA(1, 0, At, B0); PG8_MMA(1, 1, At, B1); PG8_BAR; PG8_SCHED;
	v_mfma_f32_16x16x32_bf16 v[62:65], v[130:133], v[162:165], v[62:65]
	v_mfma_f32_16x16x32_bf16 v[58:61], v[138:141], v[162:165], v[58:61]
	v_mfma_f32_16x16x32_bf16 v[46:49], v[130:133], v[170:173], v[46:49]
	v_mfma_f32_16x16x32_bf16 v[42:45], v[138:141], v[170:173], v[42:45]
	v_mfma_f32_16x16x32_bf16 v[30:33], v[130:133], v[178:181], v[30:33]
	v_mfma_f32_16x16x32_bf16 v[26:29], v[138:141], v[178:181], v[26:29]
	v_mfma_f32_16x16x32_bf16 v[14:17], v[130:133], v[186:189], v[14:17]
	v_mfma_f32_16x16x32_bf16 v[10:13], v[138:141], v[186:189], v[10:13]
	v_mfma_f32_16x16x32_bf16 v[62:65], v[134:137], v[166:169], v[62:65]
	v_mfma_f32_16x16x32_bf16 v[58:61], v[142:145], v[166:169], v[58:61]
	v_mfma_f32_16x16x32_bf16 v[46:49], v[134:137], v[174:177], v[46:49]
	v_mfma_f32_16x16x32_bf16 v[42:45], v[142:145], v[174:177], v[42:45]
	v_mfma_f32_16x16x32_bf16 v[30:33], v[134:137], v[182:185], v[30:33]
	v_mfma_f32_16x16x32_bf16 v[26:29], v[142:145], v[182:185], v[26:29]
	v_mfma_f32_16x16x32_bf16 v[14:17], v[134:137], v[190:193], v[14:17]
	v_mfma_f32_16x16x32_bf16 v[10:13], v[142:145], v[190:193], v[10:13]
	s_setprio 0
	s_setprio 1
	v_mfma_f32_16x16x32_bf16 v[54:57], v[146:149], v[162:165], v[54:57]
	v_mfma_f32_16x16x32_bf16 v[50:53], v[154:157], v[162:165], v[50:53]
	v_mfma_f32_16x16x32_bf16 v[38:41], v[146:149], v[170:173], v[38:41]
	v_mfma_f32_16x16x32_bf16 v[34:37], v[154:157], v[170:173], v[34:37]
	v_mfma_f32_16x16x32_bf16 v[22:25], v[146:149], v[178:181], v[22:25]
	v_mfma_f32_16x16x32_bf16 v[18:21], v[154:157], v[178:181], v[18:21]
	v_mfma_f32_16x16x32_bf16 v[6:9], v[146:149], v[186:189], v[6:9]
	v_mfma_f32_16x16x32_bf16 v[2:5], v[154:157], v[186:189], v[2:5]
	v_mfma_f32_16x16x32_bf16 v[54:57], v[150:153], v[166:169], v[54:57]
	v_mfma_f32_16x16x32_bf16 v[50:53], v[158:161], v[166:169], v[50:53]
	v_mfma_f32_16x16x32_bf16 v[38:41], v[150:153], v[174:177], v[38:41]
	v_mfma_f32_16x16x32_bf16 v[34:37], v[158:161], v[174:177], v[34:37]
	v_mfma_f32_16x16x32_bf16 v[22:25], v[150:153], v[182:185], v[22:25]
	v_mfma_f32_16x16x32_bf16 v[18:21], v[158:161], v[182:185], v[18:21]
	v_mfma_f32_16x16x32_bf16 v[6:9], v[150:153], v[190:193], v[6:9]
	v_mfma_f32_16x16x32_bf16 v[2:5], v[158:161], v[190:193], v[2:5]
	s_barrier
	s_setprio 0
	s_add_u32 s60, s60, 0x80000
	s_addc_u32 s61, s61, 0
	s_mov_b32 m0, s83
	v_lshl_add_u64 v[214:215], s[60:61], 0, v[194:195]
	global_load_lds_dwordx4 v[214:215], off
	v_lshl_add_u64 v[214:215], s[60:61], 0, v[198:199]
	s_mov_b32 m0, s84
	s_nop 0
	global_load_lds_dwordx4 v[214:215], off
	v_add_u32_e32 v0, 0x18400, v250
	ds_read_b128 v[130:133], v0
	ds_read_b128 v[134:137], v0 offset:1024
	ds_read_b128 v[138:141], v0 offset:2048
	ds_read_b128 v[142:145], v0 offset:3072
	v_add_u32_e32 v0, 0x1c400, v250
	ds_read_b128 v[146:149], v0
	ds_read_b128 v[150:153], v0 offset:1024
	ds_read_b128 v[154:157], v0 offset:2048
	ds_read_b128 v[158:161], v0 offset:3072
	ds_read_b128 v[162:165], v253 offset:33792
	ds_read_b128 v[166:169], v253 offset:34816
	ds_read_b128 v[170:173], v253 offset:35840
	ds_read_b128 v[174:177], v253 offset:36864
	ds_read_b128 v[178:181], v253 offset:37888
	ds_read_b128 v[182:185], v253 offset:38912
	ds_read_b128 v[186:189], v253 offset:39936
	ds_read_b128 v[190:193], v253 offset:40960
	s_waitcnt vmcnt(8)
	s_waitcnt lgkmcnt(0)
	s_setprio 1
	s_barrier
	v_mfma_f32_16x16x32_bf16 v[126:129], v[130:133], v[162:165], v[126:129]
	v_mfma_f32_16x16x32_bf16 v[122:125], v[138:141], v[162:165], v[122:125]
	v_mfma_f32_16x16x32_bf16 v[110:113], v[130:133], v[170:173], v[110:113]
	v_mfma_f32_16x16x32_bf16 v[106:109], v[138:141], v[170:173], v[106:109]
	v_mfma_f32_16x16x32_bf16 v[94:97], v[130:133], v[178:181], v[94:97]
	v_mfma_f32_16x16x32_bf16 v[90:93], v[138:141], v[178:181], v[90:93]
	v_mfma_f32_16x16x32_bf16 v[78:81], v[130:133], v[186:189], v[78:81]
	v_mfma_f32_16x16x32_bf16 v[74:77], v[138:141], v[186:189], v[74:77]
	v_mfma_f32_16x16x32_bf16 v[126:129], v[134:137], v[166:169], v[126:129]
	v_mfma_f32_16x16x32_bf16 v[122:125], v[142:145], v[166:169], v[122:125]
	v_mfma_f32_16x16x32_bf16 v[110:113], v[134:137], v[174:177], v[110:113]
	v_mfma_f32_16x16x32_bf16 v[106:109], v[142:145], v[174:177], v[106:109]
	v_mfma_f32_16x16x32_bf16 v[94:97], v[134:137], v[182:185], v[94:97]
	v_mfma_f32_16x16x32_bf16 v[90:93], v[142:145], v[182:185], v[90:93]
	v_mfma_f32_16x16x32_bf16 v[78:81], v[134:137], v[190:193], v[78:81]
	v_mfma_f32_16x16x32_bf16 v[74:77], v[142:145], v[190:193], v[74:77]
	s_setprio 0
	s_setprio 1
	v_mfma_f32_16x16x32_bf16 v[118:121], v[146:149], v[162:165], v[118:121]
	v_mfma_f32_16x16x32_bf16 v[114:117], v[154:157], v[162:165], v[114:117]
	v_mfma_f32_16x16x32_bf16 v[102:105], v[146:149], v[170:173], v[102:105]
	v_mfma_f32_16x16x32_bf16 v[98:101], v[154:157], v[170:173], v[98:101]
	v_mfma_f32_16x16x32_bf16 v[86:89], v[146:149], v[178:181], v[86:89]
	v_mfma_f32_16x16x32_bf16 v[82:85], v[154:157], v[178:181], v[82:85]
	v_mfma_f32_16x16x32_bf16 v[70:73], v[146:149], v[186:189], v[70:73]
	v_mfma_f32_16x16x32_bf16 v[66:69], v[154:157], v[186:189], v[66:69]
	v_mfma_f32_16x16x32_bf16 v[118:121], v[150:153], v[166:169], v[118:121]
	v_mfma_f32_16x16x32_bf16 v[114:117], v[158:161], v[166:169], v[114:117]
	v_mfma_f32_16x16x32_bf16 v[102:105], v[150:153], v[174:177], v[102:105]
	v_mfma_f32_16x16x32_bf16 v[98:101], v[158:161], v[174:177], v[98:101]
	v_mfma_f32_16x16x32_bf16 v[86:89], v[150:153], v[182:185], v[86:89]
	v_mfma_f32_16x16x32_bf16 v[82:85], v[158:161], v[182:185], v[82:85]
	v_mfma_f32_16x16x32_bf16 v[70:73], v[150:153], v[190:193], v[70:73]
	v_mfma_f32_16x16x32_bf16 v[66:69], v[158:161], v[190:193], v[66:69]
	s_barrier
; #define PG8_STAGE(bufoff, gbase, voff) do { _Pragma("unroll") for (int _i = 0; _i < 2; ++_i) \
;         __builtin_amdgcn_global_load_lds((const GAS unsigned*)((const GAS char*)(gbase) + (voff)[_i]), (LAS unsigned*)(lds + (bufoff) + ldsw + _i * 8192), 16, 0, 0); } while (0)
; #define PG8_LDA(dst, b, h) do { _Pragma("unroll") for (int m = 0; m < 4; ++m) _Pragma("unroll") for (int k = 0; k < 2; ++k) dst[m][k] = *(const LAS bf16x8*)(lds + PG8_SA(b, h) + aoff + m * 2048 + k * 1024); } while (0)
; #define PG8_MMA(ai, bj, At, Bt) do { __builtin_amdgcn_s_setprio(1); _Pragma("unroll") for (int m = 0; m < 4; ++m) _Pragma("unroll") for (int n = 0; n < 2; ++n) _Pragma("unroll") for (int k = 0; k < 2; ++k) \
;         acc[ai][bj][m][n] = __builtin_amdgcn_mfma_f32_16x16x32_bf16(Bt[n][k], At[m][k], acc[ai][bj][m][n], 0, 0, 0); __builtin_amdgcn_s_setprio(0); } while (0)
; #define PG8_WAIT_V(n) asm volatile("s_waitcnt vmcnt(" #n ")" ::: "memory")
; #define PG8_WAIT_L(n) asm volatile("s_waitcnt lgkmcnt(" #n ")" ::: "memory")
; #define PG8_BAR __builtin_amdgcn_s_barrier()
; #define PG8_SCHED __builtin_amdgcn_sched_barrier(0)
; template <class Epi, class Sched, bool ALIGN_EPI>
; __device__ __forceinline__ void gemm_phase(LAS unsigned char* lds, const Gemm g, const Sched& S, const Epi& E, int wave_id) {
;     ...
;             PG8_LDA(At, 1, 1); PG8_STAGE(PG8_SB(1, 0), b3, voffB); PG8_STAGE(PG8_SB(1, 1), b3 + hsB, voffB); PG8_STAGE(PG8_SA(1, 0), a3, voffA);
;             PG8_WAIT_V(8); PG8_WAIT_L(0); PG8_BAR; PG8_MMA(1, 0, At, B0); PG8_MMA(1, 1, At, B1); PG8_BAR; PG8_SCHED;
;         }
;         if constexpr (ALIGN_EPI) { if (wr == 0) PG8_BAR; }
	s_setprio 0
	s_mov_b32 m0, s95
	v_lshl_add_u64 v[206:207], v[206:207], 0, s[92:93]
	s_add_u32 s58, s58, 0x80080
	global_load_lds_dwordx4 v[206:207], off
	v_lshl_add_u64 v[206:207], v[208:209], 0, s[92:93]
	s_mov_b32 m0, s96
	s_addc_u32 s59, s59, 0
	global_load_lds_dwordx4 v[206:207], off
	v_lshl_add_u64 v[206:207], s[58:59], 0, v[196:197]
	s_mov_b32 m0, s17
	s_nop 0
	global_load_lds_dwordx4 v[206:207], off
	v_lshl_add_u64 v[206:207], s[58:59], 0, v[200:201]
	s_mov_b32 m0, s18
	s_nop 0
	global_load_lds_dwordx4 v[206:207], off
	v_lshl_add_u64 v[206:207], v[210:211], 0, s[92:93]
	s_mov_b32 m0, s97
	s_nop 0
	global_load_lds_dwordx4 v[206:207], off
	v_lshl_add_u64 v[206:207], v[212:213], 0, s[92:93]
	s_mov_b32 m0, s16
	s_nop 0
	global_load_lds_dwordx4 v[206:207], off
	ds_read_b128 v[162:165], v253 offset:50176
	ds_read_b128 v[166:169], v253 offset:51200
	ds_read_b128 v[170:173], v253 offset:52224
	ds_read_b128 v[174:177], v253 offset:53248
	ds_read_b128 v[178:181], v253 offset:54272
	ds_read_b128 v[182:185], v253 offset:55296
	ds_read_b128 v[186:189], v253 offset:56320
	ds_read_b128 v[190:193], v253 offset:57344
	s_waitcnt vmcnt(8)
	s_waitcnt lgkmcnt(0)
	s_setprio 1
	s_barrier
	v_mfma_f32_16x16x32_bf16 v[62:65], v[130:133], v[162:165], v[62:65]
	v_mfma_f32_16x16x32_bf16 v[58:61], v[138:141], v[162:165], v[58:61]
	v_mfma_f32_16x16x32_bf16 v[46:49], v[130:133], v[170:173], v[46:49]
	v_mfma_f32_16x16x32_bf16 v[42:45], v[138:141], v[170:173], v[42:45]
	v_mfma_f32_16x16x32_bf16 v[30:33], v[130:133], v[178:181], v[30:33]
	v_mfma_f32_16x16x32_bf16 v[26:29], v[138:141], v[178:181], v[26:29]
	v_mfma_f32_16x16x32_bf16 v[14:17], v[130:133], v[186:189], v[14:17]
	v_mfma_f32_16x16x32_bf16 v[10:13], v[138:141], v[186:189], v[10:13]
	v_mfma_f32_16x16x32_bf16 v[62:65], v[134:137], v[166:169], v[62:65]
	v_mfma_f32_16x16x32_bf16 v[58:61], v[142:145], v[166:169], v[58:61]
	v_mfma_f32_16x16x32_bf16 v[46:49], v[134:137], v[174:177], v[46:49]
	v_mfma_f32_16x16x32_bf16 v[42:45], v[142:145], v[174:177], v[42:45]
	v_mfma_f32_16x16x32_bf16 v[30:33], v[134:137], v[182:185], v[30:33]
	v_mfma_f32_16x16x32_bf16 v[26:29], v[142:145], v[182:185], v[26:29]
	v_mfma_f32_16x16x32_bf16 v[14:17], v[134:137], v[190:193], v[14:17]
	v_mfma_f32_16x16x32_bf16 v[10:13], v[142:145], v[190:193], v[10:13]
	s_setprio 0
	s_setprio 1
	v_mfma_f32_16x16x32_bf16 v[54:57], v[146:149], v[162:165], v[54:57]
	v_mfma_f32_16x16x32_bf16 v[50:53], v[154:157], v[162:165], v[50:53]
	v_mfma_f32_16x16x32_bf16 v[38:41], v[146:149], v[170:173], v[38:41]
	v_mfma_f32_16x16x32_bf16 v[34:37], v[154:157], v[170:173], v[34:37]
	v_mfma_f32_16x16x32_bf16 v[22:25], v[146:149], v[178:181], v[22:25]
	v_mfma_f32_16x16x32_bf16 v[18:21], v[154:157], v[178:181], v[18:21]
	v_mfma_f32_16x16x32_bf16 v[6:9], v[146:149], v[186:189], v[6:9]
	v_mfma_f32_16x16x32_bf16 v[2:5], v[154:157], v[186:189], v[2:5]
	v_mfma_f32_16x16x32_bf16 v[54:57], v[150:153], v[166:169], v[54:57]
	v_mfma_f32_16x16x32_bf16 v[50:53], v[158:161], v[166:169], v[50:53]
	v_mfma_f32_16x16x32_bf16 v[38:41], v[150:153], v[174:177], v[38:41]
	v_mfma_f32_16x16x32_bf16 v[34:37], v[158:161], v[174:177], v[34:37]
	v_mfma_f32_16x16x32_bf16 v[22:25], v[150:153], v[182:185], v[22:25]
	v_mfma_f32_16x16x32_bf16 v[18:21], v[158:161], v[182:185], v[18:21]
	v_mfma_f32_16x16x32_bf16 v[6:9], v[150:153], v[190:193], v[6:9]
	v_mfma_f32_16x16x32_bf16 v[2:5], v[158:161], v[190:193], v[2:5]
	s_barrier
	s_setprio 0
	s_add_i32 s76, s76, 2
	s_add_u32 s71, s71, 0x100
	s_addc_u32 s74, s74, 0
	s_add_u32 s0, s0, 0x100
	s_addc_u32 s1, s1, 0
	s_cmp_gt_u32 s76, 29
	s_cbranch_scc0 .LBB0_1117
	s_and_b64 vcc, exec, s[44:45]
	s_cbranch_vccz .LBB0_1120
	s_barrier

; #define GAS __attribute__((address_space(1)))
; #define PG8_STAGE(bufoff, gbase, voff) do { _Pragma("unroll") for (int _i = 0; _i < 2; ++_i) \
;         __builtin_amdgcn_global_load_lds((const GAS unsigned*)((const GAS char*)(gbase) + (voff)[_i]), (LAS unsigned*)(lds + (bufoff) + ldsw + _i * 8192), 16, 0, 0); } while (0)
; #define PG8_LDA(dst, b, h) do { _Pragma("unroll") for (int m = 0; m < 4; ++m) _Pragma("unroll") for (int k = 0; k < 2; ++k) dst[m][k] = *(const LAS bf16x8*)(lds + PG8_SA(b, h) + aoff + m * 2048 + k * 1024); } while (0)
; #define PG8_LDB(dst, b, h) do { _Pragma("unroll") for (int n = 0; n < 2; ++n) _Pragma("unroll") for (int k = 0; k < 2; ++k) dst[n][k] = *(const LAS bf16x8*)(lds + PG8_SB(b, h) + boff + n * 2048 + k * 1024); } while (0)
; #define PG8_MMA(ai, bj, At, Bt) do { __builtin_amdgcn_s_setprio(1); _Pragma("unroll") for (int m = 0; m < 4; ++m) _Pragma("unroll") for (int n = 0; n < 2; ++n) _Pragma("unroll") for (int k = 0; k < 2; ++k) \
;         acc[ai][bj][m][n] = __builtin_amdgcn_mfma_f32_16x16x32_bf16(Bt[n][k], At[m][k], acc[ai][bj][m][n], 0, 0, 0); __builtin_amdgcn_s_setprio(0); } while (0)
; #define PG8_WAIT_V(n) asm volatile("s_waitcnt vmcnt(" #n ")" ::: "memory")
; #define PG8_WAIT_L(n) asm volatile("s_waitcnt lgkmcnt(" #n ")" ::: "memory")
; #define PG8_BAR __builtin_amdgcn_s_barrier()
; #define PG8_SCHED __builtin_amdgcn_sched_barrier(0)
; template <class Epi, class Sched, bool ALIGN_EPI>
; __device__ __forceinline__ void gemm_phase(LAS unsigned char* lds, const Gemm g, const Sched& S, const Epi& E, int wave_id) {
;     ...
;             const bool last = (t == nt - 2);
;             const GAS char* a1 = cA + (size_t)(t + 1) * kstep;
;             const GAS char* a2 = last ? nA : cA + (size_t)(t + 2) * kstep; const GAS char* b2 = last ? nB : cB + (size_t)(t + 2) * kstep;
;             const GAS char* a3 = a2 + kstep; const GAS char* b3 = b2 + kstep;
;             PG8_LDB(B0, 0, 0); PG8_LDB(B1, 0, 1); PG8_SCHED; PG8_LDA(At, 0, 0); PG8_STAGE(PG8_SA(1, 1), a1 + hsA, voffA);
;             PG8_WAIT_V(8); PG8_WAIT_L(0); PG8_BAR; PG8_MMA(0, 0, At, B0); PG8_MMA(0, 1, At, B1); PG8_BAR; PG8_SCHED;
;             PG8_LDA(At, 0, 1); PG8_STAGE(PG8_SB(0, 0), b2, voffB); PG8_STAGE(PG8_SB(0, 1), b2 + hsB, voffB); PG8_STAGE(PG8_SA(0, 0), a2, voffA);
.LBB0_1458:
	s_add_u32 s21, s26, s34
	s_addc_u32 s33, s27, s35
	s_add_u32 s38, s21, 0x100
	s_addc_u32 s39, s33, 0
	s_and_b64 s[36:37], s[30:31], exec
	s_cselect_b32 s37, s3, s39
	s_cselect_b32 s36, s5, s38
	s_add_u32 s34, s6, s34
	s_addc_u32 s35, s7, s35
	s_add_u32 s34, s34, 0x100
	s_addc_u32 s35, s35, 0
	s_and_b64 s[30:31], s[30:31], exec
	s_cselect_b32 s39, s9, s35
	s_cselect_b32 s38, s19, s34
	s_add_u32 s42, s21, 0x10080
	s_addc_u32 s43, s33, 0
	s_add_i32 m0, s49, 0xc400
	s_add_i32 s21, s49, 0xe400
	s_add_u32 s40, s38, 0x10000
	s_addc_u32 s41, s39, 0
	s_add_u32 s34, s36, 0x10000
	s_addc_u32 s35, s37, 0
	s_add_u32 s30, s38, 0x10080
	s_addc_u32 s31, s39, 0
	v_lshl_add_u64 v[2:3], s[42:43], 0, v[140:141]
	global_load_lds_dwordx4 v[2:3], off
	v_lshl_add_u64 v[2:3], s[42:43], 0, v[144:145]
	s_mov_b32 m0, s21
	s_nop 0
	global_load_lds_dwordx4 v[2:3], off
	v_add_u32_e32 v0, 0x10400, v159
	ds_read_b128 v[100:103], v0
	ds_read_b128 v[108:111], v0 offset:1024
	ds_read_b128 v[148:151], v0 offset:2048
	ds_read_b128 v[152:155], v0 offset:3072
	v_add_u32_e32 v0, 0x14400, v159
	ds_read_b128 v[160:163], v0
	ds_read_b128 v[164:167], v0 offset:1024
	ds_read_b128 v[168:171], v0 offset:2048
	ds_read_b128 v[172:175], v0 offset:3072
	ds_read_b128 v[176:179], v158 offset:1024
	ds_read_b128 v[180:183], v158 offset:2048
	ds_read_b128 v[184:187], v158 offset:3072
	ds_read_b128 v[188:191], v158 offset:4096
	ds_read_b128 v[192:195], v158 offset:5120
	ds_read_b128 v[196:199], v158 offset:6144
	ds_read_b128 v[200:203], v158 offset:7168
	ds_read_b128 v[204:207], v158 offset:8192
	s_waitcnt vmcnt(8)
	s_waitcnt lgkmcnt(0)
	s_setprio 1
	s_barrier
	v_mfma_f32_16x16x32_bf16 v[136:139], v[100:103], v[176:179], v[136:139]
	v_mfma_f32_16x16x32_bf16 v[132:135], v[148:151], v[176:179], v[132:135]
	v_mfma_f32_16x16x32_bf16 v[128:131], v[100:103], v[184:187], v[128:131]
	v_mfma_f32_16x16x32_bf16 v[124:127], v[148:151], v[184:187], v[124:127]
	v_mfma_f32_16x16x32_bf16 v[120:123], v[100:103], v[192:195], v[120:123]
	v_mfma_f32_16x16x32_bf16 v[116:119], v[148:151], v[192:195], v[116:119]
	v_mfma_f32_16x16x32_bf16 v[112:115], v[100:103], v[200:203], v[112:115]
	v_mfma_f32_16x16x32_bf16 v[104:107], v[148:151], v[200:203], v[104:107]
	v_mfma_f32_16x16x32_bf16 v[136:139], v[108:111], v[180:183], v[136:139]
	v_mfma_f32_16x16x32_bf16 v[132:135], v[152:155], v[180:183], v[132:135]
	v_mfma_f32_16x16x32_bf16 v[128:131], v[108:111], v[188:191], v[128:131]
	v_mfma_f32_16x16x32_bf16 v[124:127], v[152:155], v[188:191], v[124:127]
	v_mfma_f32_16x16x32_bf16 v[120:123], v[108:111], v[196:199], v[120:123]
	v_mfma_f32_16x16x32_bf16 v[116:119], v[152:155], v[196:199], v[116:119]
	v_mfma_f32_16x16x32_bf16 v[112:115], v[108:111], v[204:207], v[112:115]
	v_mfma_f32_16x16x32_bf16 v[104:107], v[152:155], v[204:207], v[104:107]
	s_setprio 0
	s_setprio 1
	v_mfma_f32_16x16x32_bf16 v[64:67], v[160:163], v[176:179], v[64:67]
	v_mfma_f32_16x16x32_bf16 v[60:63], v[168:171], v[176:179], v[60:63]
	v_mfma_f32_16x16x32_bf16 v[56:59], v[160:163], v[184:187], v[56:59]
	v_mfma_f32_16x16x32_bf16 v[52:55], v[168:171], v[184:187], v[52:55]
	v_mfma_f32_16x16x32_bf16 v[48:51], v[160:163], v[192:195], v[48:51]
	v_mfma_f32_16x16x32_bf16 v[44:47], v[168:171], v[192:195], v[44:47]
	v_mfma_f32_16x16x32_bf16 v[40:43], v[160:163], v[200:203], v[40:43]
	v_mfma_f32_16x16x32_bf16 v[36:39], v[168:171], v[200:203], v[36:39]
	v_mfma_f32_16x16x32_bf16 v[64:67], v[164:167], v[180:183], v[64:67]
	v_mfma_f32_16x16x32_bf16 v[60:63], v[172:175], v[180:183], v[60:63]
	v_mfma_f32_16x16x32_bf16 v[56:59], v[164:167], v[188:191], v[56:59]
	v_mfma_f32_16x16x32_bf16 v[52:55], v[172:175], v[188:191], v[52:55]
	v_mfma_f32_16x16x32_bf16 v[48:51], v[164:167], v[196:199], v[48:51]
	v_mfma_f32_16x16x32_bf16 v[44:47], v[172:175], v[196:199], v[44:47]
	v_mfma_f32_16x16x32_bf16 v[40:43], v[164:167], v[204:207], v[40:43]
	v_mfma_f32_16x16x32_bf16 v[36:39], v[172:175], v[204:207], v[36:39]
	s_barrier
	s_setprio 0
	s_mov_b32 m0, s50
	v_lshl_add_u64 v[156:157], s[38:39], 0, v[142:143]
	global_load_lds_dwordx4 v[156:157], off
	v_lshl_add_u64 v[208:209], s[38:39], 0, v[146:147]
	s_mov_b32 m0, s51
	v_lshl_add_u64 v[2:3], s[40:41], 0, v[142:143]
	global_load_lds_dwordx4 v[208:209], off
	s_mov_b32 m0, s52
	v_lshl_add_u64 v[210:211], s[36:37], 0, v[140:141]
	global_load_lds_dwordx4 v[2:3], off
	v_lshl_add_u64 v[2:3], s[40:41], 0, v[146:147]
	s_mov_b32 m0, s53
	v_lshl_add_u64 v[212:213], s[36:37], 0, v[144:145]
	global_load_lds_dwordx4 v[2:3], off
	s_mov_b32 m0, s54
	s_nop 0
	global_load_lds_dwordx4 v[210:211], off
	s_mov_b32 m0, s55
	s_nop 0
	global_load_lds_dwordx4 v[212:213], off
	ds_read_b128 v[176:179], v158 offset:17408
	ds_read_b128 v[180:183], v158 offset:18432
	ds_read_b128 v[184:187], v158 offset:19456
	ds_read_b128 v[188:191], v158 offset:20480
	ds_read_b128 v[192:195], v158 offset:21504
	ds_read_b128 v[196:199], v158 offset:22528
	ds_read_b128 v[200:203], v158 offset:23552
	ds_read_b128 v[204:207], v158 offset:24576
	s_waitcnt vmcnt(8)
	s_waitcnt lgkmcnt(0)
	s_setprio 1
	s_barrier
; #define PG8_STAGE(bufoff, gbase, voff) do { _Pragma("unroll") for (int _i = 0; _i < 2; ++_i) \
;         __builtin_amdgcn_global_load_lds((const GAS unsigned*)((const GAS char*)(gbase) + (voff)[_i]), (LAS unsigned*)(lds + (bufoff) + ldsw + _i * 8192), 16, 0, 0); } while (0)
; #define PG8_LDA(dst, b, h) do { _Pragma("unroll") for (int m = 0; m < 4; ++m) _Pragma("unroll") for (int k = 0; k < 2; ++k) dst[m][k] = *(const LAS bf16x8*)(lds + PG8_SA(b, h) + aoff + m * 2048 + k * 1024); } while (0)
; #define PG8_LDB(dst, b, h) do { _Pragma("unroll") for (int n = 0; n < 2; ++n) _Pragma("unroll") for (int k = 0; k < 2; ++k) dst[n][k] = *(const LAS bf16x8*)(lds + PG8_SB(b, h) + boff + n * 2048 + k * 1024); } while (0)
; #define PG8_MMA(ai, bj, At, Bt) do { __builtin_amdgcn_s_setprio(1); _Pragma("unroll") for (int m = 0; m < 4; ++m) _Pragma("unroll") for (int n = 0; n < 2; ++n) _Pragma("unroll") for (int k = 0; k < 2; ++k) \
;         acc[ai][bj][m][n] = __builtin_amdgcn_mfma_f32_16x16x32_bf16(Bt[n][k], At[m][k], acc[ai][bj][m][n], 0, 0, 0); __builtin_amdgcn_s_setprio(0); } while (0)
; #define PG8_WAIT_V(n) asm volatile("s_waitcnt vmcnt(" #n ")" ::: "memory")
; #define PG8_WAIT_L(n) asm volatile("s_waitcnt lgkmcnt(" #n ")" ::: "memory")
; #define PG8_BAR __builtin_amdgcn_s_barrier()
; #define PG8_SCHED __builtin_amdgcn_sched_barrier(0)
; template <class Epi, class Sched, bool ALIGN_EPI>
; __device__ __forceinline__ void gemm_phase(LAS unsigned char* lds, const Gemm g, const Sched& S, const Epi& E, int wave_id) {
;     ...
;             PG8_WAIT_V(8); PG8_WAIT_L(0); PG8_BAR; PG8_MMA(1, 0, At, B0); PG8_MMA(1, 1, At, B1); PG8_BAR; PG8_SCHED;
;             PG8_LDB(B0, 1, 0); PG8_LDB(B1, 1, 1); PG8_SCHED; PG8_LDA(At, 1, 0); PG8_STAGE(PG8_SA(0, 1), a2 + hsA, voffA);
;             PG8_WAIT_V(8); PG8_WAIT_L(0); PG8_BAR; PG8_MMA(0, 0, At, B0); PG8_MMA(0, 1, At, B1); PG8_BAR; PG8_SCHED;
	v_mfma_f32_16x16x32_bf16 v[96:99], v[100:103], v[176:179], v[96:99]
	v_mfma_f32_16x16x32_bf16 v[92:95], v[148:151], v[176:179], v[92:95]
	v_mfma_f32_16x16x32_bf16 v[88:91], v[100:103], v[184:187], v[88:91]
	v_mfma_f32_16x16x32_bf16 v[84:87], v[148:151], v[184:187], v[84:87]
	v_mfma_f32_16x16x32_bf16 v[80:83], v[100:103], v[192:195], v[80:83]
	v_mfma_f32_16x16x32_bf16 v[76:79], v[148:151], v[192:195], v[76:79]
	v_mfma_f32_16x16x32_bf16 v[72:75], v[100:103], v[200:203], v[72:75]
	v_mfma_f32_16x16x32_bf16 v[68:71], v[148:151], v[200:203], v[68:71]
	v_mfma_f32_16x16x32_bf16 v[96:99], v[108:111], v[180:183], v[96:99]
	v_mfma_f32_16x16x32_bf16 v[92:95], v[152:155], v[180:183], v[92:95]
	v_mfma_f32_16x16x32_bf16 v[88:91], v[108:111], v[188:191], v[88:91]
	v_mfma_f32_16x16x32_bf16 v[84:87], v[152:155], v[188:191], v[84:87]
	v_mfma_f32_16x16x32_bf16 v[80:83], v[108:111], v[196:199], v[80:83]
	v_mfma_f32_16x16x32_bf16 v[76:79], v[152:155], v[196:199], v[76:79]
	v_mfma_f32_16x16x32_bf16 v[72:75], v[108:111], v[204:207], v[72:75]
	v_mfma_f32_16x16x32_bf16 v[68:71], v[152:155], v[204:207], v[68:71]
	s_setprio 0
	s_setprio 1
	v_mfma_f32_16x16x32_bf16 v[32:35], v[160:163], v[176:179], v[32:35]
	v_mfma_f32_16x16x32_bf16 v[28:31], v[168:171], v[176:179], v[28:31]
	v_mfma_f32_16x16x32_bf16 v[24:27], v[160:163], v[184:187], v[24:27]
	v_mfma_f32_16x16x32_bf16 v[20:23], v[168:171], v[184:187], v[20:23]
	v_mfma_f32_16x16x32_bf16 v[16:19], v[160:163], v[192:195], v[16:19]
	v_mfma_f32_16x16x32_bf16 v[12:15], v[168:171], v[192:195], v[12:15]
	v_mfma_f32_16x16x32_bf16 v[8:11], v[160:163], v[200:203], v[8:11]
	v_mfma_f32_16x16x32_bf16 v[2:5], v[168:171], v[200:203], v[4:7]
	v_mfma_f32_16x16x32_bf16 v[32:35], v[164:167], v[180:183], v[32:35]
	v_mfma_f32_16x16x32_bf16 v[28:31], v[172:175], v[180:183], v[28:31]
	v_mfma_f32_16x16x32_bf16 v[24:27], v[164:167], v[188:191], v[24:27]
	v_mfma_f32_16x16x32_bf16 v[20:23], v[172:175], v[188:191], v[20:23]
	v_mfma_f32_16x16x32_bf16 v[16:19], v[164:167], v[196:199], v[16:19]
	v_mfma_f32_16x16x32_bf16 v[12:15], v[172:175], v[196:199], v[12:15]
	v_mfma_f32_16x16x32_bf16 v[8:11], v[164:167], v[204:207], v[8:11]
	v_mfma_f32_16x16x32_bf16 v[2:5], v[172:175], v[204:207], v[2:5]
	s_barrier
	s_setprio 0
	s_mov_b32 m0, s56
	v_lshl_add_u64 v[6:7], s[34:35], 0, v[140:141]
	global_load_lds_dwordx4 v[6:7], off
	v_lshl_add_u64 v[6:7], s[34:35], 0, v[144:145]
	s_mov_b32 m0, s57
	s_nop 0
	global_load_lds_dwordx4 v[6:7], off
	v_add_u32_e32 v0, 0x18400, v159
	ds_read_b128 v[100:103], v0
	ds_read_b128 v[108:111], v0 offset:1024
	ds_read_b128 v[148:151], v0 offset:2048
	ds_read_b128 v[152:155], v0 offset:3072
	v_add_u32_e32 v0, 0x1c400, v159
	ds_read_b128 v[160:163], v0
	ds_read_b128 v[164:167], v0 offset:1024
	ds_read_b128 v[168:171], v0 offset:2048
	ds_read_b128 v[172:175], v0 offset:3072
	ds_read_b128 v[176:179], v158 offset:33792
	ds_read_b128 v[180:183], v158 offset:34816
	ds_read_b128 v[184:187], v158 offset:35840
	ds_read_b128 v[188:191], v158 offset:36864
	ds_read_b128 v[192:195], v158 offset:37888
	ds_read_b128 v[196:199], v158 offset:38912
	ds_read_b128 v[200:203], v158 offset:39936
	ds_read_b128 v[204:207], v158 offset:40960
	s_waitcnt vmcnt(8)
	s_waitcnt lgkmcnt(0)
	s_setprio 1
	s_barrier
	v_mfma_f32_16x16x32_bf16 v[136:139], v[100:103], v[176:179], v[136:139]
	v_mfma_f32_16x16x32_bf16 v[132:135], v[148:151], v[176:179], v[132:135]
	v_mfma_f32_16x16x32_bf16 v[128:131], v[100:103], v[184:187], v[128:131]
	v_mfma_f32_16x16x32_bf16 v[124:127], v[148:151], v[184:187], v[124:127]
	v_mfma_f32_16x16x32_bf16 v[120:123], v[100:103], v[192:195], v[120:123]
	v_mfma_f32_16x16x32_bf16 v[116:119], v[148:151], v[192:195], v[116:119]
	v_mfma_f32_16x16x32_bf16 v[112:115], v[100:103], v[200:203], v[112:115]
	v_mfma_f32_16x16x32_bf16 v[104:107], v[148:151], v[200:203], v[104:107]
	v_mfma_f32_16x16x32_bf16 v[136:139], v[108:111], v[180:183], v[136:139]
	v_mfma_f32_16x16x32_bf16 v[132:135], v[152:155], v[180:183], v[132:135]
	v_mfma_f32_16x16x32_bf16 v[128:131], v[108:111], v[188:191], v[128:131]
	v_mfma_f32_16x16x32_bf16 v[124:127], v[152:155], v[188:191], v[124:127]
	v_mfma_f32_16x16x32_bf16 v[120:123], v[108:111], v[196:199], v[120:123]
	v_mfma_f32_16x16x32_bf16 v[116:119], v[152:155], v[196:199], v[116:119]
	v_mfma_f32_16x16x32_bf16 v[112:115], v[108:111], v[204:207], v[112:115]
	v_mfma_f32_16x16x32_bf16 v[104:107], v[152:155], v[204:207], v[104:107]
	s_setprio 0
	s_setprio 1
	v_mfma_f32_16x16x32_bf16 v[64:67], v[160:163], v[176:179], v[64:67]
	v_mfma_f32_16x16x32_bf16 v[60:63], v[168:171], v[176:179], v[60:63]
	v_mfma_f32_16x16x32_bf16 v[56:59], v[160:163], v[184:187], v[56:59]
	v_mfma_f32_16x16x32_bf16 v[52:55], v[168:171], v[184:187], v[52:55]
	v_mfma_f32_16x16x32_bf16 v[48:51], v[160:163], v[192:195], v[48:51]
	v_mfma_f32_16x16x32_bf16 v[44:47], v[168:171], v[192:195], v[44:47]
	v_mfma_f32_16x16x32_bf16 v[40:43], v[160:163], v[200:203], v[40:43]
	v_mfma_f32_16x16x32_bf16 v[36:39], v[168:171], v[200:203], v[36:39]
	v_mfma_f32_16x16x32_bf16 v[64:67], v[164:167], v[180:183], v[64:67]
	v_mfma_f32_16x16x32_bf16 v[60:63], v[172:175], v[180:183], v[60:63]
	v_mfma_f32_16x16x32_bf16 v[56:59], v[164:167], v[188:191], v[56:59]
	v_mfma_f32_16x16x32_bf16 v[52:55], v[172:175], v[188:191], v[52:55]
	v_mfma_f32_16x16x32_bf16 v[48:51], v[164:167], v[196:199], v[48:51]
	v_mfma_f32_16x16x32_bf16 v[44:47], v[172:175], v[196:199], v[44:47]
	v_mfma_f32_16x16x32_bf16 v[40:43], v[164:167], v[204:207], v[40:43]
	v_mfma_f32_16x16x32_bf16 v[36:39], v[172:175], v[204:207], v[36:39]
	s_barrier
; #define PG8_STAGE(bufoff, gbase, voff) do { _Pragma("unroll") for (int _i = 0; _i < 2; ++_i) \
;         __builtin_amdgcn_global_load_lds((const GAS unsigned*)((const GAS char*)(gbase) + (voff)[_i]), (LAS unsigned*)(lds + (bufoff) + ldsw + _i * 8192), 16, 0, 0); } while (0)
; #define PG8_LDA(dst, b, h) do { _Pragma("unroll") for (int m = 0; m < 4; ++m) _Pragma("unroll") for (int k = 0; k < 2; ++k) dst[m][k] = *(const LAS bf16x8*)(lds + PG8_SA(b, h) + aoff + m * 2048 + k * 1024); } while (0)
; #define PG8_MMA(ai, bj, At, Bt) do { __builtin_amdgcn_s_setprio(1); _Pragma("unroll") for (int m = 0; m < 4; ++m) _Pragma("unroll") for (int n = 0; n < 2; ++n) _Pragma("unroll") for (int k = 0; k < 2; ++k) \
;         acc[ai][bj][m][n] = __builtin_amdgcn_mfma_f32_16x16x32_bf16(Bt[n][k], At[m][k], acc[ai][bj][m][n], 0, 0, 0); __builtin_amdgcn_s_setprio(0); } while (0)
; #define PG8_WAIT_V(n) asm volatile("s_waitcnt vmcnt(" #n ")" ::: "memory")
; #define PG8_WAIT_L(n) asm volatile("s_waitcnt lgkmcnt(" #n ")" ::: "memory")
; #define PG8_BAR __builtin_amdgcn_s_barrier()
; #define PG8_SCHED __builtin_amdgcn_sched_barrier(0)
; template <class Epi, class Sched, bool ALIGN_EPI>
; __device__ __forceinline__ void gemm_phase(LAS unsigned char* lds, const Gemm g, const Sched& S, const Epi& E, int wave_id) {
;     ...
;             PG8_LDA(At, 1, 1); PG8_STAGE(PG8_SB(1, 0), b3, voffB); PG8_STAGE(PG8_SB(1, 1), b3 + hsB, voffB); PG8_STAGE(PG8_SA(1, 0), a3, voffA);
;             PG8_WAIT_V(8); PG8_WAIT_L(0); PG8_BAR; PG8_MMA(1, 0, At, B0); PG8_MMA(1, 1, At, B1); PG8_BAR; PG8_SCHED;
;         }
;         if constexpr (ALIGN_EPI) { if (wr == 0) PG8_BAR; }
	s_setprio 0
	s_mov_b32 m0, s63
	v_lshl_add_u64 v[6:7], v[156:157], 0, s[92:93]
	global_load_lds_dwordx4 v[6:7], off
	v_lshl_add_u64 v[6:7], v[208:209], 0, s[92:93]
	s_mov_b32 m0, s64
	s_nop 0
	global_load_lds_dwordx4 v[6:7], off
	v_lshl_add_u64 v[6:7], s[30:31], 0, v[142:143]
	s_mov_b32 m0, s67
	s_nop 0
	global_load_lds_dwordx4 v[6:7], off
	v_lshl_add_u64 v[6:7], s[30:31], 0, v[146:147]
	s_mov_b32 m0, s72
	s_nop 0
	global_load_lds_dwordx4 v[6:7], off
	v_lshl_add_u64 v[6:7], v[210:211], 0, s[92:93]
	s_mov_b32 m0, s65
	s_nop 0
	global_load_lds_dwordx4 v[6:7], off
	v_lshl_add_u64 v[6:7], v[212:213], 0, s[92:93]
	s_mov_b32 m0, s66
	s_nop 0
	global_load_lds_dwordx4 v[6:7], off
	ds_read_b128 v[176:179], v158 offset:50176
	ds_read_b128 v[180:183], v158 offset:51200
	ds_read_b128 v[184:187], v158 offset:52224
	ds_read_b128 v[188:191], v158 offset:53248
	ds_read_b128 v[192:195], v158 offset:54272
	ds_read_b128 v[196:199], v158 offset:55296
	ds_read_b128 v[200:203], v158 offset:56320
	ds_read_b128 v[204:207], v158 offset:57344
	s_waitcnt vmcnt(8)
	s_waitcnt lgkmcnt(0)
	s_setprio 1
	s_barrier
	v_mfma_f32_16x16x32_bf16 v[96:99], v[100:103], v[176:179], v[96:99]
	v_mfma_f32_16x16x32_bf16 v[92:95], v[148:151], v[176:179], v[92:95]
	v_mfma_f32_16x16x32_bf16 v[88:91], v[100:103], v[184:187], v[88:91]
	v_mfma_f32_16x16x32_bf16 v[84:87], v[148:151], v[184:187], v[84:87]
	v_mfma_f32_16x16x32_bf16 v[80:83], v[100:103], v[192:195], v[80:83]
	v_mfma_f32_16x16x32_bf16 v[76:79], v[148:151], v[192:195], v[76:79]
	v_mfma_f32_16x16x32_bf16 v[72:75], v[100:103], v[200:203], v[72:75]
	v_mfma_f32_16x16x32_bf16 v[68:71], v[148:151], v[200:203], v[68:71]
	v_mfma_f32_16x16x32_bf16 v[96:99], v[108:111], v[180:183], v[96:99]
	v_mfma_f32_16x16x32_bf16 v[92:95], v[152:155], v[180:183], v[92:95]
	v_mfma_f32_16x16x32_bf16 v[88:91], v[108:111], v[188:191], v[88:91]
	v_mfma_f32_16x16x32_bf16 v[84:87], v[152:155], v[188:191], v[84:87]
	v_mfma_f32_16x16x32_bf16 v[80:83], v[108:111], v[196:199], v[80:83]
	v_mfma_f32_16x16x32_bf16 v[76:79], v[152:155], v[196:199], v[76:79]
	v_mfma_f32_16x16x32_bf16 v[72:75], v[108:111], v[204:207], v[72:75]
	v_mfma_f32_16x16x32_bf16 v[68:71], v[152:155], v[204:207], v[68:71]
	s_setprio 0
	s_setprio 1
	v_mfma_f32_16x16x32_bf16 v[32:35], v[160:163], v[176:179], v[32:35]
	v_mfma_f32_16x16x32_bf16 v[28:31], v[168:171], v[176:179], v[28:31]
	v_mfma_f32_16x16x32_bf16 v[24:27], v[160:163], v[184:187], v[24:27]
	v_mfma_f32_16x16x32_bf16 v[20:23], v[168:171], v[184:187], v[20:23]
	v_mfma_f32_16x16x32_bf16 v[16:19], v[160:163], v[192:195], v[16:19]
	v_mfma_f32_16x16x32_bf16 v[12:15], v[168:171], v[192:195], v[12:15]
	v_mfma_f32_16x16x32_bf16 v[6:9], v[160:163], v[200:203], v[8:11]
	v_mfma_f32_16x16x32_bf16 v[2:5], v[168:171], v[200:203], v[2:5]
	v_mfma_f32_16x16x32_bf16 v[32:35], v[164:167], v[180:183], v[32:35]
	v_mfma_f32_16x16x32_bf16 v[28:31], v[172:175], v[180:183], v[28:31]
	v_mfma_f32_16x16x32_bf16 v[24:27], v[164:167], v[188:191], v[24:27]
	v_mfma_f32_16x16x32_bf16 v[20:23], v[172:175], v[188:191], v[20:23]
	v_mfma_f32_16x16x32_bf16 v[16:19], v[164:167], v[196:199], v[16:19]
	v_mfma_f32_16x16x32_bf16 v[12:15], v[172:175], v[196:199], v[12:15]
	v_mfma_f32_16x16x32_bf16 v[8:11], v[164:167], v[204:207], v[6:9]
	v_mfma_f32_16x16x32_bf16 v[4:7], v[172:175], v[204:207], v[2:5]
	s_barrier
	s_setprio 0
	s_andn2_b64 vcc, exec, s[28:29]
	s_mov_b64 s[30:31], -1
	s_mov_b64 s[28:29], 0
	s_mov_b64 s[34:35], 0x100
	s_cbranch_vccz .LBB0_1458
	s_and_b64 vcc, exec, s[16:17]
	s_cbranch_vccz .LBB0_1461
	s_barrier

; #define GAS __attribute__((address_space(1)))
; #define PG8_STAGE(bufoff, gbase, voff) do { _Pragma("unroll") for (int _i = 0; _i < 2; ++_i) \
;         __builtin_amdgcn_global_load_lds((const GAS unsigned*)((const GAS char*)(gbase) + (voff)[_i]), (LAS unsigned*)(lds + (bufoff) + ldsw + _i * 8192), 16, 0, 0); } while (0)
; #define PG8_LDA(dst, b, h) do { _Pragma("unroll") for (int m = 0; m < 4; ++m) _Pragma("unroll") for (int k = 0; k < 2; ++k) dst[m][k] = *(const LAS bf16x8*)(lds + PG8_SA(b, h) + aoff + m * 2048 + k * 1024); } while (0)
; #define PG8_LDB(dst, b, h) do { _Pragma("unroll") for (int n = 0; n < 2; ++n) _Pragma("unroll") for (int k = 0; k < 2; ++k) dst[n][k] = *(const LAS bf16x8*)(lds + PG8_SB(b, h) + boff + n * 2048 + k * 1024); } while (0)
; #define PG8_MMA(ai, bj, At, Bt) do { __builtin_amdgcn_s_setprio(1); _Pragma("unroll") for (int m = 0; m < 4; ++m) _Pragma("unroll") for (int n = 0; n < 2; ++n) _Pragma("unroll") for (int k = 0; k < 2; ++k) \
;         acc[ai][bj][m][n] = __builtin_amdgcn_mfma_f32_16x16x32_bf16(Bt[n][k], At[m][k], acc[ai][bj][m][n], 0, 0, 0); __builtin_amdgcn_s_setprio(0); } while (0)
; #define PG8_WAIT_V(n) asm volatile("s_waitcnt vmcnt(" #n ")" ::: "memory")
; #define PG8_WAIT_L(n) asm volatile("s_waitcnt lgkmcnt(" #n ")" ::: "memory")
; #define PG8_BAR __builtin_amdgcn_s_barrier()
; #define PG8_SCHED __builtin_amdgcn_sched_barrier(0)
; template <class Epi, class Sched, bool ALIGN_EPI>
; __device__ __forceinline__ void gemm_phase(LAS unsigned char* lds, const Gemm g, const Sched& S, const Epi& E, int wave_id) {
;     ...
;             const bool last = (t == nt - 2);
;             const GAS char* a1 = cA + (size_t)(t + 1) * kstep;
;             const GAS char* a2 = last ? nA : cA + (size_t)(t + 2) * kstep; const GAS char* b2 = last ? nB : cB + (size_t)(t + 2) * kstep;
;             const GAS char* a3 = a2 + kstep; const GAS char* b3 = b2 + kstep;
;             PG8_LDB(B0, 0, 0); PG8_LDB(B1, 0, 1); PG8_SCHED; PG8_LDA(At, 0, 0); PG8_STAGE(PG8_SA(1, 1), a1 + hsA, voffA);
;             PG8_WAIT_V(8); PG8_WAIT_L(0); PG8_BAR; PG8_MMA(0, 0, At, B0); PG8_MMA(0, 1, At, B1); PG8_BAR; PG8_SCHED;
;             PG8_LDA(At, 0, 1); PG8_STAGE(PG8_SB(0, 0), b2, voffB); PG8_STAGE(PG8_SB(0, 1), b2 + hsB, voffB); PG8_STAGE(PG8_SA(0, 0), a2, voffA);
.LBB0_1645:
	s_add_u32 s20, s18, 0x100
	s_addc_u32 s21, s19, 0
	s_cmp_eq_u32 s55, 2
	s_cselect_b32 s25, s15, s21
	s_cselect_b32 s24, s14, s20
	s_cselect_b32 s23, s17, s54
	s_cselect_b32 s22, s16, s53
	v_lshl_add_u64 v[192:193], s[18:19], 0, v[170:171]
	s_add_i32 m0, s31, 0xc400
	s_nop 0
	global_load_lds_dwordx4 v[192:193], off
	v_lshl_add_u64 v[192:193], s[18:19], 0, v[168:169]
	s_add_i32 m0, s31, 0xe400
	s_nop 0
	global_load_lds_dwordx4 v[192:193], off
	v_add_u32_e32 v134, 0x10400, v195
	v_add_u32_e32 v158, 0x14400, v195
	ds_read_b128 v[114:117], v134
	ds_read_b128 v[118:121], v134 offset:1024
	ds_read_b128 v[130:133], v134 offset:2048
	ds_read_b128 v[134:137], v134 offset:3072
	ds_read_b128 v[146:149], v158
	ds_read_b128 v[150:153], v158 offset:1024
	ds_read_b128 v[154:157], v158 offset:2048
	ds_read_b128 v[158:161], v158 offset:3072
	ds_read_b128 v[172:175], v194 offset:1024
	ds_read_b128 v[176:179], v194 offset:2048
	ds_read_b128 v[180:183], v194 offset:3072
	ds_read_b128 v[184:187], v194 offset:4096
	ds_read_b128 v[188:191], v194 offset:5120
	ds_read_b128 v[196:199], v194 offset:6144
	ds_read_b128 v[200:203], v194 offset:7168
	ds_read_b128 v[204:207], v194 offset:8192
	s_waitcnt vmcnt(8)
	s_waitcnt lgkmcnt(0)
	s_setprio 1
	s_barrier
	v_mfma_f32_16x16x32_bf16 v[142:145], v[114:117], v[172:175], v[142:145]
	v_mfma_f32_16x16x32_bf16 v[138:141], v[130:133], v[172:175], v[138:141]
	v_mfma_f32_16x16x32_bf16 v[126:129], v[114:117], v[180:183], v[126:129]
	v_mfma_f32_16x16x32_bf16 v[122:125], v[130:133], v[180:183], v[122:125]
	v_mfma_f32_16x16x32_bf16 v[110:113], v[114:117], v[188:191], v[110:113]
	v_mfma_f32_16x16x32_bf16 v[106:109], v[130:133], v[188:191], v[106:109]
	v_mfma_f32_16x16x32_bf16 v[102:105], v[114:117], v[200:203], v[102:105]
	v_mfma_f32_16x16x32_bf16 v[98:101], v[130:133], v[200:203], v[98:101]
	v_mfma_f32_16x16x32_bf16 v[142:145], v[118:121], v[176:179], v[142:145]
	v_mfma_f32_16x16x32_bf16 v[138:141], v[134:137], v[176:179], v[138:141]
	v_mfma_f32_16x16x32_bf16 v[126:129], v[118:121], v[184:187], v[126:129]
	v_mfma_f32_16x16x32_bf16 v[122:125], v[134:137], v[184:187], v[122:125]
	v_mfma_f32_16x16x32_bf16 v[110:113], v[118:121], v[196:199], v[110:113]
	v_mfma_f32_16x16x32_bf16 v[106:109], v[134:137], v[196:199], v[106:109]
	v_mfma_f32_16x16x32_bf16 v[102:105], v[118:121], v[204:207], v[102:105]
	v_mfma_f32_16x16x32_bf16 v[98:101], v[134:137], v[204:207], v[98:101]
	s_setprio 0
	s_setprio 1
	v_mfma_f32_16x16x32_bf16 v[62:65], v[146:149], v[172:175], v[62:65]
	v_mfma_f32_16x16x32_bf16 v[58:61], v[154:157], v[172:175], v[58:61]
	v_mfma_f32_16x16x32_bf16 v[54:57], v[146:149], v[180:183], v[54:57]
	v_mfma_f32_16x16x32_bf16 v[50:53], v[154:157], v[180:183], v[50:53]
	v_mfma_f32_16x16x32_bf16 v[46:49], v[146:149], v[188:191], v[46:49]
	v_mfma_f32_16x16x32_bf16 v[42:45], v[154:157], v[188:191], v[42:45]
	v_mfma_f32_16x16x32_bf16 v[38:41], v[146:149], v[200:203], v[38:41]
	v_mfma_f32_16x16x32_bf16 v[34:37], v[154:157], v[200:203], v[34:37]
	v_mfma_f32_16x16x32_bf16 v[62:65], v[150:153], v[176:179], v[62:65]
	v_mfma_f32_16x16x32_bf16 v[58:61], v[158:161], v[176:179], v[58:61]
	v_mfma_f32_16x16x32_bf16 v[54:57], v[150:153], v[184:187], v[54:57]
	v_mfma_f32_16x16x32_bf16 v[50:53], v[158:161], v[184:187], v[50:53]
	v_mfma_f32_16x16x32_bf16 v[46:49], v[150:153], v[196:199], v[46:49]
	v_mfma_f32_16x16x32_bf16 v[42:45], v[158:161], v[196:199], v[42:45]
	v_mfma_f32_16x16x32_bf16 v[38:41], v[150:153], v[204:207], v[38:41]
	v_mfma_f32_16x16x32_bf16 v[34:37], v[158:161], v[204:207], v[34:37]
	s_barrier
	s_setprio 0
	s_mov_b32 m0, s34
	v_lshl_add_u64 v[192:193], s[22:23], 0, v[0:1]
	s_add_u32 s18, s22, 0x18000
	global_load_lds_dwordx4 v[192:193], off
	v_lshl_add_u64 v[208:209], s[22:23], 0, v[162:163]
	s_mov_b32 m0, s35
	s_addc_u32 s19, s23, 0
	global_load_lds_dwordx4 v[208:209], off
	v_lshl_add_u64 v[210:211], s[18:19], 0, v[0:1]
	s_mov_b32 m0, s36
	v_lshl_add_u64 v[212:213], s[24:25], 0, v[164:165]
	global_load_lds_dwordx4 v[210:211], off
	v_lshl_add_u64 v[210:211], s[18:19], 0, v[162:163]
	s_mov_b32 m0, s37
	s_nop 0
	global_load_lds_dwordx4 v[210:211], off
	v_lshl_add_u64 v[210:211], s[24:25], 0, v[166:167]
	s_mov_b32 m0, s38
	s_nop 0
	global_load_lds_dwordx4 v[210:211], off
	s_mov_b32 m0, s39
	s_nop 0
	global_load_lds_dwordx4 v[212:213], off
	ds_read_b128 v[172:175], v194 offset:17408
	ds_read_b128 v[176:179], v194 offset:18432
	ds_read_b128 v[180:183], v194 offset:19456
	ds_read_b128 v[184:187], v194 offset:20480
	ds_read_b128 v[188:191], v194 offset:21504
	ds_read_b128 v[196:199], v194 offset:22528
	ds_read_b128 v[200:203], v194 offset:23552
	ds_read_b128 v[204:207], v194 offset:24576
	s_waitcnt vmcnt(8)
	s_waitcnt lgkmcnt(0)
	s_setprio 1
	s_barrier
; #define PG8_STAGE(bufoff, gbase, voff) do { _Pragma("unroll") for (int _i = 0; _i < 2; ++_i) \
;         __builtin_amdgcn_global_load_lds((const GAS unsigned*)((const GAS char*)(gbase) + (voff)[_i]), (LAS unsigned*)(lds + (bufoff) + ldsw + _i * 8192), 16, 0, 0); } while (0)
; #define PG8_LDA(dst, b, h) do { _Pragma("unroll") for (int m = 0; m < 4; ++m) _Pragma("unroll") for (int k = 0; k < 2; ++k) dst[m][k] = *(const LAS bf16x8*)(lds + PG8_SA(b, h) + aoff + m * 2048 + k * 1024); } while (0)
; #define PG8_LDB(dst, b, h) do { _Pragma("unroll") for (int n = 0; n < 2; ++n) _Pragma("unroll") for (int k = 0; k < 2; ++k) dst[n][k] = *(const LAS bf16x8*)(lds + PG8_SB(b, h) + boff + n * 2048 + k * 1024); } while (0)
; #define PG8_MMA(ai, bj, At, Bt) do { __builtin_amdgcn_s_setprio(1); _Pragma("unroll") for (int m = 0; m < 4; ++m) _Pragma("unroll") for (int n = 0; n < 2; ++n) _Pragma("unroll") for (int k = 0; k < 2; ++k) \
;         acc[ai][bj][m][n] = __builtin_amdgcn_mfma_f32_16x16x32_bf16(Bt[n][k], At[m][k], acc[ai][bj][m][n], 0, 0, 0); __builtin_amdgcn_s_setprio(0); } while (0)
; #define PG8_WAIT_V(n) asm volatile("s_waitcnt vmcnt(" #n ")" ::: "memory")
; #define PG8_WAIT_L(n) asm volatile("s_waitcnt lgkmcnt(" #n ")" ::: "memory")
; #define PG8_BAR __builtin_amdgcn_s_barrier()
; #define PG8_SCHED __builtin_amdgcn_sched_barrier(0)
; template <class Epi, class Sched, bool ALIGN_EPI>
; __device__ __forceinline__ void gemm_phase(LAS unsigned char* lds, const Gemm g, const Sched& S, const Epi& E, int wave_id) {
;     ...
;             PG8_WAIT_V(8); PG8_WAIT_L(0); PG8_BAR; PG8_MMA(1, 0, At, B0); PG8_MMA(1, 1, At, B1); PG8_BAR; PG8_SCHED;
;             PG8_LDB(B0, 1, 0); PG8_LDB(B1, 1, 1); PG8_SCHED; PG8_LDA(At, 1, 0); PG8_STAGE(PG8_SA(0, 1), a2 + hsA, voffA);
;             PG8_WAIT_V(8); PG8_WAIT_L(0); PG8_BAR; PG8_MMA(0, 0, At, B0); PG8_MMA(0, 1, At, B1); PG8_BAR; PG8_SCHED;
	v_mfma_f32_16x16x32_bf16 v[94:97], v[114:117], v[172:175], v[94:97]
	v_mfma_f32_16x16x32_bf16 v[90:93], v[130:133], v[172:175], v[90:93]
	v_mfma_f32_16x16x32_bf16 v[86:89], v[114:117], v[180:183], v[86:89]
	v_mfma_f32_16x16x32_bf16 v[82:85], v[130:133], v[180:183], v[82:85]
	v_mfma_f32_16x16x32_bf16 v[78:81], v[114:117], v[188:191], v[78:81]
	v_mfma_f32_16x16x32_bf16 v[74:77], v[130:133], v[188:191], v[74:77]
	v_mfma_f32_16x16x32_bf16 v[70:73], v[114:117], v[200:203], v[70:73]
	v_mfma_f32_16x16x32_bf16 v[66:69], v[130:133], v[200:203], v[66:69]
	v_mfma_f32_16x16x32_bf16 v[94:97], v[118:121], v[176:179], v[94:97]
	v_mfma_f32_16x16x32_bf16 v[90:93], v[134:137], v[176:179], v[90:93]
	v_mfma_f32_16x16x32_bf16 v[86:89], v[118:121], v[184:187], v[86:89]
	v_mfma_f32_16x16x32_bf16 v[82:85], v[134:137], v[184:187], v[82:85]
	v_mfma_f32_16x16x32_bf16 v[78:81], v[118:121], v[196:199], v[78:81]
	v_mfma_f32_16x16x32_bf16 v[74:77], v[134:137], v[196:199], v[74:77]
	v_mfma_f32_16x16x32_bf16 v[70:73], v[118:121], v[204:207], v[70:73]
	v_mfma_f32_16x16x32_bf16 v[66:69], v[134:137], v[204:207], v[66:69]
	s_setprio 0
	s_setprio 1
	v_mfma_f32_16x16x32_bf16 v[30:33], v[146:149], v[172:175], v[30:33]
	v_mfma_f32_16x16x32_bf16 v[26:29], v[154:157], v[172:175], v[26:29]
	v_mfma_f32_16x16x32_bf16 v[22:25], v[146:149], v[180:183], v[22:25]
	v_mfma_f32_16x16x32_bf16 v[18:21], v[154:157], v[180:183], v[18:21]
	v_mfma_f32_16x16x32_bf16 v[14:17], v[146:149], v[188:191], v[14:17]
	v_mfma_f32_16x16x32_bf16 v[10:13], v[154:157], v[188:191], v[10:13]
	v_mfma_f32_16x16x32_bf16 v[6:9], v[146:149], v[200:203], v[6:9]
	v_mfma_f32_16x16x32_bf16 v[2:5], v[154:157], v[200:203], v[2:5]
	v_mfma_f32_16x16x32_bf16 v[30:33], v[150:153], v[176:179], v[30:33]
	v_mfma_f32_16x16x32_bf16 v[26:29], v[158:161], v[176:179], v[26:29]
	v_mfma_f32_16x16x32_bf16 v[22:25], v[150:153], v[184:187], v[22:25]
	v_mfma_f32_16x16x32_bf16 v[18:21], v[158:161], v[184:187], v[18:21]
	v_mfma_f32_16x16x32_bf16 v[14:17], v[150:153], v[196:199], v[14:17]
	v_mfma_f32_16x16x32_bf16 v[10:13], v[158:161], v[196:199], v[10:13]
	v_mfma_f32_16x16x32_bf16 v[6:9], v[150:153], v[204:207], v[6:9]
	v_mfma_f32_16x16x32_bf16 v[2:5], v[158:161], v[204:207], v[2:5]
	s_barrier
	s_setprio 0
	s_add_u32 s18, s24, 0x18000
	s_addc_u32 s19, s25, 0
	s_mov_b32 m0, s40
	v_lshl_add_u64 v[214:215], s[18:19], 0, v[166:167]
	global_load_lds_dwordx4 v[214:215], off
	v_lshl_add_u64 v[214:215], s[18:19], 0, v[164:165]
	s_mov_b32 m0, s41
	s_nop 0
	global_load_lds_dwordx4 v[214:215], off
	v_add_u32_e32 v134, 0x18400, v195
	v_add_u32_e32 v158, 0x1c400, v195
	ds_read_b128 v[114:117], v134
	ds_read_b128 v[118:121], v134 offset:1024
	ds_read_b128 v[130:133], v134 offset:2048
	ds_read_b128 v[134:137], v134 offset:3072
	ds_read_b128 v[146:149], v158
	ds_read_b128 v[150:153], v158 offset:1024
	ds_read_b128 v[154:157], v158 offset:2048
	ds_read_b128 v[158:161], v158 offset:3072
	ds_read_b128 v[172:175], v194 offset:33792
	ds_read_b128 v[176:179], v194 offset:34816
	ds_read_b128 v[180:183], v194 offset:35840
	ds_read_b128 v[184:187], v194 offset:36864
	ds_read_b128 v[188:191], v194 offset:37888
	ds_read_b128 v[196:199], v194 offset:38912
	ds_read_b128 v[200:203], v194 offset:39936
	ds_read_b128 v[204:207], v194 offset:40960
	s_waitcnt vmcnt(8)
	s_waitcnt lgkmcnt(0)
	s_setprio 1
	s_barrier
	v_mfma_f32_16x16x32_bf16 v[142:145], v[114:117], v[172:175], v[142:145]
	v_mfma_f32_16x16x32_bf16 v[138:141], v[130:133], v[172:175], v[138:141]
	v_mfma_f32_16x16x32_bf16 v[126:129], v[114:117], v[180:183], v[126:129]
	v_mfma_f32_16x16x32_bf16 v[122:125], v[130:133], v[180:183], v[122:125]
	v_mfma_f32_16x16x32_bf16 v[110:113], v[114:117], v[188:191], v[110:113]
	v_mfma_f32_16x16x32_bf16 v[106:109], v[130:133], v[188:191], v[106:109]
	v_mfma_f32_16x16x32_bf16 v[102:105], v[114:117], v[200:203], v[102:105]
	v_mfma_f32_16x16x32_bf16 v[98:101], v[130:133], v[200:203], v[98:101]
	v_mfma_f32_16x16x32_bf16 v[142:145], v[118:121], v[176:179], v[142:145]
	v_mfma_f32_16x16x32_bf16 v[138:141], v[134:137], v[176:179], v[138:141]
	v_mfma_f32_16x16x32_bf16 v[126:129], v[118:121], v[184:187], v[126:129]
	v_mfma_f32_16x16x32_bf16 v[122:125], v[134:137], v[184:187], v[122:125]
	v_mfma_f32_16x16x32_bf16 v[110:113], v[118:121], v[196:199], v[110:113]
	v_mfma_f32_16x16x32_bf16 v[106:109], v[134:137], v[196:199], v[106:109]
	v_mfma_f32_16x16x32_bf16 v[102:105], v[118:121], v[204:207], v[102:105]
	v_mfma_f32_16x16x32_bf16 v[98:101], v[134:137], v[204:207], v[98:101]
	s_setprio 0
	s_setprio 1
	v_mfma_f32_16x16x32_bf16 v[62:65], v[146:149], v[172:175], v[62:65]
	v_mfma_f32_16x16x32_bf16 v[58:61], v[154:157], v[172:175], v[58:61]
	v_mfma_f32_16x16x32_bf16 v[54:57], v[146:149], v[180:183], v[54:57]
	v_mfma_f32_16x16x32_bf16 v[50:53], v[154:157], v[180:183], v[50:53]
	v_mfma_f32_16x16x32_bf16 v[46:49], v[146:149], v[188:191], v[46:49]
	v_mfma_f32_16x16x32_bf16 v[42:45], v[154:157], v[188:191], v[42:45]
	v_mfma_f32_16x16x32_bf16 v[38:41], v[146:149], v[200:203], v[38:41]
	v_mfma_f32_16x16x32_bf16 v[34:37], v[154:157], v[200:203], v[34:37]
	v_mfma_f32_16x16x32_bf16 v[62:65], v[150:153], v[176:179], v[62:65]
	v_mfma_f32_16x16x32_bf16 v[58:61], v[158:161], v[176:179], v[58:61]
	v_mfma_f32_16x16x32_bf16 v[54:57], v[150:153], v[184:187], v[54:57]
	v_mfma_f32_16x16x32_bf16 v[50:53], v[158:161], v[184:187], v[50:53]
	v_mfma_f32_16x16x32_bf16 v[46:49], v[150:153], v[196:199], v[46:49]
	v_mfma_f32_16x16x32_bf16 v[42:45], v[158:161], v[196:199], v[42:45]
	v_mfma_f32_16x16x32_bf16 v[38:41], v[150:153], v[204:207], v[38:41]
	v_mfma_f32_16x16x32_bf16 v[34:37], v[158:161], v[204:207], v[34:37]
	s_barrier
; #define PG8_STAGE(bufoff, gbase, voff) do { _Pragma("unroll") for (int _i = 0; _i < 2; ++_i) \
;         __builtin_amdgcn_global_load_lds((const GAS unsigned*)((const GAS char*)(gbase) + (voff)[_i]), (LAS unsigned*)(lds + (bufoff) + ldsw + _i * 8192), 16, 0, 0); } while (0)
; #define PG8_LDA(dst, b, h) do { _Pragma("unroll") for (int m = 0; m < 4; ++m) _Pragma("unroll") for (int k = 0; k < 2; ++k) dst[m][k] = *(const LAS bf16x8*)(lds + PG8_SA(b, h) + aoff + m * 2048 + k * 1024); } while (0)
; #define PG8_MMA(ai, bj, At, Bt) do { __builtin_amdgcn_s_setprio(1); _Pragma("unroll") for (int m = 0; m < 4; ++m) _Pragma("unroll") for (int n = 0; n < 2; ++n) _Pragma("unroll") for (int k = 0; k < 2; ++k) \
;         acc[ai][bj][m][n] = __builtin_amdgcn_mfma_f32_16x16x32_bf16(Bt[n][k], At[m][k], acc[ai][bj][m][n], 0, 0, 0); __builtin_amdgcn_s_setprio(0); } while (0)
; #define PG8_WAIT_V(n) asm volatile("s_waitcnt vmcnt(" #n ")" ::: "memory")
; #define PG8_WAIT_L(n) asm volatile("s_waitcnt lgkmcnt(" #n ")" ::: "memory")
; #define PG8_BAR __builtin_amdgcn_s_barrier()
; #define PG8_SCHED __builtin_amdgcn_sched_barrier(0)
; template <class Epi, class Sched, bool ALIGN_EPI>
; __device__ __forceinline__ void gemm_phase(LAS unsigned char* lds, const Gemm g, const Sched& S, const Epi& E, int wave_id) {
;     ...
;             PG8_LDA(At, 1, 1); PG8_STAGE(PG8_SB(1, 0), b3, voffB); PG8_STAGE(PG8_SB(1, 1), b3 + hsB, voffB); PG8_STAGE(PG8_SA(1, 0), a3, voffA);
;             PG8_WAIT_V(8); PG8_WAIT_L(0); PG8_BAR; PG8_MMA(1, 0, At, B0); PG8_MMA(1, 1, At, B1); PG8_BAR; PG8_SCHED;
;         }
;         if constexpr (ALIGN_EPI) { if (wr == 0) PG8_BAR; }
	s_setprio 0
	s_mov_b32 m0, s44
	v_lshl_add_u64 v[192:193], v[192:193], 0, s[92:93]
	s_add_u32 s18, s22, 0x18080
	global_load_lds_dwordx4 v[192:193], off
	v_lshl_add_u64 v[192:193], v[208:209], 0, s[92:93]
	s_mov_b32 m0, s45
	s_addc_u32 s19, s23, 0
	global_load_lds_dwordx4 v[192:193], off
	v_lshl_add_u64 v[192:193], s[18:19], 0, v[0:1]
	s_mov_b32 m0, s48
	s_nop 0
	global_load_lds_dwordx4 v[192:193], off
	v_lshl_add_u64 v[192:193], s[18:19], 0, v[162:163]
	s_mov_b32 m0, s49
	s_nop 0
	global_load_lds_dwordx4 v[192:193], off
	v_lshl_add_u64 v[192:193], v[210:211], 0, s[92:93]
	s_mov_b32 m0, s46
	s_nop 0
	global_load_lds_dwordx4 v[192:193], off
	v_lshl_add_u64 v[192:193], v[212:213], 0, s[92:93]
	s_mov_b32 m0, s47
	s_nop 0
	global_load_lds_dwordx4 v[192:193], off
	ds_read_b128 v[172:175], v194 offset:50176
	ds_read_b128 v[176:179], v194 offset:51200
	ds_read_b128 v[180:183], v194 offset:52224
	ds_read_b128 v[184:187], v194 offset:53248
	ds_read_b128 v[188:191], v194 offset:54272
	ds_read_b128 v[196:199], v194 offset:55296
	ds_read_b128 v[200:203], v194 offset:56320
	ds_read_b128 v[204:207], v194 offset:57344
	s_waitcnt vmcnt(8)
	s_waitcnt lgkmcnt(0)
	s_setprio 1
	s_barrier
	v_mfma_f32_16x16x32_bf16 v[94:97], v[114:117], v[172:175], v[94:97]
	v_mfma_f32_16x16x32_bf16 v[90:93], v[130:133], v[172:175], v[90:93]
	v_mfma_f32_16x16x32_bf16 v[86:89], v[114:117], v[180:183], v[86:89]
	v_mfma_f32_16x16x32_bf16 v[82:85], v[130:133], v[180:183], v[82:85]
	v_mfma_f32_16x16x32_bf16 v[78:81], v[114:117], v[188:191], v[78:81]
	v_mfma_f32_16x16x32_bf16 v[74:77], v[130:133], v[188:191], v[74:77]
	v_mfma_f32_16x16x32_bf16 v[70:73], v[114:117], v[200:203], v[70:73]
	v_mfma_f32_16x16x32_bf16 v[66:69], v[130:133], v[200:203], v[66:69]
	v_mfma_f32_16x16x32_bf16 v[94:97], v[118:121], v[176:179], v[94:97]
	v_mfma_f32_16x16x32_bf16 v[90:93], v[134:137], v[176:179], v[90:93]
	v_mfma_f32_16x16x32_bf16 v[86:89], v[118:121], v[184:187], v[86:89]
	v_mfma_f32_16x16x32_bf16 v[82:85], v[134:137], v[184:187], v[82:85]
	v_mfma_f32_16x16x32_bf16 v[78:81], v[118:121], v[196:199], v[78:81]
	v_mfma_f32_16x16x32_bf16 v[74:77], v[134:137], v[196:199], v[74:77]
	v_mfma_f32_16x16x32_bf16 v[70:73], v[118:121], v[204:207], v[70:73]
	v_mfma_f32_16x16x32_bf16 v[66:69], v[134:137], v[204:207], v[66:69]
	s_setprio 0
	s_setprio 1
	v_mfma_f32_16x16x32_bf16 v[30:33], v[146:149], v[172:175], v[30:33]
	v_mfma_f32_16x16x32_bf16 v[26:29], v[154:157], v[172:175], v[26:29]
	v_mfma_f32_16x16x32_bf16 v[22:25], v[146:149], v[180:183], v[22:25]
	v_mfma_f32_16x16x32_bf16 v[18:21], v[154:157], v[180:183], v[18:21]
	v_mfma_f32_16x16x32_bf16 v[14:17], v[146:149], v[188:191], v[14:17]
	v_mfma_f32_16x16x32_bf16 v[10:13], v[154:157], v[188:191], v[10:13]
	v_mfma_f32_16x16x32_bf16 v[6:9], v[146:149], v[200:203], v[6:9]
	v_mfma_f32_16x16x32_bf16 v[2:5], v[154:157], v[200:203], v[2:5]
	v_mfma_f32_16x16x32_bf16 v[30:33], v[150:153], v[176:179], v[30:33]
	v_mfma_f32_16x16x32_bf16 v[26:29], v[158:161], v[176:179], v[26:29]
	v_mfma_f32_16x16x32_bf16 v[22:25], v[150:153], v[184:187], v[22:25]
	v_mfma_f32_16x16x32_bf16 v[18:21], v[158:161], v[184:187], v[18:21]
	v_mfma_f32_16x16x32_bf16 v[14:17], v[150:153], v[196:199], v[14:17]
	v_mfma_f32_16x16x32_bf16 v[10:13], v[158:161], v[196:199], v[10:13]
	v_mfma_f32_16x16x32_bf16 v[6:9], v[150:153], v[204:207], v[6:9]
	v_mfma_f32_16x16x32_bf16 v[2:5], v[158:161], v[204:207], v[2:5]
	s_barrier
	s_setprio 0
	s_add_i32 s55, s55, 2
	s_add_u32 s53, s53, 0x100
	s_addc_u32 s54, s54, 0
	s_cmp_gt_u32 s55, 3
	s_mov_b64 s[18:19], s[20:21]
	s_cbranch_scc0 .LBB0_1645
	s_and_b64 vcc, exec, s[12:13]
	s_cbranch_vccz .LBB0_1648
	s_barrier

; #define GAS __attribute__((address_space(1)))
; #define PG8_STAGE(bufoff, gbase, voff) do { _Pragma("unroll") for (int _i = 0; _i < 2; ++_i) \
;         __builtin_amdgcn_global_load_lds((const GAS unsigned*)((const GAS char*)(gbase) + (voff)[_i]), (LAS unsigned*)(lds + (bufoff) + ldsw + _i * 8192), 16, 0, 0); } while (0)
; #define PG8_LDA(dst, b, h) do { _Pragma("unroll") for (int m = 0; m < 4; ++m) _Pragma("unroll") for (int k = 0; k < 2; ++k) dst[m][k] = *(const LAS bf16x8*)(lds + PG8_SA(b, h) + aoff + m * 2048 + k * 1024); } while (0)
; #define PG8_LDB(dst, b, h) do { _Pragma("unroll") for (int n = 0; n < 2; ++n) _Pragma("unroll") for (int k = 0; k < 2; ++k) dst[n][k] = *(const LAS bf16x8*)(lds + PG8_SB(b, h) + boff + n * 2048 + k * 1024); } while (0)
; #define PG8_MMA(ai, bj, At, Bt) do { __builtin_amdgcn_s_setprio(1); _Pragma("unroll") for (int m = 0; m < 4; ++m) _Pragma("unroll") for (int n = 0; n < 2; ++n) _Pragma("unroll") for (int k = 0; k < 2; ++k) \
;         acc[ai][bj][m][n] = __builtin_amdgcn_mfma_f32_16x16x32_bf16(Bt[n][k], At[m][k], acc[ai][bj][m][n], 0, 0, 0); __builtin_amdgcn_s_setprio(0); } while (0)
; #define PG8_WAIT_V(n) asm volatile("s_waitcnt vmcnt(" #n ")" ::: "memory")
; #define PG8_WAIT_L(n) asm volatile("s_waitcnt lgkmcnt(" #n ")" ::: "memory")
; #define PG8_BAR __builtin_amdgcn_s_barrier()
; #define PG8_SCHED __builtin_amdgcn_sched_barrier(0)
; template <class Epi, class Sched, bool ALIGN_EPI>
; __device__ __forceinline__ void gemm_phase(LAS unsigned char* lds, const Gemm g, const Sched& S, const Epi& E, int wave_id) {
;     ...
;             const bool last = (t == nt - 2);
;             const GAS char* a1 = cA + (size_t)(t + 1) * kstep;
;             const GAS char* a2 = last ? nA : cA + (size_t)(t + 2) * kstep; const GAS char* b2 = last ? nB : cB + (size_t)(t + 2) * kstep;
;             const GAS char* a3 = a2 + kstep; const GAS char* b3 = b2 + kstep;
;             PG8_LDB(B0, 0, 0); PG8_LDB(B1, 0, 1); PG8_SCHED; PG8_LDA(At, 0, 0); PG8_STAGE(PG8_SA(1, 1), a1 + hsA, voffA);
;             PG8_WAIT_V(8); PG8_WAIT_L(0); PG8_BAR; PG8_MMA(0, 0, At, B0); PG8_MMA(0, 1, At, B1); PG8_BAR; PG8_SCHED;
;             PG8_LDA(At, 0, 1); PG8_STAGE(PG8_SB(0, 0), b2, voffB); PG8_STAGE(PG8_SB(0, 1), b2 + hsB, voffB); PG8_STAGE(PG8_SA(0, 0), a2, voffA);
.LBB0_1837:
	s_add_u32 s42, s40, 0xfffc0080
	s_addc_u32 s43, s41, -1
	s_cmp_eq_u32 s67, 12
	s_cselect_b32 s45, s5, s43
	s_cselect_b32 s44, s25, s42
	s_cselect_b32 s43, s27, s66
	s_cselect_b32 s42, s37, s39
	v_lshl_add_u64 v[196:197], s[40:41], 0, v[182:183]
	s_add_i32 m0, s1, 0xc400
	s_nop 0
	global_load_lds_dwordx4 v[196:197], off
	v_lshl_add_u64 v[196:197], s[40:41], 0, v[180:181]
	s_add_i32 m0, s1, 0xe400
	s_nop 0
	global_load_lds_dwordx4 v[196:197], off
	v_add_u32_e32 v142, 0x10400, v199
	v_add_u32_e32 v158, 0x14400, v199
	ds_read_b128 v[130:133], v142
	ds_read_b128 v[134:137], v142 offset:1024
	ds_read_b128 v[138:141], v142 offset:2048
	ds_read_b128 v[142:145], v142 offset:3072
	ds_read_b128 v[146:149], v158
	ds_read_b128 v[150:153], v158 offset:1024
	ds_read_b128 v[154:157], v158 offset:2048
	ds_read_b128 v[158:161], v158 offset:3072
	ds_read_b128 v[162:165], v198 offset:1024
	ds_read_b128 v[166:169], v198 offset:2048
	ds_read_b128 v[170:173], v198 offset:3072
	ds_read_b128 v[184:187], v198 offset:4096
	ds_read_b128 v[188:191], v198 offset:5120
	ds_read_b128 v[192:195], v198 offset:6144
	ds_read_b128 v[200:203], v198 offset:7168
	ds_read_b128 v[204:207], v198 offset:8192
	s_waitcnt vmcnt(8)
	s_waitcnt lgkmcnt(0)
	s_setprio 1
	s_barrier
	v_mfma_f32_16x16x32_bf16 v[126:129], v[130:133], v[162:165], v[126:129]
	v_mfma_f32_16x16x32_bf16 v[122:125], v[138:141], v[162:165], v[122:125]
	v_mfma_f32_16x16x32_bf16 v[114:117], v[130:133], v[170:173], v[114:117]
	v_mfma_f32_16x16x32_bf16 v[106:109], v[138:141], v[170:173], v[106:109]
	v_mfma_f32_16x16x32_bf16 v[98:101], v[130:133], v[188:191], v[98:101]
	v_mfma_f32_16x16x32_bf16 v[90:93], v[138:141], v[188:191], v[90:93]
	v_mfma_f32_16x16x32_bf16 v[82:85], v[130:133], v[200:203], v[82:85]
	v_mfma_f32_16x16x32_bf16 v[74:77], v[138:141], v[200:203], v[74:77]
	v_mfma_f32_16x16x32_bf16 v[126:129], v[134:137], v[166:169], v[126:129]
	v_mfma_f32_16x16x32_bf16 v[122:125], v[142:145], v[166:169], v[122:125]
	v_mfma_f32_16x16x32_bf16 v[114:117], v[134:137], v[184:187], v[114:117]
	v_mfma_f32_16x16x32_bf16 v[106:109], v[142:145], v[184:187], v[106:109]
	v_mfma_f32_16x16x32_bf16 v[98:101], v[134:137], v[192:195], v[98:101]
	v_mfma_f32_16x16x32_bf16 v[90:93], v[142:145], v[192:195], v[90:93]
	v_mfma_f32_16x16x32_bf16 v[82:85], v[134:137], v[204:207], v[82:85]
	v_mfma_f32_16x16x32_bf16 v[74:77], v[142:145], v[204:207], v[74:77]
	s_setprio 0
	s_setprio 1
	v_mfma_f32_16x16x32_bf16 v[118:121], v[146:149], v[162:165], v[118:121]
	v_mfma_f32_16x16x32_bf16 v[110:113], v[154:157], v[162:165], v[110:113]
	v_mfma_f32_16x16x32_bf16 v[102:105], v[146:149], v[170:173], v[102:105]
	v_mfma_f32_16x16x32_bf16 v[94:97], v[154:157], v[170:173], v[94:97]
	v_mfma_f32_16x16x32_bf16 v[86:89], v[146:149], v[188:191], v[86:89]
	v_mfma_f32_16x16x32_bf16 v[78:81], v[154:157], v[188:191], v[78:81]
	v_mfma_f32_16x16x32_bf16 v[70:73], v[146:149], v[200:203], v[70:73]
	v_mfma_f32_16x16x32_bf16 v[66:69], v[154:157], v[200:203], v[66:69]
	v_mfma_f32_16x16x32_bf16 v[118:121], v[150:153], v[166:169], v[118:121]
	v_mfma_f32_16x16x32_bf16 v[110:113], v[158:161], v[166:169], v[110:113]
	v_mfma_f32_16x16x32_bf16 v[102:105], v[150:153], v[184:187], v[102:105]
	v_mfma_f32_16x16x32_bf16 v[94:97], v[158:161], v[184:187], v[94:97]
	v_mfma_f32_16x16x32_bf16 v[86:89], v[150:153], v[192:195], v[86:89]
	v_mfma_f32_16x16x32_bf16 v[78:81], v[158:161], v[192:195], v[78:81]
	v_mfma_f32_16x16x32_bf16 v[70:73], v[150:153], v[204:207], v[70:73]
	v_mfma_f32_16x16x32_bf16 v[66:69], v[158:161], v[204:207], v[66:69]
	s_barrier
	s_setprio 0
	s_mov_b32 m0, s48
	v_lshl_add_u64 v[196:197], s[42:43], 0, v[0:1]
	s_add_u32 s68, s42, 0x40000
	global_load_lds_dwordx4 v[196:197], off
	v_lshl_add_u64 v[208:209], s[42:43], 0, v[178:179]
	s_mov_b32 m0, s49
	s_addc_u32 s69, s43, 0
	global_load_lds_dwordx4 v[208:209], off
	v_lshl_add_u64 v[210:211], s[68:69], 0, v[0:1]
	s_mov_b32 m0, s50
	v_lshl_add_u64 v[212:213], s[44:45], 0, v[176:177]
	global_load_lds_dwordx4 v[210:211], off
	v_lshl_add_u64 v[210:211], s[68:69], 0, v[178:179]
	s_mov_b32 m0, s51
	s_nop 0
	global_load_lds_dwordx4 v[210:211], off
	v_lshl_add_u64 v[210:211], s[44:45], 0, v[174:175]
	s_mov_b32 m0, s52
	s_nop 0
	global_load_lds_dwordx4 v[210:211], off
	s_mov_b32 m0, s53
	s_nop 0
	global_load_lds_dwordx4 v[212:213], off
	ds_read_b128 v[162:165], v198 offset:17408
	ds_read_b128 v[166:169], v198 offset:18432
	ds_read_b128 v[170:173], v198 offset:19456
	ds_read_b128 v[184:187], v198 offset:20480
	ds_read_b128 v[188:191], v198 offset:21504
	ds_read_b128 v[192:195], v198 offset:22528
	ds_read_b128 v[200:203], v198 offset:23552
	ds_read_b128 v[204:207], v198 offset:24576
	s_waitcnt vmcnt(8)
	s_waitcnt lgkmcnt(0)
	s_setprio 1
	s_barrier
; #define PG8_STAGE(bufoff, gbase, voff) do { _Pragma("unroll") for (int _i = 0; _i < 2; ++_i) \
;         __builtin_amdgcn_global_load_lds((const GAS unsigned*)((const GAS char*)(gbase) + (voff)[_i]), (LAS unsigned*)(lds + (bufoff) + ldsw + _i * 8192), 16, 0, 0); } while (0)
; #define PG8_LDA(dst, b, h) do { _Pragma("unroll") for (int m = 0; m < 4; ++m) _Pragma("unroll") for (int k = 0; k < 2; ++k) dst[m][k] = *(const LAS bf16x8*)(lds + PG8_SA(b, h) + aoff + m * 2048 + k * 1024); } while (0)
; #define PG8_LDB(dst, b, h) do { _Pragma("unroll") for (int n = 0; n < 2; ++n) _Pragma("unroll") for (int k = 0; k < 2; ++k) dst[n][k] = *(const LAS bf16x8*)(lds + PG8_SB(b, h) + boff + n * 2048 + k * 1024); } while (0)
; #define PG8_MMA(ai, bj, At, Bt) do { __builtin_amdgcn_s_setprio(1); _Pragma("unroll") for (int m = 0; m < 4; ++m) _Pragma("unroll") for (int n = 0; n < 2; ++n) _Pragma("unroll") for (int k = 0; k < 2; ++k) \
;         acc[ai][bj][m][n] = __builtin_amdgcn_mfma_f32_16x16x32_bf16(Bt[n][k], At[m][k], acc[ai][bj][m][n], 0, 0, 0); __builtin_amdgcn_s_setprio(0); } while (0)
; #define PG8_WAIT_V(n) asm volatile("s_waitcnt vmcnt(" #n ")" ::: "memory")
; #define PG8_WAIT_L(n) asm volatile("s_waitcnt lgkmcnt(" #n ")" ::: "memory")
; #define PG8_BAR __builtin_amdgcn_s_barrier()
; #define PG8_SCHED __builtin_amdgcn_sched_barrier(0)
; template <class Epi, class Sched, bool ALIGN_EPI>
; __device__ __forceinline__ void gemm_phase(LAS unsigned char* lds, const Gemm g, const Sched& S, const Epi& E, int wave_id) {
;     ...
;             PG8_WAIT_V(8); PG8_WAIT_L(0); PG8_BAR; PG8_MMA(1, 0, At, B0); PG8_MMA(1, 1, At, B1); PG8_BAR; PG8_SCHED;
;             PG8_LDB(B0, 1, 0); PG8_LDB(B1, 1, 1); PG8_SCHED; PG8_LDA(At, 1, 0); PG8_STAGE(PG8_SA(0, 1), a2 + hsA, voffA);
;             PG8_WAIT_V(8); PG8_WAIT_L(0); PG8_BAR; PG8_MMA(0, 0, At, B0); PG8_MMA(0, 1, At, B1); PG8_BAR; PG8_SCHED;
	v_mfma_f32_16x16x32_bf16 v[62:65], v[130:133], v[162:165], v[62:65]
	v_mfma_f32_16x16x32_bf16 v[58:61], v[138:141], v[162:165], v[58:61]
	v_mfma_f32_16x16x32_bf16 v[50:53], v[130:133], v[170:173], v[50:53]
	v_mfma_f32_16x16x32_bf16 v[42:45], v[138:141], v[170:173], v[42:45]
	v_mfma_f32_16x16x32_bf16 v[34:37], v[130:133], v[188:191], v[34:37]
	v_mfma_f32_16x16x32_bf16 v[26:29], v[138:141], v[188:191], v[26:29]
	v_mfma_f32_16x16x32_bf16 v[18:21], v[130:133], v[200:203], v[18:21]
	v_mfma_f32_16x16x32_bf16 v[10:13], v[138:141], v[200:203], v[10:13]
	v_mfma_f32_16x16x32_bf16 v[62:65], v[134:137], v[166:169], v[62:65]
	v_mfma_f32_16x16x32_bf16 v[58:61], v[142:145], v[166:169], v[58:61]
	v_mfma_f32_16x16x32_bf16 v[50:53], v[134:137], v[184:187], v[50:53]
	v_mfma_f32_16x16x32_bf16 v[42:45], v[142:145], v[184:187], v[42:45]
	v_mfma_f32_16x16x32_bf16 v[34:37], v[134:137], v[192:195], v[34:37]
	v_mfma_f32_16x16x32_bf16 v[26:29], v[142:145], v[192:195], v[26:29]
	v_mfma_f32_16x16x32_bf16 v[18:21], v[134:137], v[204:207], v[18:21]
	v_mfma_f32_16x16x32_bf16 v[10:13], v[142:145], v[204:207], v[10:13]
	s_setprio 0
	s_setprio 1
	v_mfma_f32_16x16x32_bf16 v[54:57], v[146:149], v[162:165], v[54:57]
	v_mfma_f32_16x16x32_bf16 v[46:49], v[154:157], v[162:165], v[46:49]
	v_mfma_f32_16x16x32_bf16 v[38:41], v[146:149], v[170:173], v[38:41]
	v_mfma_f32_16x16x32_bf16 v[30:33], v[154:157], v[170:173], v[30:33]
	v_mfma_f32_16x16x32_bf16 v[22:25], v[146:149], v[188:191], v[22:25]
	v_mfma_f32_16x16x32_bf16 v[14:17], v[154:157], v[188:191], v[14:17]
	v_mfma_f32_16x16x32_bf16 v[6:9], v[146:149], v[200:203], v[6:9]
	v_mfma_f32_16x16x32_bf16 v[2:5], v[154:157], v[200:203], v[2:5]
	v_mfma_f32_16x16x32_bf16 v[54:57], v[150:153], v[166:169], v[54:57]
	v_mfma_f32_16x16x32_bf16 v[46:49], v[158:161], v[166:169], v[46:49]
	v_mfma_f32_16x16x32_bf16 v[38:41], v[150:153], v[184:187], v[38:41]
	v_mfma_f32_16x16x32_bf16 v[30:33], v[158:161], v[184:187], v[30:33]
	v_mfma_f32_16x16x32_bf16 v[22:25], v[150:153], v[192:195], v[22:25]
	v_mfma_f32_16x16x32_bf16 v[14:17], v[158:161], v[192:195], v[14:17]
	v_mfma_f32_16x16x32_bf16 v[6:9], v[150:153], v[204:207], v[6:9]
	v_mfma_f32_16x16x32_bf16 v[2:5], v[158:161], v[204:207], v[2:5]
	s_barrier
	s_setprio 0
	s_add_u32 s44, s44, 0x40000
	s_addc_u32 s45, s45, 0
	s_mov_b32 m0, s54
	v_lshl_add_u64 v[214:215], s[44:45], 0, v[174:175]
	global_load_lds_dwordx4 v[214:215], off
	v_lshl_add_u64 v[214:215], s[44:45], 0, v[176:177]
	s_mov_b32 m0, s55
	s_nop 0
	global_load_lds_dwordx4 v[214:215], off
	v_add_u32_e32 v142, 0x18400, v199
	v_add_u32_e32 v158, 0x1c400, v199
	ds_read_b128 v[130:133], v142
	ds_read_b128 v[134:137], v142 offset:1024
	ds_read_b128 v[138:141], v142 offset:2048
	ds_read_b128 v[142:145], v142 offset:3072
	ds_read_b128 v[146:149], v158
	ds_read_b128 v[150:153], v158 offset:1024
	ds_read_b128 v[154:157], v158 offset:2048
	ds_read_b128 v[158:161], v158 offset:3072
	ds_read_b128 v[162:165], v198 offset:33792
	ds_read_b128 v[166:169], v198 offset:34816
	ds_read_b128 v[170:173], v198 offset:35840
	ds_read_b128 v[184:187], v198 offset:36864
	ds_read_b128 v[188:191], v198 offset:37888
	ds_read_b128 v[192:195], v198 offset:38912
	ds_read_b128 v[200:203], v198 offset:39936
	ds_read_b128 v[204:207], v198 offset:40960
	s_waitcnt vmcnt(8)
	s_waitcnt lgkmcnt(0)
	s_setprio 1
	s_barrier
	v_mfma_f32_16x16x32_bf16 v[126:129], v[130:133], v[162:165], v[126:129]
	v_mfma_f32_16x16x32_bf16 v[122:125], v[138:141], v[162:165], v[122:125]
	v_mfma_f32_16x16x32_bf16 v[114:117], v[130:133], v[170:173], v[114:117]
	v_mfma_f32_16x16x32_bf16 v[106:109], v[138:141], v[170:173], v[106:109]
	v_mfma_f32_16x16x32_bf16 v[98:101], v[130:133], v[188:191], v[98:101]
	v_mfma_f32_16x16x32_bf16 v[90:93], v[138:141], v[188:191], v[90:93]
	v_mfma_f32_16x16x32_bf16 v[82:85], v[130:133], v[200:203], v[82:85]
	v_mfma_f32_16x16x32_bf16 v[74:77], v[138:141], v[200:203], v[74:77]
	v_mfma_f32_16x16x32_bf16 v[126:129], v[134:137], v[166:169], v[126:129]
	v_mfma_f32_16x16x32_bf16 v[122:125], v[142:145], v[166:169], v[122:125]
	v_mfma_f32_16x16x32_bf16 v[114:117], v[134:137], v[184:187], v[114:117]
	v_mfma_f32_16x16x32_bf16 v[106:109], v[142:145], v[184:187], v[106:109]
	v_mfma_f32_16x16x32_bf16 v[98:101], v[134:137], v[192:195], v[98:101]
	v_mfma_f32_16x16x32_bf16 v[90:93], v[142:145], v[192:195], v[90:93]
	v_mfma_f32_16x16x32_bf16 v[82:85], v[134:137], v[204:207], v[82:85]
	v_mfma_f32_16x16x32_bf16 v[74:77], v[142:145], v[204:207], v[74:77]
	s_setprio 0
	s_setprio 1
	v_mfma_f32_16x16x32_bf16 v[118:121], v[146:149], v[162:165], v[118:121]
	v_mfma_f32_16x16x32_bf16 v[110:113], v[154:157], v[162:165], v[110:113]
	v_mfma_f32_16x16x32_bf16 v[102:105], v[146:149], v[170:173], v[102:105]
	v_mfma_f32_16x16x32_bf16 v[94:97], v[154:157], v[170:173], v[94:97]
	v_mfma_f32_16x16x32_bf16 v[86:89], v[146:149], v[188:191], v[86:89]
	v_mfma_f32_16x16x32_bf16 v[78:81], v[154:157], v[188:191], v[78:81]
	v_mfma_f32_16x16x32_bf16 v[70:73], v[146:149], v[200:203], v[70:73]
	v_mfma_f32_16x16x32_bf16 v[66:69], v[154:157], v[200:203], v[66:69]
	v_mfma_f32_16x16x32_bf16 v[118:121], v[150:153], v[166:169], v[118:121]
	v_mfma_f32_16x16x32_bf16 v[110:113], v[158:161], v[166:169], v[110:113]
	v_mfma_f32_16x16x32_bf16 v[102:105], v[150:153], v[184:187], v[102:105]
	v_mfma_f32_16x16x32_bf16 v[94:97], v[158:161], v[184:187], v[94:97]
	v_mfma_f32_16x16x32_bf16 v[86:89], v[150:153], v[192:195], v[86:89]
	v_mfma_f32_16x16x32_bf16 v[78:81], v[158:161], v[192:195], v[78:81]
	v_mfma_f32_16x16x32_bf16 v[70:73], v[150:153], v[204:207], v[70:73]
	v_mfma_f32_16x16x32_bf16 v[66:69], v[158:161], v[204:207], v[66:69]
	s_barrier
; #define PG8_STAGE(bufoff, gbase, voff) do { _Pragma("unroll") for (int _i = 0; _i < 2; ++_i) \
;         __builtin_amdgcn_global_load_lds((const GAS unsigned*)((const GAS char*)(gbase) + (voff)[_i]), (LAS unsigned*)(lds + (bufoff) + ldsw + _i * 8192), 16, 0, 0); } while (0)
; #define PG8_LDA(dst, b, h) do { _Pragma("unroll") for (int m = 0; m < 4; ++m) _Pragma("unroll") for (int k = 0; k < 2; ++k) dst[m][k] = *(const LAS bf16x8*)(lds + PG8_SA(b, h) + aoff + m * 2048 + k * 1024); } while (0)
; #define PG8_MMA(ai, bj, At, Bt) do { __builtin_amdgcn_s_setprio(1); _Pragma("unroll") for (int m = 0; m < 4; ++m) _Pragma("unroll") for (int n = 0; n < 2; ++n) _Pragma("unroll") for (int k = 0; k < 2; ++k) \
;         acc[ai][bj][m][n] = __builtin_amdgcn_mfma_f32_16x16x32_bf16(Bt[n][k], At[m][k], acc[ai][bj][m][n], 0, 0, 0); __builtin_amdgcn_s_setprio(0); } while (0)
; #define PG8_WAIT_V(n) asm volatile("s_waitcnt vmcnt(" #n ")" ::: "memory")
; #define PG8_WAIT_L(n) asm volatile("s_waitcnt lgkmcnt(" #n ")" ::: "memory")
; #define PG8_BAR __builtin_amdgcn_s_barrier()
; #define PG8_SCHED __builtin_amdgcn_sched_barrier(0)
; template <class Epi, class Sched, bool ALIGN_EPI>
; __device__ __forceinline__ void gemm_phase(LAS unsigned char* lds, const Gemm g, const Sched& S, const Epi& E, int wave_id) {
;     ...
;             PG8_LDA(At, 1, 1); PG8_STAGE(PG8_SB(1, 0), b3, voffB); PG8_STAGE(PG8_SB(1, 1), b3 + hsB, voffB); PG8_STAGE(PG8_SA(1, 0), a3, voffA);
;             PG8_WAIT_V(8); PG8_WAIT_L(0); PG8_BAR; PG8_MMA(1, 0, At, B0); PG8_MMA(1, 1, At, B1); PG8_BAR; PG8_SCHED;
;         }
;         if constexpr (ALIGN_EPI) { if (wr == 0) PG8_BAR; }
	s_setprio 0
	s_mov_b32 m0, s58
	v_lshl_add_u64 v[196:197], v[196:197], 0, s[92:93]
	s_add_u32 s42, s42, 0x40080
	global_load_lds_dwordx4 v[196:197], off
	v_lshl_add_u64 v[196:197], v[208:209], 0, s[92:93]
	s_mov_b32 m0, s59
	s_addc_u32 s43, s43, 0
	global_load_lds_dwordx4 v[196:197], off
	v_lshl_add_u64 v[196:197], s[42:43], 0, v[0:1]
	s_mov_b32 m0, s62
	s_nop 0
	global_load_lds_dwordx4 v[196:197], off
	v_lshl_add_u64 v[196:197], s[42:43], 0, v[178:179]
	s_mov_b32 m0, s63
	s_nop 0
	global_load_lds_dwordx4 v[196:197], off
	v_lshl_add_u64 v[196:197], v[210:211], 0, s[92:93]
	s_mov_b32 m0, s60
	s_nop 0
	global_load_lds_dwordx4 v[196:197], off
	v_lshl_add_u64 v[196:197], v[212:213], 0, s[92:93]
	s_mov_b32 m0, s61
	s_nop 0
	global_load_lds_dwordx4 v[196:197], off
	ds_read_b128 v[162:165], v198 offset:50176
	ds_read_b128 v[166:169], v198 offset:51200
	ds_read_b128 v[170:173], v198 offset:52224
	ds_read_b128 v[184:187], v198 offset:53248
	ds_read_b128 v[188:191], v198 offset:54272
	ds_read_b128 v[192:195], v198 offset:55296
	ds_read_b128 v[200:203], v198 offset:56320
	ds_read_b128 v[204:207], v198 offset:57344
	s_waitcnt vmcnt(8)
	s_waitcnt lgkmcnt(0)
	s_setprio 1
	s_barrier
	v_mfma_f32_16x16x32_bf16 v[62:65], v[130:133], v[162:165], v[62:65]
	v_mfma_f32_16x16x32_bf16 v[58:61], v[138:141], v[162:165], v[58:61]
	v_mfma_f32_16x16x32_bf16 v[50:53], v[130:133], v[170:173], v[50:53]
	v_mfma_f32_16x16x32_bf16 v[42:45], v[138:141], v[170:173], v[42:45]
	v_mfma_f32_16x16x32_bf16 v[34:37], v[130:133], v[188:191], v[34:37]
	v_mfma_f32_16x16x32_bf16 v[26:29], v[138:141], v[188:191], v[26:29]
	v_mfma_f32_16x16x32_bf16 v[18:21], v[130:133], v[200:203], v[18:21]
	v_mfma_f32_16x16x32_bf16 v[10:13], v[138:141], v[200:203], v[10:13]
	v_mfma_f32_16x16x32_bf16 v[62:65], v[134:137], v[166:169], v[62:65]
	v_mfma_f32_16x16x32_bf16 v[58:61], v[142:145], v[166:169], v[58:61]
	v_mfma_f32_16x16x32_bf16 v[50:53], v[134:137], v[184:187], v[50:53]
	v_mfma_f32_16x16x32_bf16 v[42:45], v[142:145], v[184:187], v[42:45]
	v_mfma_f32_16x16x32_bf16 v[34:37], v[134:137], v[192:195], v[34:37]
	v_mfma_f32_16x16x32_bf16 v[26:29], v[142:145], v[192:195], v[26:29]
	v_mfma_f32_16x16x32_bf16 v[18:21], v[134:137], v[204:207], v[18:21]
	v_mfma_f32_16x16x32_bf16 v[10:13], v[142:145], v[204:207], v[10:13]
	s_setprio 0
	s_setprio 1
	v_mfma_f32_16x16x32_bf16 v[54:57], v[146:149], v[162:165], v[54:57]
	v_mfma_f32_16x16x32_bf16 v[46:49], v[154:157], v[162:165], v[46:49]
	v_mfma_f32_16x16x32_bf16 v[38:41], v[146:149], v[170:173], v[38:41]
	v_mfma_f32_16x16x32_bf16 v[30:33], v[154:157], v[170:173], v[30:33]
	v_mfma_f32_16x16x32_bf16 v[22:25], v[146:149], v[188:191], v[22:25]
	v_mfma_f32_16x16x32_bf16 v[14:17], v[154:157], v[188:191], v[14:17]
	v_mfma_f32_16x16x32_bf16 v[6:9], v[146:149], v[200:203], v[6:9]
	v_mfma_f32_16x16x32_bf16 v[2:5], v[154:157], v[200:203], v[2:5]
	v_mfma_f32_16x16x32_bf16 v[54:57], v[150:153], v[166:169], v[54:57]
	v_mfma_f32_16x16x32_bf16 v[46:49], v[158:161], v[166:169], v[46:49]
	v_mfma_f32_16x16x32_bf16 v[38:41], v[150:153], v[184:187], v[38:41]
	v_mfma_f32_16x16x32_bf16 v[30:33], v[158:161], v[184:187], v[30:33]
	v_mfma_f32_16x16x32_bf16 v[22:25], v[150:153], v[192:195], v[22:25]
	v_mfma_f32_16x16x32_bf16 v[14:17], v[158:161], v[192:195], v[14:17]
	v_mfma_f32_16x16x32_bf16 v[6:9], v[150:153], v[204:207], v[6:9]
	v_mfma_f32_16x16x32_bf16 v[2:5], v[158:161], v[204:207], v[2:5]
	s_barrier
	s_setprio 0
	s_add_i32 s67, s67, 2
	s_add_u32 s39, s39, 0x100
	s_addc_u32 s66, s66, 0
	s_add_u32 s40, s40, 0x100
	s_addc_u32 s41, s41, 0
	s_cmp_gt_u32 s67, 13
	s_cbranch_scc0 .LBB0_1837
	s_and_b64 vcc, exec, s[22:23]
	s_cbranch_vccz .LBB0_1840
	s_barrier

; #define GAS __attribute__((address_space(1)))
; #define PG8_STAGE(bufoff, gbase, voff) do { _Pragma("unroll") for (int _i = 0; _i < 2; ++_i) \
;         __builtin_amdgcn_global_load_lds((const GAS unsigned*)((const GAS char*)(gbase) + (voff)[_i]), (LAS unsigned*)(lds + (bufoff) + ldsw + _i * 8192), 16, 0, 0); } while (0)
; #define PG8_LDA(dst, b, h) do { _Pragma("unroll") for (int m = 0; m < 4; ++m) _Pragma("unroll") for (int k = 0; k < 2; ++k) dst[m][k] = *(const LAS bf16x8*)(lds + PG8_SA(b, h) + aoff + m * 2048 + k * 1024); } while (0)
; #define PG8_LDB(dst, b, h) do { _Pragma("unroll") for (int n = 0; n < 2; ++n) _Pragma("unroll") for (int k = 0; k < 2; ++k) dst[n][k] = *(const LAS bf16x8*)(lds + PG8_SB(b, h) + boff + n * 2048 + k * 1024); } while (0)
; #define PG8_MMA(ai, bj, At, Bt) do { __builtin_amdgcn_s_setprio(1); _Pragma("unroll") for (int m = 0; m < 4; ++m) _Pragma("unroll") for (int n = 0; n < 2; ++n) _Pragma("unroll") for (int k = 0; k < 2; ++k) \
;         acc[ai][bj][m][n] = __builtin_amdgcn_mfma_f32_16x16x32_bf16(Bt[n][k], At[m][k], acc[ai][bj][m][n], 0, 0, 0); __builtin_amdgcn_s_setprio(0); } while (0)
; #define PG8_WAIT_V(n) asm volatile("s_waitcnt vmcnt(" #n ")" ::: "memory")
; #define PG8_WAIT_L(n) asm volatile("s_waitcnt lgkmcnt(" #n ")" ::: "memory")
; #define PG8_BAR __builtin_amdgcn_s_barrier()
; #define PG8_SCHED __builtin_amdgcn_sched_barrier(0)
; template <class Epi, class Sched, bool ALIGN_EPI>
; __device__ __forceinline__ void gemm_phase(LAS unsigned char* lds, const Gemm g, const Sched& S, const Epi& E, int wave_id) {
;     ...
;             const bool last = (t == nt - 2);
;             const GAS char* a1 = cA + (size_t)(t + 1) * kstep;
;             const GAS char* a2 = last ? nA : cA + (size_t)(t + 2) * kstep; const GAS char* b2 = last ? nB : cB + (size_t)(t + 2) * kstep;
;             const GAS char* a3 = a2 + kstep; const GAS char* b3 = b2 + kstep;
;             PG8_LDB(B0, 0, 0); PG8_LDB(B1, 0, 1); PG8_SCHED; PG8_LDA(At, 0, 0); PG8_STAGE(PG8_SA(1, 1), a1 + hsA, voffA);
;             PG8_WAIT_V(8); PG8_WAIT_L(0); PG8_BAR; PG8_MMA(0, 0, At, B0); PG8_MMA(0, 1, At, B1); PG8_BAR; PG8_SCHED;
;             PG8_LDA(At, 0, 1); PG8_STAGE(PG8_SB(0, 0), b2, voffB); PG8_STAGE(PG8_SB(0, 1), b2 + hsB, voffB); PG8_STAGE(PG8_SA(0, 0), a2, voffA);
.LBB0_2565:
	s_add_u32 s28, s26, 0xfffc0080
	s_addc_u32 s29, s27, -1
	s_cmp_eq_u32 s60, 12
	s_cselect_b32 s31, s19, s29
	s_cselect_b32 s30, s33, s28
	s_cselect_b32 s29, s17, s59
	s_cselect_b32 s28, s57, s58
	v_lshl_add_u64 v[206:207], s[26:27], 0, v[138:139]
	s_add_i32 m0, s40, 0xc400
	s_nop 0
	global_load_lds_dwordx4 v[206:207], off
	v_lshl_add_u64 v[206:207], s[26:27], 0, v[136:137]
	s_add_i32 m0, s40, 0xe400
	s_nop 0
	global_load_lds_dwordx4 v[206:207], off
	v_add_u32_e32 v154, 0x10400, v153
	v_add_u32_e32 v170, 0x14400, v153
	ds_read_b128 v[140:143], v154
	ds_read_b128 v[144:147], v154 offset:1024
	ds_read_b128 v[148:151], v154 offset:2048
	ds_read_b128 v[154:157], v154 offset:3072
	ds_read_b128 v[158:161], v170
	ds_read_b128 v[162:165], v170 offset:1024
	ds_read_b128 v[166:169], v170 offset:2048
	ds_read_b128 v[170:173], v170 offset:3072
	ds_read_b128 v[174:177], v152 offset:1024
	ds_read_b128 v[178:181], v152 offset:2048
	ds_read_b128 v[182:185], v152 offset:3072
	ds_read_b128 v[186:189], v152 offset:4096
	ds_read_b128 v[190:193], v152 offset:5120
	ds_read_b128 v[194:197], v152 offset:6144
	ds_read_b128 v[198:201], v152 offset:7168
	ds_read_b128 v[202:205], v152 offset:8192
	s_waitcnt vmcnt(8)
	s_waitcnt lgkmcnt(0)
	s_setprio 1
	s_barrier
	v_mfma_f32_16x16x32_bf16 v[126:129], v[140:143], v[174:177], v[126:129]
	v_mfma_f32_16x16x32_bf16 v[122:125], v[148:151], v[174:177], v[122:125]
	v_mfma_f32_16x16x32_bf16 v[110:113], v[140:143], v[182:185], v[110:113]
	v_mfma_f32_16x16x32_bf16 v[106:109], v[148:151], v[182:185], v[106:109]
	v_mfma_f32_16x16x32_bf16 v[94:97], v[140:143], v[190:193], v[94:97]
	v_mfma_f32_16x16x32_bf16 v[90:93], v[148:151], v[190:193], v[90:93]
	v_mfma_f32_16x16x32_bf16 v[78:81], v[140:143], v[198:201], v[78:81]
	v_mfma_f32_16x16x32_bf16 v[74:77], v[148:151], v[198:201], v[74:77]
	v_mfma_f32_16x16x32_bf16 v[126:129], v[144:147], v[178:181], v[126:129]
	v_mfma_f32_16x16x32_bf16 v[122:125], v[154:157], v[178:181], v[122:125]
	v_mfma_f32_16x16x32_bf16 v[110:113], v[144:147], v[186:189], v[110:113]
	v_mfma_f32_16x16x32_bf16 v[106:109], v[154:157], v[186:189], v[106:109]
	v_mfma_f32_16x16x32_bf16 v[94:97], v[144:147], v[194:197], v[94:97]
	v_mfma_f32_16x16x32_bf16 v[90:93], v[154:157], v[194:197], v[90:93]
	v_mfma_f32_16x16x32_bf16 v[78:81], v[144:147], v[202:205], v[78:81]
	v_mfma_f32_16x16x32_bf16 v[74:77], v[154:157], v[202:205], v[74:77]
	s_setprio 0
	s_setprio 1
	v_mfma_f32_16x16x32_bf16 v[118:121], v[158:161], v[174:177], v[118:121]
	v_mfma_f32_16x16x32_bf16 v[114:117], v[166:169], v[174:177], v[114:117]
	v_mfma_f32_16x16x32_bf16 v[102:105], v[158:161], v[182:185], v[102:105]
	v_mfma_f32_16x16x32_bf16 v[98:101], v[166:169], v[182:185], v[98:101]
	v_mfma_f32_16x16x32_bf16 v[86:89], v[158:161], v[190:193], v[86:89]
	v_mfma_f32_16x16x32_bf16 v[82:85], v[166:169], v[190:193], v[82:85]
	v_mfma_f32_16x16x32_bf16 v[70:73], v[158:161], v[198:201], v[70:73]
	v_mfma_f32_16x16x32_bf16 v[66:69], v[166:169], v[198:201], v[66:69]
	v_mfma_f32_16x16x32_bf16 v[118:121], v[162:165], v[178:181], v[118:121]
	v_mfma_f32_16x16x32_bf16 v[114:117], v[170:173], v[178:181], v[114:117]
	v_mfma_f32_16x16x32_bf16 v[102:105], v[162:165], v[186:189], v[102:105]
	v_mfma_f32_16x16x32_bf16 v[98:101], v[170:173], v[186:189], v[98:101]
	v_mfma_f32_16x16x32_bf16 v[86:89], v[162:165], v[194:197], v[86:89]
	v_mfma_f32_16x16x32_bf16 v[82:85], v[170:173], v[194:197], v[82:85]
	v_mfma_f32_16x16x32_bf16 v[70:73], v[162:165], v[202:205], v[70:73]
	v_mfma_f32_16x16x32_bf16 v[66:69], v[170:173], v[202:205], v[66:69]
	s_barrier
	s_setprio 0
	s_mov_b32 m0, s25
	v_lshl_add_u64 v[206:207], s[28:29], 0, v[0:1]
	s_add_u32 s62, s28, 0x40000
	global_load_lds_dwordx4 v[206:207], off
	v_lshl_add_u64 v[208:209], s[28:29], 0, v[130:131]
	s_mov_b32 m0, s41
	s_addc_u32 s63, s29, 0
	global_load_lds_dwordx4 v[208:209], off
	v_lshl_add_u64 v[210:211], s[62:63], 0, v[0:1]
	s_mov_b32 m0, s42
	v_lshl_add_u64 v[212:213], s[30:31], 0, v[132:133]
	global_load_lds_dwordx4 v[210:211], off
	v_lshl_add_u64 v[210:211], s[62:63], 0, v[130:131]
	s_mov_b32 m0, s43
	s_nop 0
	global_load_lds_dwordx4 v[210:211], off
	v_lshl_add_u64 v[210:211], s[30:31], 0, v[134:135]
	s_mov_b32 m0, s44
	s_nop 0
	global_load_lds_dwordx4 v[210:211], off
	s_mov_b32 m0, s45
	s_nop 0
	global_load_lds_dwordx4 v[212:213], off
	ds_read_b128 v[174:177], v152 offset:17408
	ds_read_b128 v[178:181], v152 offset:18432
	ds_read_b128 v[182:185], v152 offset:19456
	ds_read_b128 v[186:189], v152 offset:20480
	ds_read_b128 v[190:193], v152 offset:21504
	ds_read_b128 v[194:197], v152 offset:22528
	ds_read_b128 v[198:201], v152 offset:23552
	ds_read_b128 v[202:205], v152 offset:24576
	s_waitcnt vmcnt(8)
	s_waitcnt lgkmcnt(0)
	s_setprio 1
	s_barrier
; #define PG8_STAGE(bufoff, gbase, voff) do { _Pragma("unroll") for (int _i = 0; _i < 2; ++_i) \
;         __builtin_amdgcn_global_load_lds((const GAS unsigned*)((const GAS char*)(gbase) + (voff)[_i]), (LAS unsigned*)(lds + (bufoff) + ldsw + _i * 8192), 16, 0, 0); } while (0)
; #define PG8_LDA(dst, b, h) do { _Pragma("unroll") for (int m = 0; m < 4; ++m) _Pragma("unroll") for (int k = 0; k < 2; ++k) dst[m][k] = *(const LAS bf16x8*)(lds + PG8_SA(b, h) + aoff + m * 2048 + k * 1024); } while (0)
; #define PG8_LDB(dst, b, h) do { _Pragma("unroll") for (int n = 0; n < 2; ++n) _Pragma("unroll") for (int k = 0; k < 2; ++k) dst[n][k] = *(const LAS bf16x8*)(lds + PG8_SB(b, h) + boff + n * 2048 + k * 1024); } while (0)
; #define PG8_MMA(ai, bj, At, Bt) do { __builtin_amdgcn_s_setprio(1); _Pragma("unroll") for (int m = 0; m < 4; ++m) _Pragma("unroll") for (int n = 0; n < 2; ++n) _Pragma("unroll") for (int k = 0; k < 2; ++k) \
;         acc[ai][bj][m][n] = __builtin_amdgcn_mfma_f32_16x16x32_bf16(Bt[n][k], At[m][k], acc[ai][bj][m][n], 0, 0, 0); __builtin_amdgcn_s_setprio(0); } while (0)
; #define PG8_WAIT_V(n) asm volatile("s_waitcnt vmcnt(" #n ")" ::: "memory")
; #define PG8_WAIT_L(n) asm volatile("s_waitcnt lgkmcnt(" #n ")" ::: "memory")
; #define PG8_BAR __builtin_amdgcn_s_barrier()
; #define PG8_SCHED __builtin_amdgcn_sched_barrier(0)
; template <class Epi, class Sched, bool ALIGN_EPI>
; __device__ __forceinline__ void gemm_phase(LAS unsigned char* lds, const Gemm g, const Sched& S, const Epi& E, int wave_id) {
;     ...
;             PG8_WAIT_V(8); PG8_WAIT_L(0); PG8_BAR; PG8_MMA(1, 0, At, B0); PG8_MMA(1, 1, At, B1); PG8_BAR; PG8_SCHED;
;             PG8_LDB(B0, 1, 0); PG8_LDB(B1, 1, 1); PG8_SCHED; PG8_LDA(At, 1, 0); PG8_STAGE(PG8_SA(0, 1), a2 + hsA, voffA);
;             PG8_WAIT_V(8); PG8_WAIT_L(0); PG8_BAR; PG8_MMA(0, 0, At, B0); PG8_MMA(0, 1, At, B1); PG8_BAR; PG8_SCHED;
	v_mfma_f32_16x16x32_bf16 v[62:65], v[140:143], v[174:177], v[62:65]
	v_mfma_f32_16x16x32_bf16 v[58:61], v[148:151], v[174:177], v[58:61]
	v_mfma_f32_16x16x32_bf16 v[46:49], v[140:143], v[182:185], v[46:49]
	v_mfma_f32_16x16x32_bf16 v[42:45], v[148:151], v[182:185], v[42:45]
	v_mfma_f32_16x16x32_bf16 v[30:33], v[140:143], v[190:193], v[30:33]
	v_mfma_f32_16x16x32_bf16 v[26:29], v[148:151], v[190:193], v[26:29]
	v_mfma_f32_16x16x32_bf16 v[14:17], v[140:143], v[198:201], v[14:17]
	v_mfma_f32_16x16x32_bf16 v[10:13], v[148:151], v[198:201], v[10:13]
	v_mfma_f32_16x16x32_bf16 v[62:65], v[144:147], v[178:181], v[62:65]
	v_mfma_f32_16x16x32_bf16 v[58:61], v[154:157], v[178:181], v[58:61]
	v_mfma_f32_16x16x32_bf16 v[46:49], v[144:147], v[186:189], v[46:49]
	v_mfma_f32_16x16x32_bf16 v[42:45], v[154:157], v[186:189], v[42:45]
	v_mfma_f32_16x16x32_bf16 v[30:33], v[144:147], v[194:197], v[30:33]
	v_mfma_f32_16x16x32_bf16 v[26:29], v[154:157], v[194:197], v[26:29]
	v_mfma_f32_16x16x32_bf16 v[14:17], v[144:147], v[202:205], v[14:17]
	v_mfma_f32_16x16x32_bf16 v[10:13], v[154:157], v[202:205], v[10:13]
	s_setprio 0
	s_setprio 1
	v_mfma_f32_16x16x32_bf16 v[54:57], v[158:161], v[174:177], v[54:57]
	v_mfma_f32_16x16x32_bf16 v[50:53], v[166:169], v[174:177], v[50:53]
	v_mfma_f32_16x16x32_bf16 v[38:41], v[158:161], v[182:185], v[38:41]
	v_mfma_f32_16x16x32_bf16 v[34:37], v[166:169], v[182:185], v[34:37]
	v_mfma_f32_16x16x32_bf16 v[22:25], v[158:161], v[190:193], v[22:25]
	v_mfma_f32_16x16x32_bf16 v[18:21], v[166:169], v[190:193], v[18:21]
	v_mfma_f32_16x16x32_bf16 v[6:9], v[158:161], v[198:201], v[6:9]
	v_mfma_f32_16x16x32_bf16 v[2:5], v[166:169], v[198:201], v[2:5]
	v_mfma_f32_16x16x32_bf16 v[54:57], v[162:165], v[178:181], v[54:57]
	v_mfma_f32_16x16x32_bf16 v[50:53], v[170:173], v[178:181], v[50:53]
	v_mfma_f32_16x16x32_bf16 v[38:41], v[162:165], v[186:189], v[38:41]
	v_mfma_f32_16x16x32_bf16 v[34:37], v[170:173], v[186:189], v[34:37]
	v_mfma_f32_16x16x32_bf16 v[22:25], v[162:165], v[194:197], v[22:25]
	v_mfma_f32_16x16x32_bf16 v[18:21], v[170:173], v[194:197], v[18:21]
	v_mfma_f32_16x16x32_bf16 v[6:9], v[162:165], v[202:205], v[6:9]
	v_mfma_f32_16x16x32_bf16 v[2:5], v[170:173], v[202:205], v[2:5]
	s_barrier
	s_setprio 0
	s_add_u32 s30, s30, 0x40000
	s_addc_u32 s31, s31, 0
	s_mov_b32 m0, s46
	v_lshl_add_u64 v[214:215], s[30:31], 0, v[134:135]
	global_load_lds_dwordx4 v[214:215], off
	v_lshl_add_u64 v[214:215], s[30:31], 0, v[132:133]
	s_mov_b32 m0, s47
	s_nop 0
	global_load_lds_dwordx4 v[214:215], off
	v_add_u32_e32 v154, 0x18400, v153
	v_add_u32_e32 v170, 0x1c400, v153
	ds_read_b128 v[140:143], v154
	ds_read_b128 v[144:147], v154 offset:1024
	ds_read_b128 v[148:151], v154 offset:2048
	ds_read_b128 v[154:157], v154 offset:3072
	ds_read_b128 v[158:161], v170
	ds_read_b128 v[162:165], v170 offset:1024
	ds_read_b128 v[166:169], v170 offset:2048
	ds_read_b128 v[170:173], v170 offset:3072
	ds_read_b128 v[174:177], v152 offset:33792
	ds_read_b128 v[178:181], v152 offset:34816
	ds_read_b128 v[182:185], v152 offset:35840
	ds_read_b128 v[186:189], v152 offset:36864
	ds_read_b128 v[190:193], v152 offset:37888
	ds_read_b128 v[194:197], v152 offset:38912
	ds_read_b128 v[198:201], v152 offset:39936
	ds_read_b128 v[202:205], v152 offset:40960
	s_waitcnt vmcnt(8)
	s_waitcnt lgkmcnt(0)
	s_setprio 1
	s_barrier
	v_mfma_f32_16x16x32_bf16 v[126:129], v[140:143], v[174:177], v[126:129]
	v_mfma_f32_16x16x32_bf16 v[122:125], v[148:151], v[174:177], v[122:125]
	v_mfma_f32_16x16x32_bf16 v[110:113], v[140:143], v[182:185], v[110:113]
	v_mfma_f32_16x16x32_bf16 v[106:109], v[148:151], v[182:185], v[106:109]
	v_mfma_f32_16x16x32_bf16 v[94:97], v[140:143], v[190:193], v[94:97]
	v_mfma_f32_16x16x32_bf16 v[90:93], v[148:151], v[190:193], v[90:93]
	v_mfma_f32_16x16x32_bf16 v[78:81], v[140:143], v[198:201], v[78:81]
	v_mfma_f32_16x16x32_bf16 v[74:77], v[148:151], v[198:201], v[74:77]
	v_mfma_f32_16x16x32_bf16 v[126:129], v[144:147], v[178:181], v[126:129]
	v_mfma_f32_16x16x32_bf16 v[122:125], v[154:157], v[178:181], v[122:125]
	v_mfma_f32_16x16x32_bf16 v[110:113], v[144:147], v[186:189], v[110:113]
	v_mfma_f32_16x16x32_bf16 v[106:109], v[154:157], v[186:189], v[106:109]
	v_mfma_f32_16x16x32_bf16 v[94:97], v[144:147], v[194:197], v[94:97]
	v_mfma_f32_16x16x32_bf16 v[90:93], v[154:157], v[194:197], v[90:93]
	v_mfma_f32_16x16x32_bf16 v[78:81], v[144:147], v[202:205], v[78:81]
	v_mfma_f32_16x16x32_bf16 v[74:77], v[154:157], v[202:205], v[74:77]
	s_setprio 0
	s_setprio 1
	v_mfma_f32_16x16x32_bf16 v[118:121], v[158:161], v[174:177], v[118:121]
	v_mfma_f32_16x16x32_bf16 v[114:117], v[166:169], v[174:177], v[114:117]
	v_mfma_f32_16x16x32_bf16 v[102:105], v[158:161], v[182:185], v[102:105]
	v_mfma_f32_16x16x32_bf16 v[98:101], v[166:169], v[182:185], v[98:101]
	v_mfma_f32_16x16x32_bf16 v[86:89], v[158:161], v[190:193], v[86:89]
	v_mfma_f32_16x16x32_bf16 v[82:85], v[166:169], v[190:193], v[82:85]
	v_mfma_f32_16x16x32_bf16 v[70:73], v[158:161], v[198:201], v[70:73]
	v_mfma_f32_16x16x32_bf16 v[66:69], v[166:169], v[198:201], v[66:69]
	v_mfma_f32_16x16x32_bf16 v[118:121], v[162:165], v[178:181], v[118:121]
	v_mfma_f32_16x16x32_bf16 v[114:117], v[170:173], v[178:181], v[114:117]
	v_mfma_f32_16x16x32_bf16 v[102:105], v[162:165], v[186:189], v[102:105]
	v_mfma_f32_16x16x32_bf16 v[98:101], v[170:173], v[186:189], v[98:101]
	v_mfma_f32_16x16x32_bf16 v[86:89], v[162:165], v[194:197], v[86:89]
	v_mfma_f32_16x16x32_bf16 v[82:85], v[170:173], v[194:197], v[82:85]
	v_mfma_f32_16x16x32_bf16 v[70:73], v[162:165], v[202:205], v[70:73]
	v_mfma_f32_16x16x32_bf16 v[66:69], v[170:173], v[202:205], v[66:69]
	s_barrier
; #define PG8_STAGE(bufoff, gbase, voff) do { _Pragma("unroll") for (int _i = 0; _i < 2; ++_i) \
;         __builtin_amdgcn_global_load_lds((const GAS unsigned*)((const GAS char*)(gbase) + (voff)[_i]), (LAS unsigned*)(lds + (bufoff) + ldsw + _i * 8192), 16, 0, 0); } while (0)
; #define PG8_LDA(dst, b, h) do { _Pragma("unroll") for (int m = 0; m < 4; ++m) _Pragma("unroll") for (int k = 0; k < 2; ++k) dst[m][k] = *(const LAS bf16x8*)(lds + PG8_SA(b, h) + aoff + m * 2048 + k * 1024); } while (0)
; #define PG8_MMA(ai, bj, At, Bt) do { __builtin_amdgcn_s_setprio(1); _Pragma("unroll") for (int m = 0; m < 4; ++m) _Pragma("unroll") for (int n = 0; n < 2; ++n) _Pragma("unroll") for (int k = 0; k < 2; ++k) \
;         acc[ai][bj][m][n] = __builtin_amdgcn_mfma_f32_16x16x32_bf16(Bt[n][k], At[m][k], acc[ai][bj][m][n], 0, 0, 0); __builtin_amdgcn_s_setprio(0); } while (0)
; #define PG8_WAIT_V(n) asm volatile("s_waitcnt vmcnt(" #n ")" ::: "memory")
; #define PG8_WAIT_L(n) asm volatile("s_waitcnt lgkmcnt(" #n ")" ::: "memory")
; #define PG8_BAR __builtin_amdgcn_s_barrier()
; #define PG8_SCHED __builtin_amdgcn_sched_barrier(0)
; template <class Epi, class Sched, bool ALIGN_EPI>
; __device__ __forceinline__ void gemm_phase(LAS unsigned char* lds, const Gemm g, const Sched& S, const Epi& E, int wave_id) {
;     ...
;             PG8_LDA(At, 1, 1); PG8_STAGE(PG8_SB(1, 0), b3, voffB); PG8_STAGE(PG8_SB(1, 1), b3 + hsB, voffB); PG8_STAGE(PG8_SA(1, 0), a3, voffA);
;             PG8_WAIT_V(8); PG8_WAIT_L(0); PG8_BAR; PG8_MMA(1, 0, At, B0); PG8_MMA(1, 1, At, B1); PG8_BAR; PG8_SCHED;
;         }
;         if constexpr (ALIGN_EPI) { if (wr == 0) PG8_BAR; }
	s_setprio 0
	s_mov_b32 m0, s50
	v_lshl_add_u64 v[206:207], v[206:207], 0, s[92:93]
	s_add_u32 s28, s28, 0x40080
	global_load_lds_dwordx4 v[206:207], off
	v_lshl_add_u64 v[206:207], v[208:209], 0, s[92:93]
	s_mov_b32 m0, s51
	s_addc_u32 s29, s29, 0
	global_load_lds_dwordx4 v[206:207], off
	v_lshl_add_u64 v[206:207], s[28:29], 0, v[0:1]
	s_mov_b32 m0, s54
	s_nop 0
	global_load_lds_dwordx4 v[206:207], off
	v_lshl_add_u64 v[206:207], s[28:29], 0, v[130:131]
	s_mov_b32 m0, s55
	s_nop 0
	global_load_lds_dwordx4 v[206:207], off
	v_lshl_add_u64 v[206:207], v[210:211], 0, s[92:93]
	s_mov_b32 m0, s52
	s_nop 0
	global_load_lds_dwordx4 v[206:207], off
	v_lshl_add_u64 v[206:207], v[212:213], 0, s[92:93]
	s_mov_b32 m0, s53
	s_nop 0
	global_load_lds_dwordx4 v[206:207], off
	ds_read_b128 v[174:177], v152 offset:50176
	ds_read_b128 v[178:181], v152 offset:51200
	ds_read_b128 v[182:185], v152 offset:52224
	ds_read_b128 v[186:189], v152 offset:53248
	ds_read_b128 v[190:193], v152 offset:54272
	ds_read_b128 v[194:197], v152 offset:55296
	ds_read_b128 v[198:201], v152 offset:56320
	ds_read_b128 v[202:205], v152 offset:57344
	s_waitcnt vmcnt(8)
	s_waitcnt lgkmcnt(0)
	s_setprio 1
	s_barrier
	v_mfma_f32_16x16x32_bf16 v[62:65], v[140:143], v[174:177], v[62:65]
	v_mfma_f32_16x16x32_bf16 v[58:61], v[148:151], v[174:177], v[58:61]
	v_mfma_f32_16x16x32_bf16 v[46:49], v[140:143], v[182:185], v[46:49]
	v_mfma_f32_16x16x32_bf16 v[42:45], v[148:151], v[182:185], v[42:45]
	v_mfma_f32_16x16x32_bf16 v[30:33], v[140:143], v[190:193], v[30:33]
	v_mfma_f32_16x16x32_bf16 v[26:29], v[148:151], v[190:193], v[26:29]
	v_mfma_f32_16x16x32_bf16 v[14:17], v[140:143], v[198:201], v[14:17]
	v_mfma_f32_16x16x32_bf16 v[10:13], v[148:151], v[198:201], v[10:13]
	v_mfma_f32_16x16x32_bf16 v[62:65], v[144:147], v[178:181], v[62:65]
	v_mfma_f32_16x16x32_bf16 v[58:61], v[154:157], v[178:181], v[58:61]
	v_mfma_f32_16x16x32_bf16 v[46:49], v[144:147], v[186:189], v[46:49]
	v_mfma_f32_16x16x32_bf16 v[42:45], v[154:157], v[186:189], v[42:45]
	v_mfma_f32_16x16x32_bf16 v[30:33], v[144:147], v[194:197], v[30:33]
	v_mfma_f32_16x16x32_bf16 v[26:29], v[154:157], v[194:197], v[26:29]
	v_mfma_f32_16x16x32_bf16 v[14:17], v[144:147], v[202:205], v[14:17]
	v_mfma_f32_16x16x32_bf16 v[10:13], v[154:157], v[202:205], v[10:13]
	s_setprio 0
	s_setprio 1
	v_mfma_f32_16x16x32_bf16 v[54:57], v[158:161], v[174:177], v[54:57]
	v_mfma_f32_16x16x32_bf16 v[50:53], v[166:169], v[174:177], v[50:53]
	v_mfma_f32_16x16x32_bf16 v[38:41], v[158:161], v[182:185], v[38:41]
	v_mfma_f32_16x16x32_bf16 v[34:37], v[166:169], v[182:185], v[34:37]
	v_mfma_f32_16x16x32_bf16 v[22:25], v[158:161], v[190:193], v[22:25]
	v_mfma_f32_16x16x32_bf16 v[18:21], v[166:169], v[190:193], v[18:21]
	v_mfma_f32_16x16x32_bf16 v[6:9], v[158:161], v[198:201], v[6:9]
	v_mfma_f32_16x16x32_bf16 v[2:5], v[166:169], v[198:201], v[2:5]
	v_mfma_f32_16x16x32_bf16 v[54:57], v[162:165], v[178:181], v[54:57]
	v_mfma_f32_16x16x32_bf16 v[50:53], v[170:173], v[178:181], v[50:53]
	v_mfma_f32_16x16x32_bf16 v[38:41], v[162:165], v[186:189], v[38:41]
	v_mfma_f32_16x16x32_bf16 v[34:37], v[170:173], v[186:189], v[34:37]
	v_mfma_f32_16x16x32_bf16 v[22:25], v[162:165], v[194:197], v[22:25]
	v_mfma_f32_16x16x32_bf16 v[18:21], v[170:173], v[194:197], v[18:21]
	v_mfma_f32_16x16x32_bf16 v[6:9], v[162:165], v[202:205], v[6:9]
	v_mfma_f32_16x16x32_bf16 v[2:5], v[170:173], v[202:205], v[2:5]
	s_barrier
	s_setprio 0
	s_add_i32 s60, s60, 2
	s_add_u32 s58, s58, 0x100
	s_addc_u32 s59, s59, 0
	s_add_u32 s26, s26, 0x100
	s_addc_u32 s27, s27, 0
	s_cmp_gt_u32 s60, 13
	s_cbranch_scc0 .LBB0_2565
	s_and_b64 vcc, exec, s[14:15]
	s_cbranch_vccz .LBB0_2568
	s_barrier

; #define GAS __attribute__((address_space(1)))
; #define PG8_STAGE(bufoff, gbase, voff) do { _Pragma("unroll") for (int _i = 0; _i < 2; ++_i) \
;         __builtin_amdgcn_global_load_lds((const GAS unsigned*)((const GAS char*)(gbase) + (voff)[_i]), (LAS unsigned*)(lds + (bufoff) + ldsw + _i * 8192), 16, 0, 0); } while (0)
; #define PG8_LDA(dst, b, h) do { _Pragma("unroll") for (int m = 0; m < 4; ++m) _Pragma("unroll") for (int k = 0; k < 2; ++k) dst[m][k] = *(const LAS bf16x8*)(lds + PG8_SA(b, h) + aoff + m * 2048 + k * 1024); } while (0)
; #define PG8_LDB(dst, b, h) do { _Pragma("unroll") for (int n = 0; n < 2; ++n) _Pragma("unroll") for (int k = 0; k < 2; ++k) dst[n][k] = *(const LAS bf16x8*)(lds + PG8_SB(b, h) + boff + n * 2048 + k * 1024); } while (0)
; #define PG8_MMA(ai, bj, At, Bt) do { __builtin_amdgcn_s_setprio(1); _Pragma("unroll") for (int m = 0; m < 4; ++m) _Pragma("unroll") for (int n = 0; n < 2; ++n) _Pragma("unroll") for (int k = 0; k < 2; ++k) \
;         acc[ai][bj][m][n] = __builtin_amdgcn_mfma_f32_16x16x32_bf16(Bt[n][k], At[m][k], acc[ai][bj][m][n], 0, 0, 0); __builtin_amdgcn_s_setprio(0); } while (0)
; #define PG8_WAIT_V(n) asm volatile("s_waitcnt vmcnt(" #n ")" ::: "memory")
; #define PG8_WAIT_L(n) asm volatile("s_waitcnt lgkmcnt(" #n ")" ::: "memory")
; #define PG8_BAR __builtin_amdgcn_s_barrier()
; #define PG8_SCHED __builtin_amdgcn_sched_barrier(0)
; template <class Epi, class Sched, bool ALIGN_EPI>
; __device__ __forceinline__ void gemm_phase(LAS unsigned char* lds, const Gemm g, const Sched& S, const Epi& E, int wave_id) {
;     ...
;             const bool last = (t == nt - 2);
;             const GAS char* a1 = cA + (size_t)(t + 1) * kstep;
;             const GAS char* a2 = last ? nA : cA + (size_t)(t + 2) * kstep; const GAS char* b2 = last ? nB : cB + (size_t)(t + 2) * kstep;
;             const GAS char* a3 = a2 + kstep; const GAS char* b3 = b2 + kstep;
;             PG8_LDB(B0, 0, 0); PG8_LDB(B1, 0, 1); PG8_SCHED; PG8_LDA(At, 0, 0); PG8_STAGE(PG8_SA(1, 1), a1 + hsA, voffA);
;             PG8_WAIT_V(8); PG8_WAIT_L(0); PG8_BAR; PG8_MMA(0, 0, At, B0); PG8_MMA(0, 1, At, B1); PG8_BAR; PG8_SCHED;
;             PG8_LDA(At, 0, 1); PG8_STAGE(PG8_SB(0, 0), b2, voffB); PG8_STAGE(PG8_SB(0, 1), b2 + hsB, voffB); PG8_STAGE(PG8_SA(0, 0), a2, voffA);
.LBB0_2620:
	s_add_u32 s38, s36, 0xfff80080
	s_addc_u32 s39, s37, -1
	s_cmp_eq_u32 s65, 28
	s_cselect_b32 s41, s1, s39
	s_cselect_b32 s40, s5, s38
	s_cselect_b32 s39, s7, s33
	s_cselect_b32 s38, s27, s29
	v_lshl_add_u64 v[194:195], s[36:37], 0, v[218:219]
	s_add_i32 m0, s43, 0xc400
	s_nop 0
	global_load_lds_dwordx4 v[194:195], off
	v_lshl_add_u64 v[194:195], s[36:37], 0, v[216:217]
	s_add_i32 m0, s43, 0xe400
	s_nop 0
	global_load_lds_dwordx4 v[194:195], off
	v_add_u32_e32 v46, 0x10400, v235
	v_add_u32_e32 v62, 0x14400, v235
	ds_read_b128 v[34:37], v46
	ds_read_b128 v[38:41], v46 offset:1024
	ds_read_b128 v[42:45], v46 offset:2048
	ds_read_b128 v[46:49], v46 offset:3072
	ds_read_b128 v[50:53], v62
	ds_read_b128 v[54:57], v62 offset:1024
	ds_read_b128 v[58:61], v62 offset:2048
	ds_read_b128 v[62:65], v62 offset:3072
	ds_read_b128 v[82:85], v234 offset:1024
	ds_read_b128 v[94:97], v234 offset:2048
	ds_read_b128 v[170:173], v234 offset:3072
	ds_read_b128 v[174:177], v234 offset:4096
	ds_read_b128 v[178:181], v234 offset:5120
	ds_read_b128 v[182:185], v234 offset:6144
	ds_read_b128 v[186:189], v234 offset:7168
	ds_read_b128 v[190:193], v234 offset:8192
	s_waitcnt vmcnt(8)
	s_waitcnt lgkmcnt(0)
	s_setprio 1
	s_barrier
	v_mfma_f32_16x16x32_bf16 v[166:169], v[34:37], v[82:85], v[166:169]
	v_mfma_f32_16x16x32_bf16 v[162:165], v[42:45], v[82:85], v[162:165]
	v_mfma_f32_16x16x32_bf16 v[150:153], v[34:37], v[170:173], v[150:153]
	v_mfma_f32_16x16x32_bf16 v[146:149], v[42:45], v[170:173], v[146:149]
	v_mfma_f32_16x16x32_bf16 v[134:137], v[34:37], v[178:181], v[134:137]
	v_mfma_f32_16x16x32_bf16 v[130:133], v[42:45], v[178:181], v[130:133]
	v_mfma_f32_16x16x32_bf16 v[118:121], v[34:37], v[186:189], v[118:121]
	v_mfma_f32_16x16x32_bf16 v[114:117], v[42:45], v[186:189], v[114:117]
	v_mfma_f32_16x16x32_bf16 v[166:169], v[38:41], v[94:97], v[166:169]
	v_mfma_f32_16x16x32_bf16 v[162:165], v[46:49], v[94:97], v[162:165]
	v_mfma_f32_16x16x32_bf16 v[150:153], v[38:41], v[174:177], v[150:153]
	v_mfma_f32_16x16x32_bf16 v[146:149], v[46:49], v[174:177], v[146:149]
	v_mfma_f32_16x16x32_bf16 v[134:137], v[38:41], v[182:185], v[134:137]
	v_mfma_f32_16x16x32_bf16 v[130:133], v[46:49], v[182:185], v[130:133]
	v_mfma_f32_16x16x32_bf16 v[118:121], v[38:41], v[190:193], v[118:121]
	v_mfma_f32_16x16x32_bf16 v[114:117], v[46:49], v[190:193], v[114:117]
	s_setprio 0
	s_setprio 1
	v_mfma_f32_16x16x32_bf16 v[158:161], v[50:53], v[82:85], v[158:161]
	v_mfma_f32_16x16x32_bf16 v[82:85], v[58:61], v[82:85], v[154:157]
	v_mfma_f32_16x16x32_bf16 v[138:141], v[58:61], v[170:173], v[138:141]
	v_mfma_f32_16x16x32_bf16 v[126:129], v[50:53], v[178:181], v[126:129]
	v_mfma_f32_16x16x32_bf16 v[122:125], v[58:61], v[178:181], v[122:125]
	v_mfma_f32_16x16x32_bf16 v[110:113], v[50:53], v[186:189], v[110:113]
	v_mfma_f32_16x16x32_bf16 v[106:109], v[58:61], v[186:189], v[106:109]
	v_mfma_f32_16x16x32_bf16 v[158:161], v[54:57], v[94:97], v[158:161]
	v_mfma_f32_16x16x32_bf16 v[82:85], v[62:65], v[94:97], v[82:85]
	v_mfma_f32_16x16x32_bf16 v[94:97], v[50:53], v[170:173], v[142:145]
	v_mfma_f32_16x16x32_bf16 v[138:141], v[62:65], v[174:177], v[138:141]
	v_mfma_f32_16x16x32_bf16 v[126:129], v[54:57], v[182:185], v[126:129]
	v_mfma_f32_16x16x32_bf16 v[122:125], v[62:65], v[182:185], v[122:125]
	v_mfma_f32_16x16x32_bf16 v[110:113], v[54:57], v[190:193], v[110:113]
	v_mfma_f32_16x16x32_bf16 v[106:109], v[62:65], v[190:193], v[106:109]
	v_mfma_f32_16x16x32_bf16 v[94:97], v[54:57], v[174:177], v[94:97]
	s_barrier
	s_setprio 0
	s_mov_b32 m0, s48
	v_lshl_add_u64 v[202:203], s[38:39], 0, v[0:1]
	s_add_u32 s66, s38, 0x80000
	global_load_lds_dwordx4 v[202:203], off
	v_lshl_add_u64 v[204:205], s[38:39], 0, v[210:211]
	s_mov_b32 m0, s49
	s_addc_u32 s67, s39, 0
	global_load_lds_dwordx4 v[204:205], off
	v_lshl_add_u64 v[194:195], s[66:67], 0, v[0:1]
	s_mov_b32 m0, s50
	v_lshl_add_u64 v[220:221], s[40:41], 0, v[206:207]
	global_load_lds_dwordx4 v[194:195], off
	v_lshl_add_u64 v[194:195], s[66:67], 0, v[210:211]
	s_mov_b32 m0, s51
	v_lshl_add_u64 v[224:225], s[40:41], 0, v[208:209]
	global_load_lds_dwordx4 v[194:195], off
	s_mov_b32 m0, s52
	s_nop 0
	global_load_lds_dwordx4 v[220:221], off
	s_mov_b32 m0, s53
	s_nop 0
	global_load_lds_dwordx4 v[224:225], off
	ds_read_b128 v[142:145], v234 offset:17408
	ds_read_b128 v[154:157], v234 offset:18432
	ds_read_b128 v[170:173], v234 offset:19456
	ds_read_b128 v[174:177], v234 offset:20480
	ds_read_b128 v[178:181], v234 offset:21504
	ds_read_b128 v[182:185], v234 offset:22528
	ds_read_b128 v[186:189], v234 offset:23552
	ds_read_b128 v[190:193], v234 offset:24576
	s_waitcnt vmcnt(8)
	s_waitcnt lgkmcnt(0)
	s_setprio 1
	s_barrier
; #define PG8_STAGE(bufoff, gbase, voff) do { _Pragma("unroll") for (int _i = 0; _i < 2; ++_i) \
;         __builtin_amdgcn_global_load_lds((const GAS unsigned*)((const GAS char*)(gbase) + (voff)[_i]), (LAS unsigned*)(lds + (bufoff) + ldsw + _i * 8192), 16, 0, 0); } while (0)
; #define PG8_LDA(dst, b, h) do { _Pragma("unroll") for (int m = 0; m < 4; ++m) _Pragma("unroll") for (int k = 0; k < 2; ++k) dst[m][k] = *(const LAS bf16x8*)(lds + PG8_SA(b, h) + aoff + m * 2048 + k * 1024); } while (0)
; #define PG8_LDB(dst, b, h) do { _Pragma("unroll") for (int n = 0; n < 2; ++n) _Pragma("unroll") for (int k = 0; k < 2; ++k) dst[n][k] = *(const LAS bf16x8*)(lds + PG8_SB(b, h) + boff + n * 2048 + k * 1024); } while (0)
; #define PG8_MMA(ai, bj, At, Bt) do { __builtin_amdgcn_s_setprio(1); _Pragma("unroll") for (int m = 0; m < 4; ++m) _Pragma("unroll") for (int n = 0; n < 2; ++n) _Pragma("unroll") for (int k = 0; k < 2; ++k) \
;         acc[ai][bj][m][n] = __builtin_amdgcn_mfma_f32_16x16x32_bf16(Bt[n][k], At[m][k], acc[ai][bj][m][n], 0, 0, 0); __builtin_amdgcn_s_setprio(0); } while (0)
; #define PG8_WAIT_V(n) asm volatile("s_waitcnt vmcnt(" #n ")" ::: "memory")
; #define PG8_WAIT_L(n) asm volatile("s_waitcnt lgkmcnt(" #n ")" ::: "memory")
; #define PG8_BAR __builtin_amdgcn_s_barrier()
; #define PG8_SCHED __builtin_amdgcn_sched_barrier(0)
; template <class Epi, class Sched, bool ALIGN_EPI>
; __device__ __forceinline__ void gemm_phase(LAS unsigned char* lds, const Gemm g, const Sched& S, const Epi& E, int wave_id) {
;     ...
;             PG8_WAIT_V(8); PG8_WAIT_L(0); PG8_BAR; PG8_MMA(1, 0, At, B0); PG8_MMA(1, 1, At, B1); PG8_BAR; PG8_SCHED;
;             PG8_LDB(B0, 1, 0); PG8_LDB(B1, 1, 1); PG8_SCHED; PG8_LDA(At, 1, 0); PG8_STAGE(PG8_SA(0, 1), a2 + hsA, voffA);
;             PG8_WAIT_V(8); PG8_WAIT_L(0); PG8_BAR; PG8_MMA(0, 0, At, B0); PG8_MMA(0, 1, At, B1); PG8_BAR; PG8_SCHED;
	v_mfma_f32_16x16x32_bf16 v[102:105], v[34:37], v[142:145], v[102:105]
	v_mfma_f32_16x16x32_bf16 v[98:101], v[42:45], v[142:145], v[98:101]
	v_mfma_f32_16x16x32_bf16 v[78:81], v[34:37], v[170:173], v[78:81]
	v_mfma_f32_16x16x32_bf16 v[74:77], v[42:45], v[170:173], v[74:77]
	v_mfma_f32_16x16x32_bf16 v[30:33], v[34:37], v[178:181], v[30:33]
	v_mfma_f32_16x16x32_bf16 v[26:29], v[42:45], v[178:181], v[26:29]
	v_mfma_f32_16x16x32_bf16 v[14:17], v[34:37], v[186:189], v[14:17]
	v_mfma_f32_16x16x32_bf16 v[10:13], v[42:45], v[186:189], v[10:13]
	v_mfma_f32_16x16x32_bf16 v[102:105], v[38:41], v[154:157], v[102:105]
	v_mfma_f32_16x16x32_bf16 v[98:101], v[46:49], v[154:157], v[98:101]
	v_mfma_f32_16x16x32_bf16 v[78:81], v[38:41], v[174:177], v[78:81]
	v_mfma_f32_16x16x32_bf16 v[74:77], v[46:49], v[174:177], v[74:77]
	v_mfma_f32_16x16x32_bf16 v[30:33], v[38:41], v[182:185], v[30:33]
	v_mfma_f32_16x16x32_bf16 v[26:29], v[46:49], v[182:185], v[26:29]
	v_mfma_f32_16x16x32_bf16 v[14:17], v[38:41], v[190:193], v[14:17]
	v_mfma_f32_16x16x32_bf16 v[10:13], v[46:49], v[190:193], v[10:13]
	s_setprio 0
	s_setprio 1
	v_mfma_f32_16x16x32_bf16 v[22:25], v[50:53], v[178:181], v[22:25]
	v_mfma_f32_16x16x32_bf16 v[18:21], v[58:61], v[178:181], v[18:21]
	v_mfma_f32_16x16x32_bf16 v[6:9], v[50:53], v[186:189], v[6:9]
	v_mfma_f32_16x16x32_bf16 v[2:5], v[58:61], v[186:189], v[2:5]
	v_mfma_f32_16x16x32_bf16 v[34:37], v[50:53], v[142:145], v[90:93]
	v_mfma_f32_16x16x32_bf16 v[38:41], v[58:61], v[142:145], v[86:89]
	v_mfma_f32_16x16x32_bf16 v[42:45], v[50:53], v[170:173], v[70:73]
	v_mfma_f32_16x16x32_bf16 v[46:49], v[58:61], v[170:173], v[66:69]
	v_mfma_f32_16x16x32_bf16 v[22:25], v[54:57], v[182:185], v[22:25]
	v_mfma_f32_16x16x32_bf16 v[18:21], v[62:65], v[182:185], v[18:21]
	v_mfma_f32_16x16x32_bf16 v[6:9], v[54:57], v[190:193], v[6:9]
	v_mfma_f32_16x16x32_bf16 v[2:5], v[62:65], v[190:193], v[2:5]
	v_mfma_f32_16x16x32_bf16 v[34:37], v[54:57], v[154:157], v[34:37]
	v_mfma_f32_16x16x32_bf16 v[38:41], v[62:65], v[154:157], v[38:41]
	v_mfma_f32_16x16x32_bf16 v[42:45], v[54:57], v[174:177], v[42:45]
	v_mfma_f32_16x16x32_bf16 v[46:49], v[62:65], v[174:177], v[46:49]
	s_barrier
	s_setprio 0
	s_add_u32 s40, s40, 0x80000
	s_addc_u32 s41, s41, 0
	s_mov_b32 m0, s54
	v_lshl_add_u64 v[142:143], s[40:41], 0, v[206:207]
	global_load_lds_dwordx4 v[142:143], off
	v_lshl_add_u64 v[142:143], s[40:41], 0, v[208:209]
	s_mov_b32 m0, s55
	s_nop 0
	global_load_lds_dwordx4 v[142:143], off
	v_add_u32_e32 v62, 0x18400, v235
	v_add_u32_e32 v66, 0x1c400, v235
	ds_read_b128 v[50:53], v62
	ds_read_b128 v[54:57], v62 offset:1024
	ds_read_b128 v[58:61], v62 offset:2048
	ds_read_b128 v[62:65], v62 offset:3072
	ds_read_b128 v[170:173], v66
	ds_read_b128 v[174:177], v66 offset:1024
	ds_read_b128 v[178:181], v66 offset:2048
	ds_read_b128 v[182:185], v66 offset:3072
	ds_read_b128 v[66:69], v234 offset:33792
	ds_read_b128 v[70:73], v234 offset:34816
	ds_read_b128 v[86:89], v234 offset:35840
	ds_read_b128 v[90:93], v234 offset:36864
	ds_read_b128 v[186:189], v234 offset:37888
	ds_read_b128 v[190:193], v234 offset:38912
	ds_read_b128 v[194:197], v234 offset:39936
	ds_read_b128 v[198:201], v234 offset:40960
	s_waitcnt vmcnt(8)
	s_waitcnt lgkmcnt(0)
	s_setprio 1
	s_barrier
	v_mfma_f32_16x16x32_bf16 v[142:145], v[50:53], v[66:69], v[166:169]
	v_mfma_f32_16x16x32_bf16 v[166:169], v[54:57], v[70:73], v[142:145]
	v_mfma_f32_16x16x32_bf16 v[142:145], v[58:61], v[66:69], v[162:165]
	v_mfma_f32_16x16x32_bf16 v[162:165], v[62:65], v[70:73], v[142:145]
	v_mfma_f32_16x16x32_bf16 v[142:145], v[50:53], v[86:89], v[150:153]
	v_mfma_f32_16x16x32_bf16 v[150:153], v[54:57], v[90:93], v[142:145]
	v_mfma_f32_16x16x32_bf16 v[142:145], v[58:61], v[86:89], v[146:149]
	v_mfma_f32_16x16x32_bf16 v[134:137], v[50:53], v[186:189], v[134:137]
	v_mfma_f32_16x16x32_bf16 v[130:133], v[58:61], v[186:189], v[130:133]
	v_mfma_f32_16x16x32_bf16 v[118:121], v[50:53], v[194:197], v[118:121]
	v_mfma_f32_16x16x32_bf16 v[114:117], v[58:61], v[194:197], v[114:117]
	v_mfma_f32_16x16x32_bf16 v[146:149], v[62:65], v[90:93], v[142:145]
	v_mfma_f32_16x16x32_bf16 v[134:137], v[54:57], v[190:193], v[134:137]
	v_mfma_f32_16x16x32_bf16 v[130:133], v[62:65], v[190:193], v[130:133]
	v_mfma_f32_16x16x32_bf16 v[118:121], v[54:57], v[198:201], v[118:121]
	v_mfma_f32_16x16x32_bf16 v[114:117], v[62:65], v[198:201], v[114:117]
	s_setprio 0
	s_setprio 1
	v_mfma_f32_16x16x32_bf16 v[142:145], v[170:173], v[66:69], v[158:161]
	v_mfma_f32_16x16x32_bf16 v[66:69], v[178:181], v[66:69], v[82:85]
	v_mfma_f32_16x16x32_bf16 v[154:157], v[182:185], v[70:73], v[66:69]
	v_mfma_f32_16x16x32_bf16 v[66:69], v[170:173], v[86:89], v[94:97]
	v_mfma_f32_16x16x32_bf16 v[158:161], v[174:177], v[70:73], v[142:145]
	v_mfma_f32_16x16x32_bf16 v[142:145], v[174:177], v[90:93], v[66:69]
	v_mfma_f32_16x16x32_bf16 v[66:69], v[178:181], v[86:89], v[138:141]
	v_mfma_f32_16x16x32_bf16 v[138:141], v[182:185], v[90:93], v[66:69]
	v_mfma_f32_16x16x32_bf16 v[66:69], v[170:173], v[186:189], v[126:129]
	v_mfma_f32_16x16x32_bf16 v[126:129], v[174:177], v[190:193], v[66:69]
	v_mfma_f32_16x16x32_bf16 v[66:69], v[178:181], v[186:189], v[122:125]
	v_mfma_f32_16x16x32_bf16 v[122:125], v[182:185], v[190:193], v[66:69]
	v_mfma_f32_16x16x32_bf16 v[66:69], v[170:173], v[194:197], v[110:113]
	v_mfma_f32_16x16x32_bf16 v[110:113], v[174:177], v[198:201], v[66:69]
	v_mfma_f32_16x16x32_bf16 v[66:69], v[178:181], v[194:197], v[106:109]
	v_mfma_f32_16x16x32_bf16 v[106:109], v[182:185], v[198:201], v[66:69]
	s_barrier
; #define PG8_STAGE(bufoff, gbase, voff) do { _Pragma("unroll") for (int _i = 0; _i < 2; ++_i) \
;         __builtin_amdgcn_global_load_lds((const GAS unsigned*)((const GAS char*)(gbase) + (voff)[_i]), (LAS unsigned*)(lds + (bufoff) + ldsw + _i * 8192), 16, 0, 0); } while (0)
; #define PG8_LDA(dst, b, h) do { _Pragma("unroll") for (int m = 0; m < 4; ++m) _Pragma("unroll") for (int k = 0; k < 2; ++k) dst[m][k] = *(const LAS bf16x8*)(lds + PG8_SA(b, h) + aoff + m * 2048 + k * 1024); } while (0)
; #define PG8_MMA(ai, bj, At, Bt) do { __builtin_amdgcn_s_setprio(1); _Pragma("unroll") for (int m = 0; m < 4; ++m) _Pragma("unroll") for (int n = 0; n < 2; ++n) _Pragma("unroll") for (int k = 0; k < 2; ++k) \
;         acc[ai][bj][m][n] = __builtin_amdgcn_mfma_f32_16x16x32_bf16(Bt[n][k], At[m][k], acc[ai][bj][m][n], 0, 0, 0); __builtin_amdgcn_s_setprio(0); } while (0)
; #define PG8_WAIT_V(n) asm volatile("s_waitcnt vmcnt(" #n ")" ::: "memory")
; #define PG8_WAIT_L(n) asm volatile("s_waitcnt lgkmcnt(" #n ")" ::: "memory")
; #define PG8_BAR __builtin_amdgcn_s_barrier()
; #define PG8_SCHED __builtin_amdgcn_sched_barrier(0)
; template <class Epi, class Sched, bool ALIGN_EPI>
; __device__ __forceinline__ void gemm_phase(LAS unsigned char* lds, const Gemm g, const Sched& S, const Epi& E, int wave_id) {
;     ...
;             PG8_LDA(At, 1, 1); PG8_STAGE(PG8_SB(1, 0), b3, voffB); PG8_STAGE(PG8_SB(1, 1), b3 + hsB, voffB); PG8_STAGE(PG8_SA(1, 0), a3, voffA);
;             PG8_WAIT_V(8); PG8_WAIT_L(0); PG8_BAR; PG8_MMA(1, 0, At, B0); PG8_MMA(1, 1, At, B1); PG8_BAR; PG8_SCHED;
;         }
;         if constexpr (ALIGN_EPI) { if (wr == 0) PG8_BAR; }
	s_setprio 0
	s_mov_b32 m0, s58
	v_lshl_add_u64 v[86:87], v[202:203], 0, s[92:93]
	s_add_u32 s38, s38, 0x80080
	s_nop 1
	global_load_lds_dwordx4 v[86:87], off
	v_lshl_add_u64 v[86:87], v[204:205], 0, s[92:93]
	s_mov_b32 m0, s59
	s_addc_u32 s39, s39, 0
	global_load_lds_dwordx4 v[86:87], off
	v_lshl_add_u64 v[86:87], s[38:39], 0, v[0:1]
	s_mov_b32 m0, s62
	s_nop 0
	global_load_lds_dwordx4 v[86:87], off
	v_lshl_add_u64 v[86:87], s[38:39], 0, v[210:211]
	s_mov_b32 m0, s63
	s_nop 0
	global_load_lds_dwordx4 v[86:87], off
	v_lshl_add_u64 v[86:87], v[220:221], 0, s[92:93]
	s_mov_b32 m0, s60
	s_nop 0
	global_load_lds_dwordx4 v[86:87], off
	v_lshl_add_u64 v[86:87], v[224:225], 0, s[92:93]
	s_mov_b32 m0, s61
	s_nop 0
	global_load_lds_dwordx4 v[86:87], off
	ds_read_b128 v[66:69], v234 offset:50176
	ds_read_b128 v[70:73], v234 offset:51200
	ds_read_b128 v[82:85], v234 offset:52224
	ds_read_b128 v[94:97], v234 offset:53248
	ds_read_b128 v[186:189], v234 offset:54272
	ds_read_b128 v[190:193], v234 offset:55296
	ds_read_b128 v[194:197], v234 offset:56320
	ds_read_b128 v[198:201], v234 offset:57344
	s_waitcnt vmcnt(8)
	s_waitcnt lgkmcnt(0)
	s_setprio 1
	s_barrier
	v_mfma_f32_16x16x32_bf16 v[86:89], v[50:53], v[66:69], v[102:105]
	v_mfma_f32_16x16x32_bf16 v[102:105], v[54:57], v[70:73], v[86:89]
	v_mfma_f32_16x16x32_bf16 v[86:89], v[58:61], v[66:69], v[98:101]
	v_mfma_f32_16x16x32_bf16 v[78:81], v[50:53], v[82:85], v[78:81]
	v_mfma_f32_16x16x32_bf16 v[74:77], v[58:61], v[82:85], v[74:77]
	v_mfma_f32_16x16x32_bf16 v[30:33], v[50:53], v[186:189], v[30:33]
	v_mfma_f32_16x16x32_bf16 v[26:29], v[58:61], v[186:189], v[26:29]
	v_mfma_f32_16x16x32_bf16 v[14:17], v[50:53], v[194:197], v[14:17]
	v_mfma_f32_16x16x32_bf16 v[10:13], v[58:61], v[194:197], v[10:13]
	v_mfma_f32_16x16x32_bf16 v[98:101], v[62:65], v[70:73], v[86:89]
	v_mfma_f32_16x16x32_bf16 v[78:81], v[54:57], v[94:97], v[78:81]
	v_mfma_f32_16x16x32_bf16 v[74:77], v[62:65], v[94:97], v[74:77]
	v_mfma_f32_16x16x32_bf16 v[30:33], v[54:57], v[190:193], v[30:33]
	v_mfma_f32_16x16x32_bf16 v[26:29], v[62:65], v[190:193], v[26:29]
	v_mfma_f32_16x16x32_bf16 v[14:17], v[54:57], v[198:201], v[14:17]
	v_mfma_f32_16x16x32_bf16 v[10:13], v[62:65], v[198:201], v[10:13]
	s_setprio 0
	s_setprio 1
	v_mfma_f32_16x16x32_bf16 v[34:37], v[170:173], v[66:69], v[34:37]
	v_mfma_f32_16x16x32_bf16 v[90:93], v[174:177], v[70:73], v[34:37]
	v_mfma_f32_16x16x32_bf16 v[34:37], v[178:181], v[66:69], v[38:41]
	v_mfma_f32_16x16x32_bf16 v[86:89], v[182:185], v[70:73], v[34:37]
	v_mfma_f32_16x16x32_bf16 v[34:37], v[170:173], v[82:85], v[42:45]
	v_mfma_f32_16x16x32_bf16 v[70:73], v[174:177], v[94:97], v[34:37]
	v_mfma_f32_16x16x32_bf16 v[34:37], v[178:181], v[82:85], v[46:49]
	v_mfma_f32_16x16x32_bf16 v[22:25], v[170:173], v[186:189], v[22:25]
	v_mfma_f32_16x16x32_bf16 v[18:21], v[178:181], v[186:189], v[18:21]
	v_mfma_f32_16x16x32_bf16 v[6:9], v[170:173], v[194:197], v[6:9]
	v_mfma_f32_16x16x32_bf16 v[2:5], v[178:181], v[194:197], v[2:5]
	v_mfma_f32_16x16x32_bf16 v[66:69], v[182:185], v[94:97], v[34:37]
	v_mfma_f32_16x16x32_bf16 v[22:25], v[174:177], v[190:193], v[22:25]
	v_mfma_f32_16x16x32_bf16 v[18:21], v[182:185], v[190:193], v[18:21]
	v_mfma_f32_16x16x32_bf16 v[6:9], v[174:177], v[198:201], v[6:9]
	v_mfma_f32_16x16x32_bf16 v[2:5], v[182:185], v[198:201], v[2:5]
	s_barrier
	s_setprio 0
	s_add_i32 s65, s65, 2
	s_add_u32 s29, s29, 0x100
	s_addc_u32 s33, s33, 0
	s_add_u32 s36, s36, 0x100
	s_addc_u32 s37, s37, 0
	s_cmp_gt_u32 s65, 29
	s_cbranch_scc0 .LBB0_2620
	s_and_b64 vcc, exec, s[22:23]
	s_cbranch_vccz .LBB0_2623
	s_barrier

; #define GAS __attribute__((address_space(1)))
; #define PG8_STAGE(bufoff, gbase, voff) do { _Pragma("unroll") for (int _i = 0; _i < 2; ++_i) \
;         __builtin_amdgcn_global_load_lds((const GAS unsigned*)((const GAS char*)(gbase) + (voff)[_i]), (LAS unsigned*)(lds + (bufoff) + ldsw + _i * 8192), 16, 0, 0); } while (0)
; #define PG8_LDA(dst, b, h) do { _Pragma("unroll") for (int m = 0; m < 4; ++m) _Pragma("unroll") for (int k = 0; k < 2; ++k) dst[m][k] = *(const LAS bf16x8*)(lds + PG8_SA(b, h) + aoff + m * 2048 + k * 1024); } while (0)
; #define PG8_LDB(dst, b, h) do { _Pragma("unroll") for (int n = 0; n < 2; ++n) _Pragma("unroll") for (int k = 0; k < 2; ++k) dst[n][k] = *(const LAS bf16x8*)(lds + PG8_SB(b, h) + boff + n * 2048 + k * 1024); } while (0)
; #define PG8_MMA(ai, bj, At, Bt) do { __builtin_amdgcn_s_setprio(1); _Pragma("unroll") for (int m = 0; m < 4; ++m) _Pragma("unroll") for (int n = 0; n < 2; ++n) _Pragma("unroll") for (int k = 0; k < 2; ++k) \
;         acc[ai][bj][m][n] = __builtin_amdgcn_mfma_f32_16x16x32_bf16(Bt[n][k], At[m][k], acc[ai][bj][m][n], 0, 0, 0); __builtin_amdgcn_s_setprio(0); } while (0)
; #define PG8_WAIT_V(n) asm volatile("s_waitcnt vmcnt(" #n ")" ::: "memory")
; #define PG8_WAIT_L(n) asm volatile("s_waitcnt lgkmcnt(" #n ")" ::: "memory")
; #define PG8_BAR __builtin_amdgcn_s_barrier()
; #define PG8_SCHED __builtin_amdgcn_sched_barrier(0)
; template <class Epi, class Sched, bool ALIGN_EPI>
; __device__ __forceinline__ void gemm_phase(LAS unsigned char* lds, const Gemm g, const Sched& S, const Epi& E, int wave_id) {
;     ...
;             const bool last = (t == nt - 2);
;             const GAS char* a1 = cA + (size_t)(t + 1) * kstep;
;             const GAS char* a2 = last ? nA : cA + (size_t)(t + 2) * kstep; const GAS char* b2 = last ? nB : cB + (size_t)(t + 2) * kstep;
;             const GAS char* a3 = a2 + kstep; const GAS char* b3 = b2 + kstep;
;             PG8_LDB(B0, 0, 0); PG8_LDB(B1, 0, 1); PG8_SCHED; PG8_LDA(At, 0, 0); PG8_STAGE(PG8_SA(1, 1), a1 + hsA, voffA);
;             PG8_WAIT_V(8); PG8_WAIT_L(0); PG8_BAR; PG8_MMA(0, 0, At, B0); PG8_MMA(0, 1, At, B1); PG8_BAR; PG8_SCHED;
;             PG8_LDA(At, 0, 1); PG8_STAGE(PG8_SB(0, 0), b2, voffB); PG8_STAGE(PG8_SB(0, 1), b2 + hsB, voffB); PG8_STAGE(PG8_SA(0, 0), a2, voffA);
.LBB0_2874:
	s_add_u32 s28, s2, 0xfff80080
	s_addc_u32 s29, s3, -1
	s_cmp_eq_u32 s67, 28
	s_cselect_b32 s31, s23, s29
	s_cselect_b32 s30, s22, s28
	s_cselect_b32 s29, s21, s66
	s_cselect_b32 s28, s27, s33
	v_lshl_add_u64 v[208:209], s[2:3], 0, v[232:233]
	s_add_i32 m0, s40, 0xc400
	s_nop 0
	global_load_lds_dwordx4 v[208:209], off
	v_lshl_add_u64 v[208:209], s[2:3], 0, v[230:231]
	s_add_i32 m0, s40, 0xe400
	s_nop 0
	global_load_lds_dwordx4 v[208:209], off
	v_add_u32_e32 v82, 0x10400, v240
	ds_read_b128 v[18:21], v82
	ds_read_b128 v[88:91], v82 offset:1024
	ds_read_b128 v[108:111], v82 offset:2048
	ds_read_b128 v[112:115], v82 offset:3072
	v_add_u32_e32 v82, 0x14400, v240
	ds_read_b128 v[116:119], v82
	ds_read_b128 v[120:123], v82 offset:1024
	ds_read_b128 v[128:131], v82 offset:2048
	ds_read_b128 v[132:135], v82 offset:3072
	ds_read_b128 v[136:139], v239 offset:1024
	ds_read_b128 v[140:143], v239 offset:2048
	ds_read_b128 v[144:147], v239 offset:3072
	ds_read_b128 v[164:167], v239 offset:4096
	ds_read_b128 v[180:183], v239 offset:5120
	ds_read_b128 v[184:187], v239 offset:6144
	ds_read_b128 v[188:191], v239 offset:7168
	ds_read_b128 v[192:195], v239 offset:8192
	s_waitcnt vmcnt(8)
	s_waitcnt lgkmcnt(0)
	s_setprio 1
	s_barrier
	v_mfma_f32_16x16x32_bf16 v[176:179], v[18:21], v[136:139], v[176:179]
	v_mfma_f32_16x16x32_bf16 v[30:33], v[108:111], v[136:139], v[30:33]
	v_mfma_f32_16x16x32_bf16 v[172:175], v[18:21], v[144:147], v[172:175]
	v_mfma_f32_16x16x32_bf16 v[50:53], v[108:111], v[144:147], v[50:53]
	v_mfma_f32_16x16x32_bf16 v[156:159], v[18:21], v[180:183], v[156:159]
	v_mfma_f32_16x16x32_bf16 v[78:81], v[108:111], v[180:183], v[78:81]
	v_mfma_f32_16x16x32_bf16 v[124:127], v[18:21], v[188:191], v[124:127]
	v_mfma_f32_16x16x32_bf16 v[104:107], v[108:111], v[188:191], v[104:107]
	v_mfma_f32_16x16x32_bf16 v[176:179], v[88:91], v[140:143], v[176:179]
	v_mfma_f32_16x16x32_bf16 v[30:33], v[112:115], v[140:143], v[30:33]
	v_mfma_f32_16x16x32_bf16 v[172:175], v[88:91], v[164:167], v[172:175]
	v_mfma_f32_16x16x32_bf16 v[50:53], v[112:115], v[164:167], v[50:53]
	v_mfma_f32_16x16x32_bf16 v[156:159], v[88:91], v[184:187], v[156:159]
	v_mfma_f32_16x16x32_bf16 v[78:81], v[112:115], v[184:187], v[78:81]
	v_mfma_f32_16x16x32_bf16 v[124:127], v[88:91], v[192:195], v[124:127]
	v_mfma_f32_16x16x32_bf16 v[104:107], v[112:115], v[192:195], v[104:107]
	s_setprio 0
	s_setprio 1
	v_mfma_f32_16x16x32_bf16 v[160:163], v[116:119], v[136:139], v[160:163]
	v_mfma_f32_16x16x32_bf16 v[62:65], v[128:131], v[136:139], v[62:65]
	v_mfma_f32_16x16x32_bf16 v[92:95], v[128:131], v[144:147], v[92:95]
	v_mfma_f32_16x16x32_bf16 v[100:103], v[116:119], v[188:191], v[100:103]
	v_mfma_f32_16x16x32_bf16 v[96:99], v[128:131], v[188:191], v[96:99]
	v_mfma_f32_16x16x32_bf16 v[160:163], v[120:123], v[140:143], v[160:163]
	v_mfma_f32_16x16x32_bf16 v[62:65], v[132:135], v[140:143], v[62:65]
	v_mfma_f32_16x16x32_bf16 v[136:139], v[116:119], v[144:147], v[168:171]
	v_mfma_f32_16x16x32_bf16 v[92:95], v[132:135], v[164:167], v[92:95]
	v_mfma_f32_16x16x32_bf16 v[140:143], v[116:119], v[180:183], v[152:155]
	v_mfma_f32_16x16x32_bf16 v[144:147], v[128:131], v[180:183], v[148:151]
	v_mfma_f32_16x16x32_bf16 v[100:103], v[120:123], v[192:195], v[100:103]
	v_mfma_f32_16x16x32_bf16 v[96:99], v[132:135], v[192:195], v[96:99]
	v_mfma_f32_16x16x32_bf16 v[136:139], v[120:123], v[164:167], v[136:139]
	v_mfma_f32_16x16x32_bf16 v[140:143], v[120:123], v[184:187], v[140:143]
	v_mfma_f32_16x16x32_bf16 v[144:147], v[132:135], v[184:187], v[144:147]
	s_barrier
	s_setprio 0
	s_mov_b32 m0, s41
	v_lshl_add_u64 v[200:201], s[28:29], 0, v[0:1]
	s_add_u32 s68, s28, 0x80000
	global_load_lds_dwordx4 v[200:201], off
	v_lshl_add_u64 v[202:203], s[28:29], 0, v[228:229]
	s_mov_b32 m0, s42
	s_addc_u32 s69, s29, 0
	global_load_lds_dwordx4 v[202:203], off
	v_lshl_add_u64 v[82:83], s[68:69], 0, v[0:1]
	s_mov_b32 m0, s43
	v_lshl_add_u64 v[204:205], s[30:31], 0, v[224:225]
	global_load_lds_dwordx4 v[82:83], off
	v_lshl_add_u64 v[82:83], s[68:69], 0, v[228:229]
	s_mov_b32 m0, s44
	v_lshl_add_u64 v[206:207], s[30:31], 0, v[226:227]
	global_load_lds_dwordx4 v[82:83], off
	s_mov_b32 m0, s45
	s_nop 0
	global_load_lds_dwordx4 v[204:205], off
	s_mov_b32 m0, s46
	s_nop 0
	global_load_lds_dwordx4 v[206:207], off
	ds_read_b128 v[148:151], v239 offset:17408
	ds_read_b128 v[152:155], v239 offset:18432
	ds_read_b128 v[164:167], v239 offset:19456
	ds_read_b128 v[168:171], v239 offset:20480
	ds_read_b128 v[180:183], v239 offset:21504
	ds_read_b128 v[184:187], v239 offset:22528
	ds_read_b128 v[188:191], v239 offset:23552
	ds_read_b128 v[192:195], v239 offset:24576
	s_waitcnt vmcnt(8)
	s_waitcnt lgkmcnt(0)
	s_setprio 1
	s_barrier
; #define PG8_STAGE(bufoff, gbase, voff) do { _Pragma("unroll") for (int _i = 0; _i < 2; ++_i) \
;         __builtin_amdgcn_global_load_lds((const GAS unsigned*)((const GAS char*)(gbase) + (voff)[_i]), (LAS unsigned*)(lds + (bufoff) + ldsw + _i * 8192), 16, 0, 0); } while (0)
; #define PG8_LDA(dst, b, h) do { _Pragma("unroll") for (int m = 0; m < 4; ++m) _Pragma("unroll") for (int k = 0; k < 2; ++k) dst[m][k] = *(const LAS bf16x8*)(lds + PG8_SA(b, h) + aoff + m * 2048 + k * 1024); } while (0)
; #define PG8_LDB(dst, b, h) do { _Pragma("unroll") for (int n = 0; n < 2; ++n) _Pragma("unroll") for (int k = 0; k < 2; ++k) dst[n][k] = *(const LAS bf16x8*)(lds + PG8_SB(b, h) + boff + n * 2048 + k * 1024); } while (0)
; #define PG8_MMA(ai, bj, At, Bt) do { __builtin_amdgcn_s_setprio(1); _Pragma("unroll") for (int m = 0; m < 4; ++m) _Pragma("unroll") for (int n = 0; n < 2; ++n) _Pragma("unroll") for (int k = 0; k < 2; ++k) \
;         acc[ai][bj][m][n] = __builtin_amdgcn_mfma_f32_16x16x32_bf16(Bt[n][k], At[m][k], acc[ai][bj][m][n], 0, 0, 0); __builtin_amdgcn_s_setprio(0); } while (0)
; #define PG8_WAIT_V(n) asm volatile("s_waitcnt vmcnt(" #n ")" ::: "memory")
; #define PG8_WAIT_L(n) asm volatile("s_waitcnt lgkmcnt(" #n ")" ::: "memory")
; #define PG8_BAR __builtin_amdgcn_s_barrier()
; #define PG8_SCHED __builtin_amdgcn_sched_barrier(0)
; template <class Epi, class Sched, bool ALIGN_EPI>
; __device__ __forceinline__ void gemm_phase(LAS unsigned char* lds, const Gemm g, const Sched& S, const Epi& E, int wave_id) {
;     ...
;             PG8_WAIT_V(8); PG8_WAIT_L(0); PG8_BAR; PG8_MMA(1, 0, At, B0); PG8_MMA(1, 1, At, B1); PG8_BAR; PG8_SCHED;
;             PG8_LDB(B0, 1, 0); PG8_LDB(B1, 1, 1); PG8_SCHED; PG8_LDA(At, 1, 0); PG8_STAGE(PG8_SA(0, 1), a2 + hsA, voffA);
;             PG8_WAIT_V(8); PG8_WAIT_L(0); PG8_BAR; PG8_MMA(0, 0, At, B0); PG8_MMA(0, 1, At, B1); PG8_BAR; PG8_SCHED;
	v_mfma_f32_16x16x32_bf16 v[82:85], v[18:21], v[148:151], v[84:87]
	v_mfma_f32_16x16x32_bf16 v[70:73], v[108:111], v[148:151], v[70:73]
	v_mfma_f32_16x16x32_bf16 v[58:61], v[18:21], v[164:167], v[58:61]
	v_mfma_f32_16x16x32_bf16 v[54:57], v[108:111], v[164:167], v[54:57]
	v_mfma_f32_16x16x32_bf16 v[38:41], v[18:21], v[180:183], v[38:41]
	v_mfma_f32_16x16x32_bf16 v[34:37], v[108:111], v[180:183], v[34:37]
	v_mfma_f32_16x16x32_bf16 v[14:17], v[18:21], v[188:191], v[14:17]
	v_mfma_f32_16x16x32_bf16 v[10:13], v[108:111], v[188:191], v[10:13]
	v_mfma_f32_16x16x32_bf16 v[82:85], v[88:91], v[152:155], v[82:85]
	v_mfma_f32_16x16x32_bf16 v[70:73], v[112:115], v[152:155], v[70:73]
	v_mfma_f32_16x16x32_bf16 v[58:61], v[88:91], v[168:171], v[58:61]
	v_mfma_f32_16x16x32_bf16 v[54:57], v[112:115], v[168:171], v[54:57]
	v_mfma_f32_16x16x32_bf16 v[38:41], v[88:91], v[184:187], v[38:41]
	v_mfma_f32_16x16x32_bf16 v[34:37], v[112:115], v[184:187], v[34:37]
	v_mfma_f32_16x16x32_bf16 v[14:17], v[88:91], v[192:195], v[14:17]
	v_mfma_f32_16x16x32_bf16 v[10:13], v[112:115], v[192:195], v[10:13]
	s_setprio 0
	s_setprio 1
	v_mfma_f32_16x16x32_bf16 v[66:69], v[128:131], v[148:151], v[66:69]
	v_mfma_f32_16x16x32_bf16 v[46:49], v[116:119], v[164:167], v[46:49]
	v_mfma_f32_16x16x32_bf16 v[42:45], v[128:131], v[164:167], v[42:45]
	v_mfma_f32_16x16x32_bf16 v[26:29], v[116:119], v[180:183], v[26:29]
	v_mfma_f32_16x16x32_bf16 v[22:25], v[128:131], v[180:183], v[22:25]
	v_mfma_f32_16x16x32_bf16 v[6:9], v[116:119], v[188:191], v[6:9]
	v_mfma_f32_16x16x32_bf16 v[2:5], v[128:131], v[188:191], v[2:5]
	v_mfma_f32_16x16x32_bf16 v[18:21], v[116:119], v[148:151], v[74:77]
	v_mfma_f32_16x16x32_bf16 v[66:69], v[132:135], v[152:155], v[66:69]
	v_mfma_f32_16x16x32_bf16 v[46:49], v[120:123], v[168:171], v[46:49]
	v_mfma_f32_16x16x32_bf16 v[42:45], v[132:135], v[168:171], v[42:45]
	v_mfma_f32_16x16x32_bf16 v[26:29], v[120:123], v[184:187], v[26:29]
	v_mfma_f32_16x16x32_bf16 v[22:25], v[132:135], v[184:187], v[22:25]
	v_mfma_f32_16x16x32_bf16 v[6:9], v[120:123], v[192:195], v[6:9]
	v_mfma_f32_16x16x32_bf16 v[2:5], v[132:135], v[192:195], v[2:5]
	v_mfma_f32_16x16x32_bf16 v[18:21], v[120:123], v[152:155], v[18:21]
	s_barrier
	s_setprio 0
	s_add_u32 s30, s30, 0x80000
	s_addc_u32 s31, s31, 0
	s_mov_b32 m0, s47
	v_lshl_add_u64 v[210:211], s[30:31], 0, v[224:225]
	global_load_lds_dwordx4 v[210:211], off
	v_lshl_add_u64 v[210:211], s[30:31], 0, v[226:227]
	s_mov_b32 m0, s48
	s_nop 0
	global_load_lds_dwordx4 v[210:211], off
	v_add_u32_e32 v86, 0x18400, v240
	ds_read_b128 v[74:77], v86
	ds_read_b128 v[88:91], v86 offset:1024
	ds_read_b128 v[108:111], v86 offset:2048
	ds_read_b128 v[112:115], v86 offset:3072
	v_add_u32_e32 v86, 0x1c400, v240
	ds_read_b128 v[116:119], v86
	ds_read_b128 v[120:123], v86 offset:1024
	ds_read_b128 v[128:131], v86 offset:2048
	ds_read_b128 v[132:135], v86 offset:3072
	ds_read_b128 v[148:151], v239 offset:33792
	ds_read_b128 v[152:155], v239 offset:34816
	ds_read_b128 v[164:167], v239 offset:35840
	ds_read_b128 v[180:183], v239 offset:36864
	ds_read_b128 v[184:187], v239 offset:37888
	ds_read_b128 v[188:191], v239 offset:38912
	ds_read_b128 v[192:195], v239 offset:39936
	ds_read_b128 v[196:199], v239 offset:40960
	s_waitcnt vmcnt(8)
	s_waitcnt lgkmcnt(0)
	s_setprio 1
	s_barrier
	v_mfma_f32_16x16x32_bf16 v[168:171], v[74:77], v[148:151], v[176:179]
	v_mfma_f32_16x16x32_bf16 v[176:179], v[88:91], v[152:155], v[168:171]
	v_mfma_f32_16x16x32_bf16 v[30:33], v[108:111], v[148:151], v[30:33]
	v_mfma_f32_16x16x32_bf16 v[168:171], v[74:77], v[164:167], v[172:175]
	v_mfma_f32_16x16x32_bf16 v[50:53], v[108:111], v[164:167], v[50:53]
	v_mfma_f32_16x16x32_bf16 v[156:159], v[74:77], v[184:187], v[156:159]
	v_mfma_f32_16x16x32_bf16 v[78:81], v[108:111], v[184:187], v[78:81]
	v_mfma_f32_16x16x32_bf16 v[124:127], v[74:77], v[192:195], v[124:127]
	v_mfma_f32_16x16x32_bf16 v[104:107], v[108:111], v[192:195], v[104:107]
	v_mfma_f32_16x16x32_bf16 v[30:33], v[112:115], v[152:155], v[30:33]
	v_mfma_f32_16x16x32_bf16 v[172:175], v[88:91], v[180:183], v[168:171]
	v_mfma_f32_16x16x32_bf16 v[50:53], v[112:115], v[180:183], v[50:53]
	v_mfma_f32_16x16x32_bf16 v[156:159], v[88:91], v[188:191], v[156:159]
	v_mfma_f32_16x16x32_bf16 v[78:81], v[112:115], v[188:191], v[78:81]
	v_mfma_f32_16x16x32_bf16 v[124:127], v[88:91], v[196:199], v[124:127]
	v_mfma_f32_16x16x32_bf16 v[104:107], v[112:115], v[196:199], v[104:107]
	s_setprio 0
	s_setprio 1
	v_mfma_f32_16x16x32_bf16 v[136:139], v[116:119], v[164:167], v[136:139]
	v_mfma_f32_16x16x32_bf16 v[160:163], v[116:119], v[148:151], v[160:163]
	v_mfma_f32_16x16x32_bf16 v[62:65], v[128:131], v[148:151], v[62:65]
	v_mfma_f32_16x16x32_bf16 v[168:171], v[120:123], v[180:183], v[136:139]
	v_mfma_f32_16x16x32_bf16 v[136:139], v[116:119], v[184:187], v[140:143]
	v_mfma_f32_16x16x32_bf16 v[160:163], v[120:123], v[152:155], v[160:163]
	v_mfma_f32_16x16x32_bf16 v[62:65], v[132:135], v[152:155], v[62:65]
	v_mfma_f32_16x16x32_bf16 v[92:95], v[128:131], v[164:167], v[92:95]
	v_mfma_f32_16x16x32_bf16 v[152:155], v[120:123], v[188:191], v[136:139]
	v_mfma_f32_16x16x32_bf16 v[136:139], v[128:131], v[184:187], v[144:147]
	v_mfma_f32_16x16x32_bf16 v[100:103], v[116:119], v[192:195], v[100:103]
	v_mfma_f32_16x16x32_bf16 v[96:99], v[128:131], v[192:195], v[96:99]
	v_mfma_f32_16x16x32_bf16 v[92:95], v[132:135], v[180:183], v[92:95]
	v_mfma_f32_16x16x32_bf16 v[148:151], v[132:135], v[188:191], v[136:139]
	v_mfma_f32_16x16x32_bf16 v[100:103], v[120:123], v[196:199], v[100:103]
	v_mfma_f32_16x16x32_bf16 v[96:99], v[132:135], v[196:199], v[96:99]
	s_barrier
; #define PG8_STAGE(bufoff, gbase, voff) do { _Pragma("unroll") for (int _i = 0; _i < 2; ++_i) \
;         __builtin_amdgcn_global_load_lds((const GAS unsigned*)((const GAS char*)(gbase) + (voff)[_i]), (LAS unsigned*)(lds + (bufoff) + ldsw + _i * 8192), 16, 0, 0); } while (0)
; #define PG8_LDA(dst, b, h) do { _Pragma("unroll") for (int m = 0; m < 4; ++m) _Pragma("unroll") for (int k = 0; k < 2; ++k) dst[m][k] = *(const LAS bf16x8*)(lds + PG8_SA(b, h) + aoff + m * 2048 + k * 1024); } while (0)
; #define PG8_MMA(ai, bj, At, Bt) do { __builtin_amdgcn_s_setprio(1); _Pragma("unroll") for (int m = 0; m < 4; ++m) _Pragma("unroll") for (int n = 0; n < 2; ++n) _Pragma("unroll") for (int k = 0; k < 2; ++k) \
;         acc[ai][bj][m][n] = __builtin_amdgcn_mfma_f32_16x16x32_bf16(Bt[n][k], At[m][k], acc[ai][bj][m][n], 0, 0, 0); __builtin_amdgcn_s_setprio(0); } while (0)
; #define PG8_WAIT_V(n) asm volatile("s_waitcnt vmcnt(" #n ")" ::: "memory")
; #define PG8_WAIT_L(n) asm volatile("s_waitcnt lgkmcnt(" #n ")" ::: "memory")
; #define PG8_BAR __builtin_amdgcn_s_barrier()
; #define PG8_SCHED __builtin_amdgcn_sched_barrier(0)
; template <class Epi, class Sched, bool ALIGN_EPI>
; __device__ __forceinline__ void gemm_phase(LAS unsigned char* lds, const Gemm g, const Sched& S, const Epi& E, int wave_id) {
;     ...
;             PG8_LDA(At, 1, 1); PG8_STAGE(PG8_SB(1, 0), b3, voffB); PG8_STAGE(PG8_SB(1, 1), b3 + hsB, voffB); PG8_STAGE(PG8_SA(1, 0), a3, voffA);
;             PG8_WAIT_V(8); PG8_WAIT_L(0); PG8_BAR; PG8_MMA(1, 0, At, B0); PG8_MMA(1, 1, At, B1); PG8_BAR; PG8_SCHED;
;         }
;         if constexpr (ALIGN_EPI) { if (wr == 0) PG8_BAR; }
	s_setprio 0
	s_mov_b32 m0, s52
	v_lshl_add_u64 v[86:87], v[200:201], 0, s[92:93]
	s_add_u32 s28, s28, 0x80080
	global_load_lds_dwordx4 v[86:87], off
	v_lshl_add_u64 v[86:87], v[202:203], 0, s[92:93]
	s_mov_b32 m0, s53
	s_addc_u32 s29, s29, 0
	global_load_lds_dwordx4 v[86:87], off
	v_lshl_add_u64 v[86:87], s[28:29], 0, v[0:1]
	s_mov_b32 m0, s56
	s_nop 0
	global_load_lds_dwordx4 v[86:87], off
	v_lshl_add_u64 v[86:87], s[28:29], 0, v[228:229]
	s_mov_b32 m0, s57
	s_nop 0
	global_load_lds_dwordx4 v[86:87], off
	v_lshl_add_u64 v[86:87], v[204:205], 0, s[92:93]
	s_mov_b32 m0, s54
	s_nop 0
	global_load_lds_dwordx4 v[86:87], off
	v_lshl_add_u64 v[86:87], v[206:207], 0, s[92:93]
	s_mov_b32 m0, s55
	s_nop 0
	global_load_lds_dwordx4 v[86:87], off
	ds_read_b128 v[136:139], v239 offset:50176
	ds_read_b128 v[140:143], v239 offset:51200
	ds_read_b128 v[144:147], v239 offset:52224
	ds_read_b128 v[164:167], v239 offset:53248
	ds_read_b128 v[180:183], v239 offset:54272
	ds_read_b128 v[184:187], v239 offset:55296
	ds_read_b128 v[188:191], v239 offset:56320
	ds_read_b128 v[192:195], v239 offset:57344
	s_waitcnt vmcnt(8)
	s_waitcnt lgkmcnt(0)
	s_setprio 1
	s_barrier
	v_mfma_f32_16x16x32_bf16 v[82:85], v[74:77], v[136:139], v[82:85]
	v_mfma_f32_16x16x32_bf16 v[70:73], v[108:111], v[136:139], v[70:73]
	v_mfma_f32_16x16x32_bf16 v[58:61], v[74:77], v[144:147], v[58:61]
	v_mfma_f32_16x16x32_bf16 v[54:57], v[108:111], v[144:147], v[54:57]
	v_mfma_f32_16x16x32_bf16 v[38:41], v[74:77], v[180:183], v[38:41]
	v_mfma_f32_16x16x32_bf16 v[34:37], v[108:111], v[180:183], v[34:37]
	v_mfma_f32_16x16x32_bf16 v[14:17], v[74:77], v[188:191], v[14:17]
	v_mfma_f32_16x16x32_bf16 v[10:13], v[108:111], v[188:191], v[10:13]
	v_mfma_f32_16x16x32_bf16 v[84:87], v[88:91], v[140:143], v[82:85]
	v_mfma_f32_16x16x32_bf16 v[70:73], v[112:115], v[140:143], v[70:73]
	v_mfma_f32_16x16x32_bf16 v[58:61], v[88:91], v[164:167], v[58:61]
	v_mfma_f32_16x16x32_bf16 v[54:57], v[112:115], v[164:167], v[54:57]
	v_mfma_f32_16x16x32_bf16 v[38:41], v[88:91], v[184:187], v[38:41]
	v_mfma_f32_16x16x32_bf16 v[34:37], v[112:115], v[184:187], v[34:37]
	v_mfma_f32_16x16x32_bf16 v[14:17], v[88:91], v[192:195], v[14:17]
	v_mfma_f32_16x16x32_bf16 v[10:13], v[112:115], v[192:195], v[10:13]
	s_setprio 0
	s_setprio 1
	v_mfma_f32_16x16x32_bf16 v[18:21], v[116:119], v[136:139], v[18:21]
	v_mfma_f32_16x16x32_bf16 v[74:77], v[120:123], v[140:143], v[18:21]
	v_mfma_f32_16x16x32_bf16 v[18:21], v[128:131], v[136:139], v[66:69]
	v_mfma_f32_16x16x32_bf16 v[66:69], v[132:135], v[140:143], v[18:21]
	v_mfma_f32_16x16x32_bf16 v[18:21], v[116:119], v[144:147], v[46:49]
	v_mfma_f32_16x16x32_bf16 v[46:49], v[120:123], v[164:167], v[18:21]
	v_mfma_f32_16x16x32_bf16 v[18:21], v[128:131], v[144:147], v[42:45]
	v_mfma_f32_16x16x32_bf16 v[42:45], v[132:135], v[164:167], v[18:21]
	v_mfma_f32_16x16x32_bf16 v[18:21], v[116:119], v[180:183], v[26:29]
	v_mfma_f32_16x16x32_bf16 v[26:29], v[120:123], v[184:187], v[18:21]
	v_mfma_f32_16x16x32_bf16 v[18:21], v[128:131], v[180:183], v[22:25]
	v_mfma_f32_16x16x32_bf16 v[6:9], v[116:119], v[188:191], v[6:9]
	v_mfma_f32_16x16x32_bf16 v[2:5], v[128:131], v[188:191], v[2:5]
	v_mfma_f32_16x16x32_bf16 v[22:25], v[132:135], v[184:187], v[18:21]
	v_mfma_f32_16x16x32_bf16 v[6:9], v[120:123], v[192:195], v[6:9]
	v_mfma_f32_16x16x32_bf16 v[2:5], v[132:135], v[192:195], v[2:5]
	s_barrier
	s_setprio 0
	s_add_i32 s67, s67, 2
	s_add_u32 s33, s33, 0x100
	s_addc_u32 s66, s66, 0
	s_add_u32 s2, s2, 0x100
	s_addc_u32 s3, s3, 0
	s_cmp_gt_u32 s67, 29
	s_cbranch_scc0 .LBB0_2874
	s_and_b64 vcc, exec, s[16:17]
	s_cbranch_vccz .LBB0_2877
	s_barrier

; #define GAS __attribute__((address_space(1)))
; #define PG8_STAGE(bufoff, gbase, voff) do { _Pragma("unroll") for (int _i = 0; _i < 2; ++_i) \
;         __builtin_amdgcn_global_load_lds((const GAS unsigned*)((const GAS char*)(gbase) + (voff)[_i]), (LAS unsigned*)(lds + (bufoff) + ldsw + _i * 8192), 16, 0, 0); } while (0)
; #define PG8_LDA(dst, b, h) do { _Pragma("unroll") for (int m = 0; m < 4; ++m) _Pragma("unroll") for (int k = 0; k < 2; ++k) dst[m][k] = *(const LAS bf16x8*)(lds + PG8_SA(b, h) + aoff + m * 2048 + k * 1024); } while (0)
; #define PG8_LDB(dst, b, h) do { _Pragma("unroll") for (int n = 0; n < 2; ++n) _Pragma("unroll") for (int k = 0; k < 2; ++k) dst[n][k] = *(const LAS bf16x8*)(lds + PG8_SB(b, h) + boff + n * 2048 + k * 1024); } while (0)
; #define PG8_MMA(ai, bj, At, Bt) do { __builtin_amdgcn_s_setprio(1); _Pragma("unroll") for (int m = 0; m < 4; ++m) _Pragma("unroll") for (int n = 0; n < 2; ++n) _Pragma("unroll") for (int k = 0; k < 2; ++k) \
;         acc[ai][bj][m][n] = __builtin_amdgcn_mfma_f32_16x16x32_bf16(Bt[n][k], At[m][k], acc[ai][bj][m][n], 0, 0, 0); __builtin_amdgcn_s_setprio(0); } while (0)
; #define PG8_WAIT_V(n) asm volatile("s_waitcnt vmcnt(" #n ")" ::: "memory")
; #define PG8_WAIT_L(n) asm volatile("s_waitcnt lgkmcnt(" #n ")" ::: "memory")
; #define PG8_BAR __builtin_amdgcn_s_barrier()
; #define PG8_SCHED __builtin_amdgcn_sched_barrier(0)
; template <class Epi, class Sched, bool ALIGN_EPI>
; __device__ __forceinline__ void gemm_phase(LAS unsigned char* lds, const Gemm g, const Sched& S, const Epi& E, int wave_id) {
;     ...
;             const bool last = (t == nt - 2);
;             const GAS char* a1 = cA + (size_t)(t + 1) * kstep;
;             const GAS char* a2 = last ? nA : cA + (size_t)(t + 2) * kstep; const GAS char* b2 = last ? nB : cB + (size_t)(t + 2) * kstep;
;             const GAS char* a3 = a2 + kstep; const GAS char* b3 = b2 + kstep;
;             PG8_LDB(B0, 0, 0); PG8_LDB(B1, 0, 1); PG8_SCHED; PG8_LDA(At, 0, 0); PG8_STAGE(PG8_SA(1, 1), a1 + hsA, voffA);
;             PG8_WAIT_V(8); PG8_WAIT_L(0); PG8_BAR; PG8_MMA(0, 0, At, B0); PG8_MMA(0, 1, At, B1); PG8_BAR; PG8_SCHED;
;             PG8_LDA(At, 0, 1); PG8_STAGE(PG8_SB(0, 0), b2, voffB); PG8_STAGE(PG8_SB(0, 1), b2 + hsB, voffB); PG8_STAGE(PG8_SA(0, 0), a2, voffA);
.LBB0_3681:
	s_add_u32 s0, s28, 0x100
	s_addc_u32 s1, s29, 0
	s_cmpk_eq_i32 s63, 0x54
	s_cselect_b32 s35, s25, s1
	s_cselect_b32 s34, s24, s0
	s_cselect_b32 s31, s27, s62
	s_cselect_b32 s30, s26, s61
	v_lshl_add_u64 v[204:205], s[28:29], 0, v[190:191]
	s_add_i32 m0, s41, 0xc400
	s_nop 0
	global_load_lds_dwordx4 v[204:205], off
	v_lshl_add_u64 v[204:205], s[28:29], 0, v[188:189]
	s_add_i32 m0, s41, 0xe400
	s_nop 0
	global_load_lds_dwordx4 v[204:205], off
	v_add_u32_e32 v46, 0x10400, v208
	v_add_u32_e32 v62, 0x14400, v208
	ds_read_b128 v[34:37], v46
	ds_read_b128 v[38:41], v46 offset:1024
	ds_read_b128 v[42:45], v46 offset:2048
	ds_read_b128 v[46:49], v46 offset:3072
	ds_read_b128 v[50:53], v62
	ds_read_b128 v[54:57], v62 offset:1024
	ds_read_b128 v[58:61], v62 offset:2048
	ds_read_b128 v[62:65], v62 offset:3072
	ds_read_b128 v[162:165], v207 offset:1024
	ds_read_b128 v[166:169], v207 offset:2048
	ds_read_b128 v[170:173], v207 offset:3072
	ds_read_b128 v[174:177], v207 offset:4096
	ds_read_b128 v[178:181], v207 offset:5120
	ds_read_b128 v[192:195], v207 offset:6144
	ds_read_b128 v[196:199], v207 offset:7168
	ds_read_b128 v[200:203], v207 offset:8192
	s_waitcnt vmcnt(8)
	s_waitcnt lgkmcnt(0)
	s_setprio 1
	s_barrier
	v_mfma_f32_16x16x32_bf16 v[158:161], v[34:37], v[162:165], v[158:161]
	v_mfma_f32_16x16x32_bf16 v[154:157], v[42:45], v[162:165], v[154:157]
	v_mfma_f32_16x16x32_bf16 v[142:145], v[34:37], v[170:173], v[142:145]
	v_mfma_f32_16x16x32_bf16 v[138:141], v[42:45], v[170:173], v[138:141]
	v_mfma_f32_16x16x32_bf16 v[126:129], v[34:37], v[178:181], v[126:129]
	v_mfma_f32_16x16x32_bf16 v[122:125], v[42:45], v[178:181], v[122:125]
	v_mfma_f32_16x16x32_bf16 v[110:113], v[34:37], v[196:199], v[110:113]
	v_mfma_f32_16x16x32_bf16 v[106:109], v[42:45], v[196:199], v[106:109]
	v_mfma_f32_16x16x32_bf16 v[158:161], v[38:41], v[166:169], v[158:161]
	v_mfma_f32_16x16x32_bf16 v[154:157], v[46:49], v[166:169], v[154:157]
	v_mfma_f32_16x16x32_bf16 v[142:145], v[38:41], v[174:177], v[142:145]
	v_mfma_f32_16x16x32_bf16 v[138:141], v[46:49], v[174:177], v[138:141]
	v_mfma_f32_16x16x32_bf16 v[126:129], v[38:41], v[192:195], v[126:129]
	v_mfma_f32_16x16x32_bf16 v[122:125], v[46:49], v[192:195], v[122:125]
	v_mfma_f32_16x16x32_bf16 v[110:113], v[38:41], v[200:203], v[110:113]
	v_mfma_f32_16x16x32_bf16 v[106:109], v[46:49], v[200:203], v[106:109]
	s_setprio 0
	s_setprio 1
	v_mfma_f32_16x16x32_bf16 v[150:153], v[50:53], v[162:165], v[150:153]
	v_mfma_f32_16x16x32_bf16 v[146:149], v[58:61], v[162:165], v[146:149]
	v_mfma_f32_16x16x32_bf16 v[134:137], v[50:53], v[170:173], v[134:137]
	v_mfma_f32_16x16x32_bf16 v[130:133], v[58:61], v[170:173], v[130:133]
	v_mfma_f32_16x16x32_bf16 v[118:121], v[50:53], v[178:181], v[118:121]
	v_mfma_f32_16x16x32_bf16 v[114:117], v[58:61], v[178:181], v[114:117]
	v_mfma_f32_16x16x32_bf16 v[102:105], v[50:53], v[196:199], v[102:105]
	v_mfma_f32_16x16x32_bf16 v[98:101], v[58:61], v[196:199], v[98:101]
	v_mfma_f32_16x16x32_bf16 v[150:153], v[54:57], v[166:169], v[150:153]
	v_mfma_f32_16x16x32_bf16 v[146:149], v[62:65], v[166:169], v[146:149]
	v_mfma_f32_16x16x32_bf16 v[134:137], v[54:57], v[174:177], v[134:137]
	v_mfma_f32_16x16x32_bf16 v[130:133], v[62:65], v[174:177], v[130:133]
	v_mfma_f32_16x16x32_bf16 v[118:121], v[54:57], v[192:195], v[118:121]
	v_mfma_f32_16x16x32_bf16 v[114:117], v[62:65], v[192:195], v[114:117]
	v_mfma_f32_16x16x32_bf16 v[102:105], v[54:57], v[200:203], v[102:105]
	v_mfma_f32_16x16x32_bf16 v[98:101], v[62:65], v[200:203], v[98:101]
	s_barrier
	s_setprio 0
	s_mov_b32 m0, s42
	v_lshl_add_u64 v[204:205], s[30:31], 0, v[0:1]
	s_add_u32 s28, s30, 0x160000
	global_load_lds_dwordx4 v[204:205], off
	v_lshl_add_u64 v[218:219], s[30:31], 0, v[186:187]
	s_mov_b32 m0, s43
	s_addc_u32 s29, s31, 0
	global_load_lds_dwordx4 v[218:219], off
	v_lshl_add_u64 v[210:211], s[28:29], 0, v[0:1]
	s_mov_b32 m0, s44
	v_lshl_add_u64 v[220:221], s[34:35], 0, v[182:183]
	global_load_lds_dwordx4 v[210:211], off
	v_lshl_add_u64 v[210:211], s[28:29], 0, v[186:187]
	s_mov_b32 m0, s45
	v_lshl_add_u64 v[224:225], s[34:35], 0, v[184:185]
	global_load_lds_dwordx4 v[210:211], off
	s_mov_b32 m0, s46
	s_nop 0
	global_load_lds_dwordx4 v[220:221], off
	s_mov_b32 m0, s47
	s_nop 0
	global_load_lds_dwordx4 v[224:225], off
	ds_read_b128 v[162:165], v207 offset:17408
	ds_read_b128 v[166:169], v207 offset:18432
	ds_read_b128 v[170:173], v207 offset:19456
	ds_read_b128 v[174:177], v207 offset:20480
	ds_read_b128 v[178:181], v207 offset:21504
	ds_read_b128 v[192:195], v207 offset:22528
	ds_read_b128 v[196:199], v207 offset:23552
	ds_read_b128 v[200:203], v207 offset:24576
	s_waitcnt vmcnt(8)
	s_waitcnt lgkmcnt(0)
	s_setprio 1
	s_barrier
; #define PG8_STAGE(bufoff, gbase, voff) do { _Pragma("unroll") for (int _i = 0; _i < 2; ++_i) \
;         __builtin_amdgcn_global_load_lds((const GAS unsigned*)((const GAS char*)(gbase) + (voff)[_i]), (LAS unsigned*)(lds + (bufoff) + ldsw + _i * 8192), 16, 0, 0); } while (0)
; #define PG8_LDA(dst, b, h) do { _Pragma("unroll") for (int m = 0; m < 4; ++m) _Pragma("unroll") for (int k = 0; k < 2; ++k) dst[m][k] = *(const LAS bf16x8*)(lds + PG8_SA(b, h) + aoff + m * 2048 + k * 1024); } while (0)
; #define PG8_LDB(dst, b, h) do { _Pragma("unroll") for (int n = 0; n < 2; ++n) _Pragma("unroll") for (int k = 0; k < 2; ++k) dst[n][k] = *(const LAS bf16x8*)(lds + PG8_SB(b, h) + boff + n * 2048 + k * 1024); } while (0)
; #define PG8_MMA(ai, bj, At, Bt) do { __builtin_amdgcn_s_setprio(1); _Pragma("unroll") for (int m = 0; m < 4; ++m) _Pragma("unroll") for (int n = 0; n < 2; ++n) _Pragma("unroll") for (int k = 0; k < 2; ++k) \
;         acc[ai][bj][m][n] = __builtin_amdgcn_mfma_f32_16x16x32_bf16(Bt[n][k], At[m][k], acc[ai][bj][m][n], 0, 0, 0); __builtin_amdgcn_s_setprio(0); } while (0)
; #define PG8_WAIT_V(n) asm volatile("s_waitcnt vmcnt(" #n ")" ::: "memory")
; #define PG8_WAIT_L(n) asm volatile("s_waitcnt lgkmcnt(" #n ")" ::: "memory")
; #define PG8_BAR __builtin_amdgcn_s_barrier()
; #define PG8_SCHED __builtin_amdgcn_sched_barrier(0)
; template <class Epi, class Sched, bool ALIGN_EPI>
; __device__ __forceinline__ void gemm_phase(LAS unsigned char* lds, const Gemm g, const Sched& S, const Epi& E, int wave_id) {
;     ...
;             PG8_WAIT_V(8); PG8_WAIT_L(0); PG8_BAR; PG8_MMA(1, 0, At, B0); PG8_MMA(1, 1, At, B1); PG8_BAR; PG8_SCHED;
;             PG8_LDB(B0, 1, 0); PG8_LDB(B1, 1, 1); PG8_SCHED; PG8_LDA(At, 1, 0); PG8_STAGE(PG8_SA(0, 1), a2 + hsA, voffA);
;             PG8_WAIT_V(8); PG8_WAIT_L(0); PG8_BAR; PG8_MMA(0, 0, At, B0); PG8_MMA(0, 1, At, B1); PG8_BAR; PG8_SCHED;
	v_mfma_f32_16x16x32_bf16 v[94:97], v[34:37], v[162:165], v[94:97]
	v_mfma_f32_16x16x32_bf16 v[90:93], v[42:45], v[162:165], v[90:93]
	v_mfma_f32_16x16x32_bf16 v[78:81], v[34:37], v[170:173], v[78:81]
	v_mfma_f32_16x16x32_bf16 v[74:77], v[42:45], v[170:173], v[74:77]
	v_mfma_f32_16x16x32_bf16 v[30:33], v[34:37], v[178:181], v[30:33]
	v_mfma_f32_16x16x32_bf16 v[26:29], v[42:45], v[178:181], v[26:29]
	v_mfma_f32_16x16x32_bf16 v[14:17], v[34:37], v[196:199], v[14:17]
	v_mfma_f32_16x16x32_bf16 v[10:13], v[42:45], v[196:199], v[10:13]
	v_mfma_f32_16x16x32_bf16 v[94:97], v[38:41], v[166:169], v[94:97]
	v_mfma_f32_16x16x32_bf16 v[90:93], v[46:49], v[166:169], v[90:93]
	v_mfma_f32_16x16x32_bf16 v[78:81], v[38:41], v[174:177], v[78:81]
	v_mfma_f32_16x16x32_bf16 v[74:77], v[46:49], v[174:177], v[74:77]
	v_mfma_f32_16x16x32_bf16 v[30:33], v[38:41], v[192:195], v[30:33]
	v_mfma_f32_16x16x32_bf16 v[26:29], v[46:49], v[192:195], v[26:29]
	v_mfma_f32_16x16x32_bf16 v[14:17], v[38:41], v[200:203], v[14:17]
	v_mfma_f32_16x16x32_bf16 v[10:13], v[46:49], v[200:203], v[10:13]
	s_setprio 0
	s_setprio 1
	v_mfma_f32_16x16x32_bf16 v[22:25], v[50:53], v[178:181], v[22:25]
	v_mfma_f32_16x16x32_bf16 v[18:21], v[58:61], v[178:181], v[18:21]
	v_mfma_f32_16x16x32_bf16 v[6:9], v[50:53], v[196:199], v[6:9]
	v_mfma_f32_16x16x32_bf16 v[2:5], v[58:61], v[196:199], v[2:5]
	v_mfma_f32_16x16x32_bf16 v[34:37], v[50:53], v[162:165], v[86:89]
	v_mfma_f32_16x16x32_bf16 v[38:41], v[58:61], v[162:165], v[82:85]
	v_mfma_f32_16x16x32_bf16 v[42:45], v[50:53], v[170:173], v[70:73]
	v_mfma_f32_16x16x32_bf16 v[46:49], v[58:61], v[170:173], v[66:69]
	v_mfma_f32_16x16x32_bf16 v[22:25], v[54:57], v[192:195], v[22:25]
	v_mfma_f32_16x16x32_bf16 v[18:21], v[62:65], v[192:195], v[18:21]
	v_mfma_f32_16x16x32_bf16 v[6:9], v[54:57], v[200:203], v[6:9]
	v_mfma_f32_16x16x32_bf16 v[2:5], v[62:65], v[200:203], v[2:5]
	v_mfma_f32_16x16x32_bf16 v[34:37], v[54:57], v[166:169], v[34:37]
	v_mfma_f32_16x16x32_bf16 v[38:41], v[62:65], v[166:169], v[38:41]
	v_mfma_f32_16x16x32_bf16 v[42:45], v[54:57], v[174:177], v[42:45]
	v_mfma_f32_16x16x32_bf16 v[46:49], v[62:65], v[174:177], v[46:49]
	s_barrier
	s_setprio 0
	s_add_u32 s28, s34, 0x160000
	s_addc_u32 s29, s35, 0
	s_mov_b32 m0, s48
	v_lshl_add_u64 v[210:211], s[28:29], 0, v[182:183]
	global_load_lds_dwordx4 v[210:211], off
	v_lshl_add_u64 v[210:211], s[28:29], 0, v[184:185]
	s_mov_b32 m0, s49
	s_nop 0
	global_load_lds_dwordx4 v[210:211], off
	v_add_u32_e32 v62, 0x18400, v208
	v_add_u32_e32 v66, 0x1c400, v208
	ds_read_b128 v[50:53], v62
	ds_read_b128 v[54:57], v62 offset:1024
	ds_read_b128 v[58:61], v62 offset:2048
	ds_read_b128 v[62:65], v62 offset:3072
	ds_read_b128 v[162:165], v66
	ds_read_b128 v[166:169], v66 offset:1024
	ds_read_b128 v[170:173], v66 offset:2048
	ds_read_b128 v[174:177], v66 offset:3072
	ds_read_b128 v[66:69], v207 offset:33792
	ds_read_b128 v[70:73], v207 offset:34816
	ds_read_b128 v[82:85], v207 offset:35840
	ds_read_b128 v[86:89], v207 offset:36864
	ds_read_b128 v[178:181], v207 offset:37888
	ds_read_b128 v[192:195], v207 offset:38912
	ds_read_b128 v[196:199], v207 offset:39936
	ds_read_b128 v[200:203], v207 offset:40960
	s_waitcnt vmcnt(8)
	s_waitcnt lgkmcnt(0)
	s_setprio 1
	s_barrier
	v_mfma_f32_16x16x32_bf16 v[158:161], v[50:53], v[66:69], v[158:161]
	v_mfma_f32_16x16x32_bf16 v[154:157], v[58:61], v[66:69], v[154:157]
	v_mfma_f32_16x16x32_bf16 v[142:145], v[50:53], v[82:85], v[142:145]
	v_mfma_f32_16x16x32_bf16 v[138:141], v[58:61], v[82:85], v[138:141]
	v_mfma_f32_16x16x32_bf16 v[126:129], v[50:53], v[178:181], v[126:129]
	v_mfma_f32_16x16x32_bf16 v[122:125], v[58:61], v[178:181], v[122:125]
	v_mfma_f32_16x16x32_bf16 v[110:113], v[50:53], v[196:199], v[110:113]
	v_mfma_f32_16x16x32_bf16 v[106:109], v[58:61], v[196:199], v[106:109]
	v_mfma_f32_16x16x32_bf16 v[158:161], v[54:57], v[70:73], v[158:161]
	v_mfma_f32_16x16x32_bf16 v[154:157], v[62:65], v[70:73], v[154:157]
	v_mfma_f32_16x16x32_bf16 v[142:145], v[54:57], v[86:89], v[142:145]
	v_mfma_f32_16x16x32_bf16 v[138:141], v[62:65], v[86:89], v[138:141]
	v_mfma_f32_16x16x32_bf16 v[126:129], v[54:57], v[192:195], v[126:129]
	v_mfma_f32_16x16x32_bf16 v[122:125], v[62:65], v[192:195], v[122:125]
	v_mfma_f32_16x16x32_bf16 v[110:113], v[54:57], v[200:203], v[110:113]
	v_mfma_f32_16x16x32_bf16 v[106:109], v[62:65], v[200:203], v[106:109]
	s_setprio 0
	s_setprio 1
	v_mfma_f32_16x16x32_bf16 v[150:153], v[162:165], v[66:69], v[150:153]
	v_mfma_f32_16x16x32_bf16 v[66:69], v[170:173], v[66:69], v[146:149]
	v_mfma_f32_16x16x32_bf16 v[146:149], v[174:177], v[70:73], v[66:69]
	v_mfma_f32_16x16x32_bf16 v[66:69], v[162:165], v[82:85], v[134:137]
	v_mfma_f32_16x16x32_bf16 v[134:137], v[166:169], v[86:89], v[66:69]
	v_mfma_f32_16x16x32_bf16 v[66:69], v[170:173], v[82:85], v[130:133]
	v_mfma_f32_16x16x32_bf16 v[130:133], v[174:177], v[86:89], v[66:69]
	v_mfma_f32_16x16x32_bf16 v[66:69], v[162:165], v[178:181], v[118:121]
	v_mfma_f32_16x16x32_bf16 v[118:121], v[166:169], v[192:195], v[66:69]
	v_mfma_f32_16x16x32_bf16 v[66:69], v[170:173], v[178:181], v[114:117]
	v_mfma_f32_16x16x32_bf16 v[114:117], v[174:177], v[192:195], v[66:69]
	v_mfma_f32_16x16x32_bf16 v[66:69], v[162:165], v[196:199], v[102:105]
	v_mfma_f32_16x16x32_bf16 v[102:105], v[166:169], v[200:203], v[66:69]
	v_mfma_f32_16x16x32_bf16 v[66:69], v[170:173], v[196:199], v[98:101]
	v_mfma_f32_16x16x32_bf16 v[150:153], v[166:169], v[70:73], v[150:153]
	v_mfma_f32_16x16x32_bf16 v[98:101], v[174:177], v[200:203], v[66:69]
	s_barrier
; #define PG8_STAGE(bufoff, gbase, voff) do { _Pragma("unroll") for (int _i = 0; _i < 2; ++_i) \
;         __builtin_amdgcn_global_load_lds((const GAS unsigned*)((const GAS char*)(gbase) + (voff)[_i]), (LAS unsigned*)(lds + (bufoff) + ldsw + _i * 8192), 16, 0, 0); } while (0)
; #define PG8_LDA(dst, b, h) do { _Pragma("unroll") for (int m = 0; m < 4; ++m) _Pragma("unroll") for (int k = 0; k < 2; ++k) dst[m][k] = *(const LAS bf16x8*)(lds + PG8_SA(b, h) + aoff + m * 2048 + k * 1024); } while (0)
; #define PG8_MMA(ai, bj, At, Bt) do { __builtin_amdgcn_s_setprio(1); _Pragma("unroll") for (int m = 0; m < 4; ++m) _Pragma("unroll") for (int n = 0; n < 2; ++n) _Pragma("unroll") for (int k = 0; k < 2; ++k) \
;         acc[ai][bj][m][n] = __builtin_amdgcn_mfma_f32_16x16x32_bf16(Bt[n][k], At[m][k], acc[ai][bj][m][n], 0, 0, 0); __builtin_amdgcn_s_setprio(0); } while (0)
; #define PG8_WAIT_V(n) asm volatile("s_waitcnt vmcnt(" #n ")" ::: "memory")
; #define PG8_WAIT_L(n) asm volatile("s_waitcnt lgkmcnt(" #n ")" ::: "memory")
; #define PG8_BAR __builtin_amdgcn_s_barrier()
; #define PG8_SCHED __builtin_amdgcn_sched_barrier(0)
; template <class Epi, class Sched, bool ALIGN_EPI>
; __device__ __forceinline__ void gemm_phase(LAS unsigned char* lds, const Gemm g, const Sched& S, const Epi& E, int wave_id) {
;     ...
;             PG8_LDA(At, 1, 1); PG8_STAGE(PG8_SB(1, 0), b3, voffB); PG8_STAGE(PG8_SB(1, 1), b3 + hsB, voffB); PG8_STAGE(PG8_SA(1, 0), a3, voffA);
;             PG8_WAIT_V(8); PG8_WAIT_L(0); PG8_BAR; PG8_MMA(1, 0, At, B0); PG8_MMA(1, 1, At, B1); PG8_BAR; PG8_SCHED;
;         }
;         if constexpr (ALIGN_EPI) { if (wr == 0) PG8_BAR; }
	s_setprio 0
	s_mov_b32 m0, s52
	v_lshl_add_u64 v[82:83], v[204:205], 0, s[92:93]
	s_add_u32 s28, s30, 0x160080
	s_nop 0
	global_load_lds_dwordx4 v[82:83], off
	v_lshl_add_u64 v[82:83], v[218:219], 0, s[92:93]
	s_mov_b32 m0, s53
	s_addc_u32 s29, s31, 0
	global_load_lds_dwordx4 v[82:83], off
	v_lshl_add_u64 v[82:83], s[28:29], 0, v[0:1]
	s_mov_b32 m0, s56
	s_nop 0
	global_load_lds_dwordx4 v[82:83], off
	v_lshl_add_u64 v[82:83], s[28:29], 0, v[186:187]
	s_mov_b32 m0, s57
	s_nop 0
	global_load_lds_dwordx4 v[82:83], off
	v_lshl_add_u64 v[82:83], v[220:221], 0, s[92:93]
	s_mov_b32 m0, s54
	s_nop 0
	global_load_lds_dwordx4 v[82:83], off
	v_lshl_add_u64 v[82:83], v[224:225], 0, s[92:93]
	s_mov_b32 m0, s55
	s_nop 0
	global_load_lds_dwordx4 v[82:83], off
	ds_read_b128 v[66:69], v207 offset:50176
	ds_read_b128 v[70:73], v207 offset:51200
	ds_read_b128 v[178:181], v207 offset:52224
	ds_read_b128 v[192:195], v207 offset:53248
	ds_read_b128 v[196:199], v207 offset:54272
	ds_read_b128 v[200:203], v207 offset:55296
	ds_read_b128 v[210:213], v207 offset:56320
	ds_read_b128 v[214:217], v207 offset:57344
	s_waitcnt vmcnt(8)
	s_waitcnt lgkmcnt(0)
	s_setprio 1
	s_barrier
	v_mfma_f32_16x16x32_bf16 v[82:85], v[50:53], v[66:69], v[94:97]
	v_mfma_f32_16x16x32_bf16 v[94:97], v[54:57], v[70:73], v[82:85]
	v_mfma_f32_16x16x32_bf16 v[82:85], v[58:61], v[66:69], v[90:93]
	v_mfma_f32_16x16x32_bf16 v[78:81], v[50:53], v[178:181], v[78:81]
	v_mfma_f32_16x16x32_bf16 v[74:77], v[58:61], v[178:181], v[74:77]
	v_mfma_f32_16x16x32_bf16 v[30:33], v[50:53], v[196:199], v[30:33]
	v_mfma_f32_16x16x32_bf16 v[26:29], v[58:61], v[196:199], v[26:29]
	v_mfma_f32_16x16x32_bf16 v[14:17], v[50:53], v[210:213], v[14:17]
	v_mfma_f32_16x16x32_bf16 v[10:13], v[58:61], v[210:213], v[10:13]
	v_mfma_f32_16x16x32_bf16 v[90:93], v[62:65], v[70:73], v[82:85]
	v_mfma_f32_16x16x32_bf16 v[78:81], v[54:57], v[192:195], v[78:81]
	v_mfma_f32_16x16x32_bf16 v[74:77], v[62:65], v[192:195], v[74:77]
	v_mfma_f32_16x16x32_bf16 v[30:33], v[54:57], v[200:203], v[30:33]
	v_mfma_f32_16x16x32_bf16 v[26:29], v[62:65], v[200:203], v[26:29]
	v_mfma_f32_16x16x32_bf16 v[14:17], v[54:57], v[214:217], v[14:17]
	v_mfma_f32_16x16x32_bf16 v[10:13], v[62:65], v[214:217], v[10:13]
	s_setprio 0
	s_setprio 1
	v_mfma_f32_16x16x32_bf16 v[34:37], v[162:165], v[66:69], v[34:37]
	v_mfma_f32_16x16x32_bf16 v[86:89], v[166:169], v[70:73], v[34:37]
	v_mfma_f32_16x16x32_bf16 v[34:37], v[170:173], v[66:69], v[38:41]
	v_mfma_f32_16x16x32_bf16 v[82:85], v[174:177], v[70:73], v[34:37]
	v_mfma_f32_16x16x32_bf16 v[34:37], v[162:165], v[178:181], v[42:45]
	v_mfma_f32_16x16x32_bf16 v[70:73], v[166:169], v[192:195], v[34:37]
	v_mfma_f32_16x16x32_bf16 v[34:37], v[170:173], v[178:181], v[46:49]
	v_mfma_f32_16x16x32_bf16 v[22:25], v[162:165], v[196:199], v[22:25]
	v_mfma_f32_16x16x32_bf16 v[18:21], v[170:173], v[196:199], v[18:21]
	v_mfma_f32_16x16x32_bf16 v[6:9], v[162:165], v[210:213], v[6:9]
	v_mfma_f32_16x16x32_bf16 v[2:5], v[170:173], v[210:213], v[2:5]
	v_mfma_f32_16x16x32_bf16 v[66:69], v[174:177], v[192:195], v[34:37]
	v_mfma_f32_16x16x32_bf16 v[22:25], v[166:169], v[200:203], v[22:25]
	v_mfma_f32_16x16x32_bf16 v[18:21], v[174:177], v[200:203], v[18:21]
	v_mfma_f32_16x16x32_bf16 v[6:9], v[166:169], v[214:217], v[6:9]
	v_mfma_f32_16x16x32_bf16 v[2:5], v[174:177], v[214:217], v[2:5]
	s_barrier
	s_setprio 0
	s_add_i32 s63, s63, 2
	s_add_u32 s61, s61, 0x100
	s_addc_u32 s62, s62, 0
	s_cmpk_gt_u32 s63, 0x55
	s_mov_b64 s[28:29], s[0:1]
	s_cbranch_scc0 .LBB0_3681
	s_and_b64 vcc, exec, s[22:23]
	s_cbranch_vccz .LBB0_3684
	s_barrier
